# v34 + GEMM K loops: s_setprio 1 issued before the hand-over barrier and held through both MFMA groups (mid-section 0/1 flip removed)
# speedup vs baseline: 1.0009x; 1.0009x over previous
; #define PG8_STAGE(bufoff, gbase, voff) do { _Pragma("unroll") for (int _i = 0; _i < 2; ++_i) \
;         __builtin_amdgcn_global_load_lds((const unsigned*)((const char*)(gbase) + (voff)[_i]), (LAS unsigned*)(lds + (bufoff) + ldsw + _i * 8192), 16, 0, 0); } while (0)
; #define PG8_LDA(dst, b, h) do { _Pragma("unroll") for (int m = 0; m < 4; ++m) _Pragma("unroll") for (int k = 0; k < 2; ++k) dst[m][k] = *(const LAS bf16x8*)(lds + PG8_SA(b, h) + aoff + m * 2048 + k * 1024); } while (0)
; #define PG8_LDB(dst, b, h) do { _Pragma("unroll") for (int n = 0; n < 2; ++n) _Pragma("unroll") for (int k = 0; k < 2; ++k) dst[n][k] = *(const LAS bf16x8*)(lds + PG8_SB(b, h) + boff + n * 2048 + k * 1024); } while (0)
; #define PG8_MMA(ai, bj, At, Bt) do { __builtin_amdgcn_s_setprio(1); _Pragma("unroll") for (int m = 0; m < 4; ++m) _Pragma("unroll") for (int n = 0; n < 2; ++n) _Pragma("unroll") for (int k = 0; k < 2; ++k) \
;         acc[ai][bj][m][n] = __builtin_amdgcn_mfma_f32_16x16x32_bf16(Bt[n][k], At[m][k], acc[ai][bj][m][n], 0, 0, 0); __builtin_amdgcn_s_setprio(0); } while (0)
; #define PG8_WAIT_V(n) asm volatile("s_waitcnt vmcnt(" #n ")" ::: "memory")
; #define PG8_WAIT_L(n) asm volatile("s_waitcnt lgkmcnt(" #n ")" ::: "memory")
; #define PG8_BAR __builtin_amdgcn_s_barrier()
; #define PG8_SCHED __builtin_amdgcn_sched_barrier(0)
; template <class Epi>
; __device__ __forceinline__ void gemm_phase(LAS unsigned char* lds, const Gemm g, const StaticOrder& S, const Epi& E, int wave_s) {
;     ...
;             PG8_LDB(B0, 0, 0); PG8_LDB(B1, 0, 1); PG8_SCHED; PG8_LDA(At, 0, 0); PG8_STAGE(PG8_SA(1, 1), a1 + hstepA, voffA);
;             PG8_WAIT_V(8); PG8_WAIT_L(0); PG8_BAR; PG8_MMA(0, 0, At, B0); PG8_MMA(0, 1, At, B1); PG8_BAR; PG8_SCHED;
;             PG8_LDA(At, 0, 1); PG8_STAGE(PG8_SB(0, 0), b2, voffB); PG8_STAGE(PG8_SB(0, 1), b2 + hstepB, voffB); PG8_STAGE(PG8_SA(0, 0), a2, voffA);
;             PG8_WAIT_V(8); PG8_WAIT_L(0); PG8_BAR; PG8_MMA(1, 0, At, B0); PG8_MMA(1, 1, At, B1); PG8_BAR; PG8_SCHED;
;             PG8_LDB(B0, 1, 0); PG8_LDB(B1, 1, 1); PG8_SCHED; PG8_LDA(At, 1, 0); PG8_STAGE(PG8_SA(0, 1), a2 + hstepA, voffA);
.Lpp_lead_5:
	s_waitcnt lgkmcnt(4)
	s_setprio 1
	s_barrier
	s_waitcnt lgkmcnt(4)
	v_mfma_f32_16x16x32_bf16 v[126:129], v[150:153], v[190:193], v[126:129]
	v_mfma_f32_16x16x32_bf16 v[122:125], v[158:161], v[190:193], v[122:125]
	v_mfma_f32_16x16x32_bf16 v[118:121], v[150:153], v[198:201], v[118:121]
	v_mfma_f32_16x16x32_bf16 v[114:117], v[158:161], v[198:201], v[114:117]
	v_mfma_f32_16x16x32_bf16 v[110:113], v[150:153], v[206:209], v[110:113]
	v_mfma_f32_16x16x32_bf16 v[106:109], v[158:161], v[206:209], v[106:109]
	v_mfma_f32_16x16x32_bf16 v[102:105], v[150:153], v[214:217], v[102:105]
	v_mfma_f32_16x16x32_bf16 v[98:101], v[158:161], v[214:217], v[98:101]
	v_mfma_f32_16x16x32_bf16 v[126:129], v[154:157], v[194:197], v[126:129]
	v_mfma_f32_16x16x32_bf16 v[122:125], v[162:165], v[194:197], v[122:125]
	v_mfma_f32_16x16x32_bf16 v[118:121], v[154:157], v[202:205], v[118:121]
	v_mfma_f32_16x16x32_bf16 v[114:117], v[162:165], v[202:205], v[114:117]
	v_mfma_f32_16x16x32_bf16 v[110:113], v[154:157], v[210:213], v[110:113]
	v_mfma_f32_16x16x32_bf16 v[106:109], v[162:165], v[210:213], v[106:109]
	v_mfma_f32_16x16x32_bf16 v[102:105], v[154:157], v[218:221], v[102:105]
	v_mfma_f32_16x16x32_bf16 v[98:101], v[162:165], v[218:221], v[98:101]
	s_waitcnt lgkmcnt(0)
	v_mfma_f32_16x16x32_bf16 v[62:65], v[166:169], v[190:193], v[62:65]
	v_mfma_f32_16x16x32_bf16 v[58:61], v[182:185], v[190:193], v[58:61]
	v_mfma_f32_16x16x32_bf16 v[54:57], v[166:169], v[198:201], v[54:57]
	v_mfma_f32_16x16x32_bf16 v[50:53], v[182:185], v[198:201], v[50:53]
	v_mfma_f32_16x16x32_bf16 v[46:49], v[166:169], v[206:209], v[46:49]
	v_mfma_f32_16x16x32_bf16 v[42:45], v[182:185], v[206:209], v[42:45]
	v_mfma_f32_16x16x32_bf16 v[38:41], v[166:169], v[214:217], v[38:41]
	v_mfma_f32_16x16x32_bf16 v[34:37], v[182:185], v[214:217], v[34:37]
	v_mfma_f32_16x16x32_bf16 v[62:65], v[178:181], v[194:197], v[62:65]
	v_mfma_f32_16x16x32_bf16 v[58:61], v[186:189], v[194:197], v[58:61]
	v_mfma_f32_16x16x32_bf16 v[54:57], v[178:181], v[202:205], v[54:57]
	v_mfma_f32_16x16x32_bf16 v[50:53], v[186:189], v[202:205], v[50:53]
	v_mfma_f32_16x16x32_bf16 v[46:49], v[178:181], v[210:213], v[46:49]
	v_mfma_f32_16x16x32_bf16 v[42:45], v[186:189], v[210:213], v[42:45]
	v_mfma_f32_16x16x32_bf16 v[38:41], v[178:181], v[218:221], v[38:41]
	v_mfma_f32_16x16x32_bf16 v[34:37], v[186:189], v[218:221], v[34:37]
	s_setprio 0
	s_barrier
	s_add_i32 s49, s49, s18
	v_lshl_add_u64 v[170:171], s[26:27], 0, v[134:135]
	s_mov_b32 m0, s49
	ds_read_b128 v[190:193], v149 offset:16384
	ds_read_b128 v[194:197], v149 offset:17408
	ds_read_b128 v[198:201], v149 offset:18432
	ds_read_b128 v[202:205], v149 offset:19456
	ds_read_b128 v[206:209], v149 offset:20480
	ds_read_b128 v[210:213], v149 offset:21504
	ds_read_b128 v[214:217], v149 offset:22528
	ds_read_b128 v[218:221], v149 offset:23552
	global_load_lds_dwordx4 v[170:171], off
	s_add_i32 m0, s49, 0x2000
	s_add_u32 s50, s26, 0x40000
	v_lshl_add_u64 v[172:173], s[26:27], 0, v[130:131]
	s_addc_u32 s51, s27, 0
	s_add_i32 s49, s52, s18
	global_load_lds_dwordx4 v[172:173], off
	v_lshl_add_u64 v[174:175], s[50:51], 0, v[134:135]
	s_mov_b32 m0, s49
	v_lshl_add_u64 v[176:177], s[30:31], 0, v[132:133]
	global_load_lds_dwordx4 v[174:175], off
	v_lshl_add_u64 v[174:175], s[50:51], 0, v[130:131]
	s_add_i32 m0, s49, 0x2000
	s_nop 0
	global_load_lds_dwordx4 v[174:175], off
	v_lshl_add_u64 v[174:175], s[30:31], 0, v[136:137]
	s_mov_b32 m0, s20
	s_nop 0
	global_load_lds_dwordx4 v[174:175], off
	s_mov_b32 m0, s25
	s_nop 0
	global_load_lds_dwordx4 v[176:177], off
	s_waitcnt vmcnt(8)
	s_waitcnt lgkmcnt(0)
	s_setprio 1
	s_barrier
	s_waitcnt lgkmcnt(0)
	v_mfma_f32_16x16x32_bf16 v[94:97], v[150:153], v[190:193], v[94:97]
	v_mfma_f32_16x16x32_bf16 v[90:93], v[158:161], v[190:193], v[90:93]
	v_mfma_f32_16x16x32_bf16 v[86:89], v[150:153], v[198:201], v[86:89]
	v_mfma_f32_16x16x32_bf16 v[82:85], v[158:161], v[198:201], v[82:85]
	v_mfma_f32_16x16x32_bf16 v[78:81], v[150:153], v[206:209], v[78:81]
	v_mfma_f32_16x16x32_bf16 v[74:77], v[158:161], v[206:209], v[74:77]
	v_mfma_f32_16x16x32_bf16 v[70:73], v[150:153], v[214:217], v[70:73]
	v_mfma_f32_16x16x32_bf16 v[66:69], v[158:161], v[214:217], v[66:69]
	v_mfma_f32_16x16x32_bf16 v[94:97], v[154:157], v[194:197], v[94:97]
	v_mfma_f32_16x16x32_bf16 v[90:93], v[162:165], v[194:197], v[90:93]
	v_mfma_f32_16x16x32_bf16 v[86:89], v[154:157], v[202:205], v[86:89]
	v_mfma_f32_16x16x32_bf16 v[82:85], v[162:165], v[202:205], v[82:85]
	v_mfma_f32_16x16x32_bf16 v[78:81], v[154:157], v[210:213], v[78:81]
	v_mfma_f32_16x16x32_bf16 v[74:77], v[162:165], v[210:213], v[74:77]
	v_mfma_f32_16x16x32_bf16 v[70:73], v[154:157], v[218:221], v[70:73]
	v_mfma_f32_16x16x32_bf16 v[66:69], v[162:165], v[218:221], v[66:69]
	v_mfma_f32_16x16x32_bf16 v[30:33], v[166:169], v[190:193], v[30:33]
	v_mfma_f32_16x16x32_bf16 v[26:29], v[182:185], v[190:193], v[26:29]
	v_mfma_f32_16x16x32_bf16 v[22:25], v[166:169], v[198:201], v[22:25]
	v_mfma_f32_16x16x32_bf16 v[18:21], v[182:185], v[198:201], v[18:21]
	v_mfma_f32_16x16x32_bf16 v[14:17], v[166:169], v[206:209], v[14:17]
	v_mfma_f32_16x16x32_bf16 v[8:11], v[182:185], v[206:209], v[8:11]
	v_mfma_f32_16x16x32_bf16 v[4:7], v[166:169], v[214:217], v[4:7]
	v_mfma_f32_16x16x32_bf16 v[0:3], v[182:185], v[214:217], v[0:3]
	v_mfma_f32_16x16x32_bf16 v[30:33], v[178:181], v[194:197], v[30:33]
	v_mfma_f32_16x16x32_bf16 v[26:29], v[186:189], v[194:197], v[26:29]
	v_mfma_f32_16x16x32_bf16 v[22:25], v[178:181], v[202:205], v[22:25]
	v_mfma_f32_16x16x32_bf16 v[18:21], v[186:189], v[202:205], v[18:21]
	v_mfma_f32_16x16x32_bf16 v[14:17], v[178:181], v[210:213], v[14:17]
	v_mfma_f32_16x16x32_bf16 v[8:11], v[186:189], v[210:213], v[8:11]
	v_mfma_f32_16x16x32_bf16 v[4:7], v[178:181], v[218:221], v[4:7]
	v_mfma_f32_16x16x32_bf16 v[0:3], v[186:189], v[218:221], v[0:3]
	s_setprio 0
	s_barrier
	s_add_i32 s49, 0, 0x18000
	v_add_u32_e32 v12, s49, v148
	s_add_i32 s50, 0, 0x1c000
	ds_read_b128 v[150:153], v12
	ds_read_b128 v[154:157], v12 offset:1024
	ds_read_b128 v[158:161], v12 offset:2048
	ds_read_b128 v[162:165], v12 offset:3072
	v_add_u32_e32 v12, s50, v148
	ds_read_b128 v[190:193], v149 offset:32768
	ds_read_b128 v[194:197], v149 offset:33792
	ds_read_b128 v[198:201], v149 offset:34816
	ds_read_b128 v[202:205], v149 offset:35840
	ds_read_b128 v[206:209], v149 offset:36864
	ds_read_b128 v[210:213], v149 offset:37888
	ds_read_b128 v[214:217], v149 offset:38912
	ds_read_b128 v[218:221], v149 offset:39936
	ds_read_b128 v[166:169], v12
	ds_read_b128 v[178:181], v12 offset:1024
	ds_read_b128 v[182:185], v12 offset:2048
	ds_read_b128 v[186:189], v12 offset:3072
	s_add_u32 s30, s30, 0x40000
	s_addc_u32 s31, s31, 0
	s_mov_b32 m0, s29
	v_lshl_add_u64 v[222:223], s[30:31], 0, v[136:137]
	global_load_lds_dwordx4 v[222:223], off
	v_lshl_add_u64 v[222:223], s[30:31], 0, v[132:133]
	s_mov_b32 m0, s35
	s_nop 0
	global_load_lds_dwordx4 v[222:223], off
	s_waitcnt vmcnt(8)
	s_cmp_lg_u64 s[8:9], 0
	s_cbranch_scc1 .Lpp_lead_6
	s_waitcnt lgkmcnt(0)
; #define PG8_STAGE(bufoff, gbase, voff) do { _Pragma("unroll") for (int _i = 0; _i < 2; ++_i) \
;         __builtin_amdgcn_global_load_lds((const unsigned*)((const char*)(gbase) + (voff)[_i]), (LAS unsigned*)(lds + (bufoff) + ldsw + _i * 8192), 16, 0, 0); } while (0)
; #define PG8_LDA(dst, b, h) do { _Pragma("unroll") for (int m = 0; m < 4; ++m) _Pragma("unroll") for (int k = 0; k < 2; ++k) dst[m][k] = *(const LAS bf16x8*)(lds + PG8_SA(b, h) + aoff + m * 2048 + k * 1024); } while (0)
; #define PG8_LDB(dst, b, h) do { _Pragma("unroll") for (int n = 0; n < 2; ++n) _Pragma("unroll") for (int k = 0; k < 2; ++k) dst[n][k] = *(const LAS bf16x8*)(lds + PG8_SB(b, h) + boff + n * 2048 + k * 1024); } while (0)
; #define PG8_MMA(ai, bj, At, Bt) do { __builtin_amdgcn_s_setprio(1); _Pragma("unroll") for (int m = 0; m < 4; ++m) _Pragma("unroll") for (int n = 0; n < 2; ++n) _Pragma("unroll") for (int k = 0; k < 2; ++k) \
;         acc[ai][bj][m][n] = __builtin_amdgcn_mfma_f32_16x16x32_bf16(Bt[n][k], At[m][k], acc[ai][bj][m][n], 0, 0, 0); __builtin_amdgcn_s_setprio(0); } while (0)
; #define PG8_WAIT_V(n) asm volatile("s_waitcnt vmcnt(" #n ")" ::: "memory")
; #define PG8_WAIT_L(n) asm volatile("s_waitcnt lgkmcnt(" #n ")" ::: "memory")
; #define PG8_BAR __builtin_amdgcn_s_barrier()
; #define PG8_SCHED __builtin_amdgcn_sched_barrier(0)
; template <class Epi>
; __device__ __forceinline__ void gemm_phase(LAS unsigned char* lds, const Gemm g, const StaticOrder& S, const Epi& E, int wave_s) {
;     ...
;             PG8_LDB(B0, 1, 0); PG8_LDB(B1, 1, 1); PG8_SCHED; PG8_LDA(At, 1, 0); PG8_STAGE(PG8_SA(0, 1), a2 + hstepA, voffA);
;             PG8_WAIT_V(8); PG8_WAIT_L(0); PG8_BAR; PG8_MMA(0, 0, At, B0); PG8_MMA(0, 1, At, B1); PG8_BAR; PG8_SCHED;
;             PG8_LDA(At, 1, 1); PG8_STAGE(PG8_SB(1, 0), b3, voffB); PG8_STAGE(PG8_SB(1, 1), b3 + hstepB, voffB); PG8_STAGE(PG8_SA(1, 0), a3, voffA);
;             PG8_WAIT_V(8); PG8_WAIT_L(0); PG8_BAR; PG8_MMA(1, 0, At, B0); PG8_MMA(1, 1, At, B1); PG8_BAR; PG8_SCHED;
;         }
;         if (wr == 0) PG8_BAR;
.Lpp_lead_6:
	s_waitcnt lgkmcnt(4)
	s_setprio 1
	s_barrier
	s_waitcnt lgkmcnt(4)
	v_mfma_f32_16x16x32_bf16 v[126:129], v[150:153], v[190:193], v[126:129]
	v_mfma_f32_16x16x32_bf16 v[122:125], v[158:161], v[190:193], v[122:125]
	v_mfma_f32_16x16x32_bf16 v[118:121], v[150:153], v[198:201], v[118:121]
	v_mfma_f32_16x16x32_bf16 v[114:117], v[158:161], v[198:201], v[114:117]
	v_mfma_f32_16x16x32_bf16 v[110:113], v[150:153], v[206:209], v[110:113]
	v_mfma_f32_16x16x32_bf16 v[106:109], v[158:161], v[206:209], v[106:109]
	v_mfma_f32_16x16x32_bf16 v[102:105], v[150:153], v[214:217], v[102:105]
	v_mfma_f32_16x16x32_bf16 v[98:101], v[158:161], v[214:217], v[98:101]
	v_mfma_f32_16x16x32_bf16 v[126:129], v[154:157], v[194:197], v[126:129]
	v_mfma_f32_16x16x32_bf16 v[122:125], v[162:165], v[194:197], v[122:125]
	v_mfma_f32_16x16x32_bf16 v[118:121], v[154:157], v[202:205], v[118:121]
	v_mfma_f32_16x16x32_bf16 v[114:117], v[162:165], v[202:205], v[114:117]
	v_mfma_f32_16x16x32_bf16 v[110:113], v[154:157], v[210:213], v[110:113]
	v_mfma_f32_16x16x32_bf16 v[106:109], v[162:165], v[210:213], v[106:109]
	v_mfma_f32_16x16x32_bf16 v[102:105], v[154:157], v[218:221], v[102:105]
	v_mfma_f32_16x16x32_bf16 v[98:101], v[162:165], v[218:221], v[98:101]
	s_waitcnt lgkmcnt(0)
	v_mfma_f32_16x16x32_bf16 v[62:65], v[166:169], v[190:193], v[62:65]
	v_mfma_f32_16x16x32_bf16 v[58:61], v[182:185], v[190:193], v[58:61]
	v_mfma_f32_16x16x32_bf16 v[54:57], v[166:169], v[198:201], v[54:57]
	v_mfma_f32_16x16x32_bf16 v[50:53], v[182:185], v[198:201], v[50:53]
	v_mfma_f32_16x16x32_bf16 v[46:49], v[166:169], v[206:209], v[46:49]
	v_mfma_f32_16x16x32_bf16 v[42:45], v[182:185], v[206:209], v[42:45]
	v_mfma_f32_16x16x32_bf16 v[38:41], v[166:169], v[214:217], v[38:41]
	v_mfma_f32_16x16x32_bf16 v[34:37], v[182:185], v[214:217], v[34:37]
	v_mfma_f32_16x16x32_bf16 v[62:65], v[178:181], v[194:197], v[62:65]
	v_mfma_f32_16x16x32_bf16 v[58:61], v[186:189], v[194:197], v[58:61]
	v_mfma_f32_16x16x32_bf16 v[54:57], v[178:181], v[202:205], v[54:57]
	v_mfma_f32_16x16x32_bf16 v[50:53], v[186:189], v[202:205], v[50:53]
	v_mfma_f32_16x16x32_bf16 v[46:49], v[178:181], v[210:213], v[46:49]
	v_mfma_f32_16x16x32_bf16 v[42:45], v[186:189], v[210:213], v[42:45]
	v_mfma_f32_16x16x32_bf16 v[38:41], v[178:181], v[218:221], v[38:41]
	v_mfma_f32_16x16x32_bf16 v[34:37], v[186:189], v[218:221], v[34:37]
	s_setprio 0
	s_barrier
	s_add_i32 s30, s49, s18
	v_lshl_add_u64 v[170:171], v[170:171], 0, s[84:85]
	s_mov_b32 m0, s30
	ds_read_b128 v[190:193], v149 offset:49152
	ds_read_b128 v[194:197], v149 offset:50176
	ds_read_b128 v[198:201], v149 offset:51200
	ds_read_b128 v[202:205], v149 offset:52224
	ds_read_b128 v[206:209], v149 offset:53248
	ds_read_b128 v[210:213], v149 offset:54272
	ds_read_b128 v[214:217], v149 offset:55296
	ds_read_b128 v[218:221], v149 offset:56320
	global_load_lds_dwordx4 v[170:171], off
	s_add_i32 m0, s30, 0x2000
	s_add_u32 s26, s26, 0x40080
	v_lshl_add_u64 v[170:171], v[172:173], 0, s[84:85]
	s_addc_u32 s27, s27, 0
	s_add_i32 s30, s50, s18
	global_load_lds_dwordx4 v[170:171], off
	v_lshl_add_u64 v[170:171], s[26:27], 0, v[134:135]
	s_mov_b32 m0, s30
	s_nop 0
	global_load_lds_dwordx4 v[170:171], off
	v_lshl_add_u64 v[170:171], s[26:27], 0, v[130:131]
	s_add_i32 m0, s30, 0x2000
	s_nop 0
	global_load_lds_dwordx4 v[170:171], off
	v_lshl_add_u64 v[170:171], v[174:175], 0, s[84:85]
	s_mov_b32 m0, s37
	s_nop 0
	global_load_lds_dwordx4 v[170:171], off
	v_lshl_add_u64 v[170:171], v[176:177], 0, s[84:85]
	s_mov_b32 m0, s40
	s_nop 0
	global_load_lds_dwordx4 v[170:171], off
	s_waitcnt vmcnt(8)
	s_waitcnt lgkmcnt(0)
	s_setprio 1
	s_barrier
	s_waitcnt lgkmcnt(0)
	v_mfma_f32_16x16x32_bf16 v[94:97], v[150:153], v[190:193], v[94:97]
	v_mfma_f32_16x16x32_bf16 v[90:93], v[158:161], v[190:193], v[90:93]
	v_mfma_f32_16x16x32_bf16 v[86:89], v[150:153], v[198:201], v[86:89]
	v_mfma_f32_16x16x32_bf16 v[82:85], v[158:161], v[198:201], v[82:85]
	v_mfma_f32_16x16x32_bf16 v[78:81], v[150:153], v[206:209], v[78:81]
	v_mfma_f32_16x16x32_bf16 v[74:77], v[158:161], v[206:209], v[74:77]
	v_mfma_f32_16x16x32_bf16 v[70:73], v[150:153], v[214:217], v[70:73]
	v_mfma_f32_16x16x32_bf16 v[66:69], v[158:161], v[214:217], v[66:69]
	v_mfma_f32_16x16x32_bf16 v[94:97], v[154:157], v[194:197], v[94:97]
	v_mfma_f32_16x16x32_bf16 v[90:93], v[162:165], v[194:197], v[90:93]
	v_mfma_f32_16x16x32_bf16 v[86:89], v[154:157], v[202:205], v[86:89]
	v_mfma_f32_16x16x32_bf16 v[82:85], v[162:165], v[202:205], v[82:85]
	v_mfma_f32_16x16x32_bf16 v[78:81], v[154:157], v[210:213], v[78:81]
	v_mfma_f32_16x16x32_bf16 v[74:77], v[162:165], v[210:213], v[74:77]
	v_mfma_f32_16x16x32_bf16 v[70:73], v[154:157], v[218:221], v[70:73]
	v_mfma_f32_16x16x32_bf16 v[66:69], v[162:165], v[218:221], v[66:69]
	v_mfma_f32_16x16x32_bf16 v[30:33], v[166:169], v[190:193], v[30:33]
	v_mfma_f32_16x16x32_bf16 v[26:29], v[182:185], v[190:193], v[26:29]
	v_mfma_f32_16x16x32_bf16 v[22:25], v[166:169], v[198:201], v[22:25]
	v_mfma_f32_16x16x32_bf16 v[18:21], v[182:185], v[198:201], v[18:21]
	v_mfma_f32_16x16x32_bf16 v[14:17], v[166:169], v[206:209], v[14:17]
	v_mfma_f32_16x16x32_bf16 v[8:11], v[182:185], v[206:209], v[8:11]
	v_mfma_f32_16x16x32_bf16 v[4:7], v[166:169], v[214:217], v[4:7]
	v_mfma_f32_16x16x32_bf16 v[0:3], v[182:185], v[214:217], v[0:3]
	v_mfma_f32_16x16x32_bf16 v[30:33], v[178:181], v[194:197], v[30:33]
	v_mfma_f32_16x16x32_bf16 v[26:29], v[186:189], v[194:197], v[26:29]
	v_mfma_f32_16x16x32_bf16 v[22:25], v[178:181], v[202:205], v[22:25]
	v_mfma_f32_16x16x32_bf16 v[18:21], v[186:189], v[202:205], v[18:21]
	v_mfma_f32_16x16x32_bf16 v[14:17], v[178:181], v[210:213], v[14:17]
	v_mfma_f32_16x16x32_bf16 v[8:11], v[186:189], v[210:213], v[8:11]
	v_mfma_f32_16x16x32_bf16 v[4:7], v[178:181], v[218:221], v[4:7]
	v_mfma_f32_16x16x32_bf16 v[0:3], v[186:189], v[218:221], v[0:3]
	s_setprio 0
	s_barrier
	s_add_i32 s48, s48, 2
	s_add_u32 s4, s4, 0x100
	s_addc_u32 s5, s5, 0
	s_add_u32 s46, s46, 0x100
	s_addc_u32 s47, s47, 0
	s_cmp_gt_u32 s48, 13
	s_cbranch_scc0 .LBB0_215
	s_and_b64 vcc, exec, s[8:9]
	s_cbranch_vccz .LBB0_218
	s_barrier

; #define PG8_STAGE(bufoff, gbase, voff) do { _Pragma("unroll") for (int _i = 0; _i < 2; ++_i) \
;         __builtin_amdgcn_global_load_lds((const unsigned*)((const char*)(gbase) + (voff)[_i]), (LAS unsigned*)(lds + (bufoff) + ldsw + _i * 8192), 16, 0, 0); } while (0)
; #define PG8_LDA(dst, b, h) do { _Pragma("unroll") for (int m = 0; m < 4; ++m) _Pragma("unroll") for (int k = 0; k < 2; ++k) dst[m][k] = *(const LAS bf16x8*)(lds + PG8_SA(b, h) + aoff + m * 2048 + k * 1024); } while (0)
; #define PG8_LDB(dst, b, h) do { _Pragma("unroll") for (int n = 0; n < 2; ++n) _Pragma("unroll") for (int k = 0; k < 2; ++k) dst[n][k] = *(const LAS bf16x8*)(lds + PG8_SB(b, h) + boff + n * 2048 + k * 1024); } while (0)
; #define PG8_MMA(ai, bj, At, Bt) do { __builtin_amdgcn_s_setprio(1); _Pragma("unroll") for (int m = 0; m < 4; ++m) _Pragma("unroll") for (int n = 0; n < 2; ++n) _Pragma("unroll") for (int k = 0; k < 2; ++k) \
;         acc[ai][bj][m][n] = __builtin_amdgcn_mfma_f32_16x16x32_bf16(Bt[n][k], At[m][k], acc[ai][bj][m][n], 0, 0, 0); __builtin_amdgcn_s_setprio(0); } while (0)
; #define PG8_WAIT_V(n) asm volatile("s_waitcnt vmcnt(" #n ")" ::: "memory")
; #define PG8_WAIT_L(n) asm volatile("s_waitcnt lgkmcnt(" #n ")" ::: "memory")
; #define PG8_BAR __builtin_amdgcn_s_barrier()
; #define PG8_SCHED __builtin_amdgcn_sched_barrier(0)
; template <class Epi>
; __device__ __forceinline__ void gemm_phase(LAS unsigned char* lds, const Gemm g, const StaticOrder& S, const Epi& E, int wave_s) {
;     ...
;             PG8_LDB(B0, 0, 0); PG8_LDB(B1, 0, 1); PG8_SCHED; PG8_LDA(At, 0, 0); PG8_STAGE(PG8_SA(1, 1), a1 + hstepA, voffA);
;             PG8_WAIT_V(8); PG8_WAIT_L(0); PG8_BAR; PG8_MMA(0, 0, At, B0); PG8_MMA(0, 1, At, B1); PG8_BAR; PG8_SCHED;
;             PG8_LDA(At, 0, 1); PG8_STAGE(PG8_SB(0, 0), b2, voffB); PG8_STAGE(PG8_SB(0, 1), b2 + hstepB, voffB); PG8_STAGE(PG8_SA(0, 0), a2, voffA);
;             PG8_WAIT_V(8); PG8_WAIT_L(0); PG8_BAR; PG8_MMA(1, 0, At, B0); PG8_MMA(1, 1, At, B1); PG8_BAR; PG8_SCHED;
;             PG8_LDB(B0, 1, 0); PG8_LDB(B1, 1, 1); PG8_SCHED; PG8_LDA(At, 1, 0); PG8_STAGE(PG8_SA(0, 1), a2 + hstepA, voffA);
.Lpp_lead_7:
	s_waitcnt lgkmcnt(4)
	s_setprio 1
	s_barrier
	s_waitcnt lgkmcnt(4)
	v_mfma_f32_16x16x32_bf16 v[126:129], v[130:133], v[188:191], v[126:129]
	v_mfma_f32_16x16x32_bf16 v[122:125], v[138:141], v[188:191], v[122:125]
	v_mfma_f32_16x16x32_bf16 v[118:121], v[130:133], v[196:199], v[118:121]
	v_mfma_f32_16x16x32_bf16 v[114:117], v[138:141], v[196:199], v[114:117]
	v_mfma_f32_16x16x32_bf16 v[110:113], v[130:133], v[204:207], v[110:113]
	v_mfma_f32_16x16x32_bf16 v[106:109], v[138:141], v[204:207], v[106:109]
	v_mfma_f32_16x16x32_bf16 v[102:105], v[130:133], v[212:215], v[102:105]
	v_mfma_f32_16x16x32_bf16 v[98:101], v[138:141], v[212:215], v[98:101]
	v_mfma_f32_16x16x32_bf16 v[126:129], v[134:137], v[192:195], v[126:129]
	v_mfma_f32_16x16x32_bf16 v[122:125], v[142:145], v[192:195], v[122:125]
	v_mfma_f32_16x16x32_bf16 v[118:121], v[134:137], v[200:203], v[118:121]
	v_mfma_f32_16x16x32_bf16 v[114:117], v[142:145], v[200:203], v[114:117]
	v_mfma_f32_16x16x32_bf16 v[110:113], v[134:137], v[208:211], v[110:113]
	v_mfma_f32_16x16x32_bf16 v[106:109], v[142:145], v[208:211], v[106:109]
	v_mfma_f32_16x16x32_bf16 v[102:105], v[134:137], v[216:219], v[102:105]
	v_mfma_f32_16x16x32_bf16 v[98:101], v[142:145], v[216:219], v[98:101]
	s_waitcnt lgkmcnt(0)
	v_mfma_f32_16x16x32_bf16 v[62:65], v[146:149], v[188:191], v[62:65]
	v_mfma_f32_16x16x32_bf16 v[58:61], v[168:171], v[188:191], v[58:61]
	v_mfma_f32_16x16x32_bf16 v[54:57], v[146:149], v[196:199], v[54:57]
	v_mfma_f32_16x16x32_bf16 v[50:53], v[168:171], v[196:199], v[50:53]
	v_mfma_f32_16x16x32_bf16 v[46:49], v[146:149], v[204:207], v[46:49]
	v_mfma_f32_16x16x32_bf16 v[42:45], v[168:171], v[204:207], v[42:45]
	v_mfma_f32_16x16x32_bf16 v[38:41], v[146:149], v[212:215], v[38:41]
	v_mfma_f32_16x16x32_bf16 v[34:37], v[168:171], v[212:215], v[34:37]
	v_mfma_f32_16x16x32_bf16 v[62:65], v[150:153], v[192:195], v[62:65]
	v_mfma_f32_16x16x32_bf16 v[58:61], v[184:187], v[192:195], v[58:61]
	v_mfma_f32_16x16x32_bf16 v[54:57], v[150:153], v[200:203], v[54:57]
	v_mfma_f32_16x16x32_bf16 v[50:53], v[184:187], v[200:203], v[50:53]
	v_mfma_f32_16x16x32_bf16 v[46:49], v[150:153], v[208:211], v[46:49]
	v_mfma_f32_16x16x32_bf16 v[42:45], v[184:187], v[208:211], v[42:45]
	v_mfma_f32_16x16x32_bf16 v[38:41], v[150:153], v[216:219], v[38:41]
	v_mfma_f32_16x16x32_bf16 v[34:37], v[184:187], v[216:219], v[34:37]
	s_setprio 0
	s_barrier
	s_add_i32 s22, s51, s25
	v_lshl_add_u64 v[172:173], s[26:27], 0, v[158:159]
	s_mov_b32 m0, s22
	ds_read_b128 v[188:191], v167 offset:16384
	ds_read_b128 v[192:195], v167 offset:17408
	ds_read_b128 v[196:199], v167 offset:18432
	ds_read_b128 v[200:203], v167 offset:19456
	ds_read_b128 v[204:207], v167 offset:20480
	ds_read_b128 v[208:211], v167 offset:21504
	ds_read_b128 v[212:215], v167 offset:22528
	ds_read_b128 v[216:219], v167 offset:23552
	global_load_lds_dwordx4 v[172:173], off
	s_add_i32 m0, s22, 0x2000
	s_add_u32 s22, s26, 0x18000
	v_lshl_add_u64 v[174:175], s[26:27], 0, v[154:155]
	s_addc_u32 s23, s27, 0
	s_add_i32 s51, s52, s25
	global_load_lds_dwordx4 v[174:175], off
	v_lshl_add_u64 v[176:177], s[22:23], 0, v[158:159]
	s_mov_b32 m0, s51
	v_lshl_add_u64 v[220:221], s[30:31], 0, v[156:157]
	global_load_lds_dwordx4 v[176:177], off
	v_lshl_add_u64 v[176:177], s[22:23], 0, v[154:155]
	s_add_i32 m0, s51, 0x2000
	s_nop 0
	global_load_lds_dwordx4 v[176:177], off
	v_lshl_add_u64 v[176:177], s[30:31], 0, v[160:161]
	s_mov_b32 m0, s29
	s_nop 0
	global_load_lds_dwordx4 v[176:177], off
	s_mov_b32 m0, s35
	s_nop 0
	global_load_lds_dwordx4 v[220:221], off
	s_waitcnt vmcnt(8)
	s_waitcnt lgkmcnt(0)
	s_setprio 1
	s_barrier
	s_waitcnt lgkmcnt(0)
	v_mfma_f32_16x16x32_bf16 v[94:97], v[130:133], v[188:191], v[94:97]
	v_mfma_f32_16x16x32_bf16 v[90:93], v[138:141], v[188:191], v[90:93]
	v_mfma_f32_16x16x32_bf16 v[86:89], v[130:133], v[196:199], v[86:89]
	v_mfma_f32_16x16x32_bf16 v[82:85], v[138:141], v[196:199], v[82:85]
	v_mfma_f32_16x16x32_bf16 v[78:81], v[130:133], v[204:207], v[78:81]
	v_mfma_f32_16x16x32_bf16 v[74:77], v[138:141], v[204:207], v[74:77]
	v_mfma_f32_16x16x32_bf16 v[70:73], v[130:133], v[212:215], v[70:73]
	v_mfma_f32_16x16x32_bf16 v[66:69], v[138:141], v[212:215], v[66:69]
	v_mfma_f32_16x16x32_bf16 v[94:97], v[134:137], v[192:195], v[94:97]
	v_mfma_f32_16x16x32_bf16 v[90:93], v[142:145], v[192:195], v[90:93]
	v_mfma_f32_16x16x32_bf16 v[86:89], v[134:137], v[200:203], v[86:89]
	v_mfma_f32_16x16x32_bf16 v[82:85], v[142:145], v[200:203], v[82:85]
	v_mfma_f32_16x16x32_bf16 v[78:81], v[134:137], v[208:211], v[78:81]
	v_mfma_f32_16x16x32_bf16 v[74:77], v[142:145], v[208:211], v[74:77]
	v_mfma_f32_16x16x32_bf16 v[70:73], v[134:137], v[216:219], v[70:73]
	v_mfma_f32_16x16x32_bf16 v[66:69], v[142:145], v[216:219], v[66:69]
	v_mfma_f32_16x16x32_bf16 v[30:33], v[146:149], v[188:191], v[30:33]
	v_mfma_f32_16x16x32_bf16 v[26:29], v[168:171], v[188:191], v[26:29]
	v_mfma_f32_16x16x32_bf16 v[22:25], v[146:149], v[196:199], v[22:25]
	v_mfma_f32_16x16x32_bf16 v[18:21], v[168:171], v[196:199], v[18:21]
	v_mfma_f32_16x16x32_bf16 v[14:17], v[146:149], v[204:207], v[14:17]
	v_mfma_f32_16x16x32_bf16 v[8:11], v[168:171], v[204:207], v[8:11]
	v_mfma_f32_16x16x32_bf16 v[4:7], v[146:149], v[212:215], v[4:7]
	v_mfma_f32_16x16x32_bf16 v[0:3], v[168:171], v[212:215], v[0:3]
	v_mfma_f32_16x16x32_bf16 v[30:33], v[150:153], v[192:195], v[30:33]
	v_mfma_f32_16x16x32_bf16 v[26:29], v[184:187], v[192:195], v[26:29]
	v_mfma_f32_16x16x32_bf16 v[22:25], v[150:153], v[200:203], v[22:25]
	v_mfma_f32_16x16x32_bf16 v[18:21], v[184:187], v[200:203], v[18:21]
	v_mfma_f32_16x16x32_bf16 v[14:17], v[150:153], v[208:211], v[14:17]
	v_mfma_f32_16x16x32_bf16 v[8:11], v[184:187], v[208:211], v[8:11]
	v_mfma_f32_16x16x32_bf16 v[4:7], v[150:153], v[216:219], v[4:7]
	v_mfma_f32_16x16x32_bf16 v[0:3], v[184:187], v[216:219], v[0:3]
	s_setprio 0
	s_barrier
	s_add_i32 s51, 0, 0x18000
	v_add_u32_e32 v12, s51, v166
	s_add_i32 s52, 0, 0x1c000
	ds_read_b128 v[130:133], v12
	ds_read_b128 v[134:137], v12 offset:1024
	ds_read_b128 v[138:141], v12 offset:2048
	ds_read_b128 v[142:145], v12 offset:3072
	v_add_u32_e32 v12, s52, v166
	ds_read_b128 v[188:191], v167 offset:32768
	ds_read_b128 v[192:195], v167 offset:33792
	ds_read_b128 v[196:199], v167 offset:34816
	ds_read_b128 v[200:203], v167 offset:35840
	ds_read_b128 v[204:207], v167 offset:36864
	ds_read_b128 v[208:211], v167 offset:37888
	ds_read_b128 v[212:215], v167 offset:38912
	ds_read_b128 v[216:219], v167 offset:39936
	ds_read_b128 v[146:149], v12
	ds_read_b128 v[150:153], v12 offset:1024
	ds_read_b128 v[168:171], v12 offset:2048
	ds_read_b128 v[184:187], v12 offset:3072
	s_add_u32 s22, s30, 0xc0000
	s_addc_u32 s23, s31, 0
	s_mov_b32 m0, s36
	v_lshl_add_u64 v[222:223], s[22:23], 0, v[160:161]
	global_load_lds_dwordx4 v[222:223], off
	v_lshl_add_u64 v[222:223], s[22:23], 0, v[156:157]
	s_mov_b32 m0, s37
	s_nop 0
	global_load_lds_dwordx4 v[222:223], off
	s_waitcnt vmcnt(8)
	s_cmp_lg_u64 s[10:11], 0
	s_cbranch_scc1 .Lpp_lead_8
	s_waitcnt lgkmcnt(0)
; #define PG8_STAGE(bufoff, gbase, voff) do { _Pragma("unroll") for (int _i = 0; _i < 2; ++_i) \
;         __builtin_amdgcn_global_load_lds((const unsigned*)((const char*)(gbase) + (voff)[_i]), (LAS unsigned*)(lds + (bufoff) + ldsw + _i * 8192), 16, 0, 0); } while (0)
; #define PG8_LDA(dst, b, h) do { _Pragma("unroll") for (int m = 0; m < 4; ++m) _Pragma("unroll") for (int k = 0; k < 2; ++k) dst[m][k] = *(const LAS bf16x8*)(lds + PG8_SA(b, h) + aoff + m * 2048 + k * 1024); } while (0)
; #define PG8_LDB(dst, b, h) do { _Pragma("unroll") for (int n = 0; n < 2; ++n) _Pragma("unroll") for (int k = 0; k < 2; ++k) dst[n][k] = *(const LAS bf16x8*)(lds + PG8_SB(b, h) + boff + n * 2048 + k * 1024); } while (0)
; #define PG8_MMA(ai, bj, At, Bt) do { __builtin_amdgcn_s_setprio(1); _Pragma("unroll") for (int m = 0; m < 4; ++m) _Pragma("unroll") for (int n = 0; n < 2; ++n) _Pragma("unroll") for (int k = 0; k < 2; ++k) \
;         acc[ai][bj][m][n] = __builtin_amdgcn_mfma_f32_16x16x32_bf16(Bt[n][k], At[m][k], acc[ai][bj][m][n], 0, 0, 0); __builtin_amdgcn_s_setprio(0); } while (0)
; #define PG8_WAIT_V(n) asm volatile("s_waitcnt vmcnt(" #n ")" ::: "memory")
; #define PG8_WAIT_L(n) asm volatile("s_waitcnt lgkmcnt(" #n ")" ::: "memory")
; #define PG8_BAR __builtin_amdgcn_s_barrier()
; #define PG8_SCHED __builtin_amdgcn_sched_barrier(0)
; template <class Epi>
; __device__ __forceinline__ void gemm_phase(LAS unsigned char* lds, const Gemm g, const StaticOrder& S, const Epi& E, int wave_s) {
;     ...
;             PG8_LDB(B0, 1, 0); PG8_LDB(B1, 1, 1); PG8_SCHED; PG8_LDA(At, 1, 0); PG8_STAGE(PG8_SA(0, 1), a2 + hstepA, voffA);
;             PG8_WAIT_V(8); PG8_WAIT_L(0); PG8_BAR; PG8_MMA(0, 0, At, B0); PG8_MMA(0, 1, At, B1); PG8_BAR; PG8_SCHED;
;             PG8_LDA(At, 1, 1); PG8_STAGE(PG8_SB(1, 0), b3, voffB); PG8_STAGE(PG8_SB(1, 1), b3 + hstepB, voffB); PG8_STAGE(PG8_SA(1, 0), a3, voffA);
;             PG8_WAIT_V(8); PG8_WAIT_L(0); PG8_BAR; PG8_MMA(1, 0, At, B0); PG8_MMA(1, 1, At, B1); PG8_BAR; PG8_SCHED;
;         }
;         if (wr == 0) PG8_BAR;
.Lpp_lead_8:
	s_waitcnt lgkmcnt(4)
	s_setprio 1
	s_barrier
	s_waitcnt lgkmcnt(4)
	v_mfma_f32_16x16x32_bf16 v[126:129], v[130:133], v[188:191], v[126:129]
	v_mfma_f32_16x16x32_bf16 v[122:125], v[138:141], v[188:191], v[122:125]
	v_mfma_f32_16x16x32_bf16 v[118:121], v[130:133], v[196:199], v[118:121]
	v_mfma_f32_16x16x32_bf16 v[114:117], v[138:141], v[196:199], v[114:117]
	v_mfma_f32_16x16x32_bf16 v[110:113], v[130:133], v[204:207], v[110:113]
	v_mfma_f32_16x16x32_bf16 v[106:109], v[138:141], v[204:207], v[106:109]
	v_mfma_f32_16x16x32_bf16 v[102:105], v[130:133], v[212:215], v[102:105]
	v_mfma_f32_16x16x32_bf16 v[98:101], v[138:141], v[212:215], v[98:101]
	v_mfma_f32_16x16x32_bf16 v[126:129], v[134:137], v[192:195], v[126:129]
	v_mfma_f32_16x16x32_bf16 v[122:125], v[142:145], v[192:195], v[122:125]
	v_mfma_f32_16x16x32_bf16 v[118:121], v[134:137], v[200:203], v[118:121]
	v_mfma_f32_16x16x32_bf16 v[114:117], v[142:145], v[200:203], v[114:117]
	v_mfma_f32_16x16x32_bf16 v[110:113], v[134:137], v[208:211], v[110:113]
	v_mfma_f32_16x16x32_bf16 v[106:109], v[142:145], v[208:211], v[106:109]
	v_mfma_f32_16x16x32_bf16 v[102:105], v[134:137], v[216:219], v[102:105]
	v_mfma_f32_16x16x32_bf16 v[98:101], v[142:145], v[216:219], v[98:101]
	s_waitcnt lgkmcnt(0)
	v_mfma_f32_16x16x32_bf16 v[62:65], v[146:149], v[188:191], v[62:65]
	v_mfma_f32_16x16x32_bf16 v[58:61], v[168:171], v[188:191], v[58:61]
	v_mfma_f32_16x16x32_bf16 v[54:57], v[146:149], v[196:199], v[54:57]
	v_mfma_f32_16x16x32_bf16 v[50:53], v[168:171], v[196:199], v[50:53]
	v_mfma_f32_16x16x32_bf16 v[46:49], v[146:149], v[204:207], v[46:49]
	v_mfma_f32_16x16x32_bf16 v[42:45], v[168:171], v[204:207], v[42:45]
	v_mfma_f32_16x16x32_bf16 v[38:41], v[146:149], v[212:215], v[38:41]
	v_mfma_f32_16x16x32_bf16 v[34:37], v[168:171], v[212:215], v[34:37]
	v_mfma_f32_16x16x32_bf16 v[62:65], v[150:153], v[192:195], v[62:65]
	v_mfma_f32_16x16x32_bf16 v[58:61], v[184:187], v[192:195], v[58:61]
	v_mfma_f32_16x16x32_bf16 v[54:57], v[150:153], v[200:203], v[54:57]
	v_mfma_f32_16x16x32_bf16 v[50:53], v[184:187], v[200:203], v[50:53]
	v_mfma_f32_16x16x32_bf16 v[46:49], v[150:153], v[208:211], v[46:49]
	v_mfma_f32_16x16x32_bf16 v[42:45], v[184:187], v[208:211], v[42:45]
	v_mfma_f32_16x16x32_bf16 v[38:41], v[150:153], v[216:219], v[38:41]
	v_mfma_f32_16x16x32_bf16 v[34:37], v[184:187], v[216:219], v[34:37]
	s_setprio 0
	s_barrier
	s_add_i32 s22, s51, s25
	v_lshl_add_u64 v[172:173], v[172:173], 0, s[84:85]
	s_mov_b32 m0, s22
	ds_read_b128 v[188:191], v167 offset:49152
	ds_read_b128 v[192:195], v167 offset:50176
	ds_read_b128 v[196:199], v167 offset:51200
	ds_read_b128 v[200:203], v167 offset:52224
	ds_read_b128 v[204:207], v167 offset:53248
	ds_read_b128 v[208:211], v167 offset:54272
	ds_read_b128 v[212:215], v167 offset:55296
	ds_read_b128 v[216:219], v167 offset:56320
	global_load_lds_dwordx4 v[172:173], off
	s_add_i32 m0, s22, 0x2000
	s_add_u32 s22, s26, 0x18080
	v_lshl_add_u64 v[172:173], v[174:175], 0, s[84:85]
	s_addc_u32 s23, s27, 0
	s_add_i32 s26, s52, s25
	global_load_lds_dwordx4 v[172:173], off
	v_lshl_add_u64 v[172:173], s[22:23], 0, v[158:159]
	s_mov_b32 m0, s26
	s_nop 0
	global_load_lds_dwordx4 v[172:173], off
	v_lshl_add_u64 v[172:173], s[22:23], 0, v[154:155]
	s_add_i32 m0, s26, 0x2000
	s_nop 0
	global_load_lds_dwordx4 v[172:173], off
	v_lshl_add_u64 v[172:173], v[176:177], 0, s[84:85]
	s_mov_b32 m0, s41
	s_nop 0
	global_load_lds_dwordx4 v[172:173], off
	v_lshl_add_u64 v[172:173], v[220:221], 0, s[84:85]
	s_mov_b32 m0, s42
	s_nop 0
	global_load_lds_dwordx4 v[172:173], off
	s_waitcnt vmcnt(8)
	s_waitcnt lgkmcnt(0)
	s_setprio 1
	s_barrier
	s_waitcnt lgkmcnt(0)
	v_mfma_f32_16x16x32_bf16 v[94:97], v[130:133], v[188:191], v[94:97]
	v_mfma_f32_16x16x32_bf16 v[90:93], v[138:141], v[188:191], v[90:93]
	v_mfma_f32_16x16x32_bf16 v[86:89], v[130:133], v[196:199], v[86:89]
	v_mfma_f32_16x16x32_bf16 v[82:85], v[138:141], v[196:199], v[82:85]
	v_mfma_f32_16x16x32_bf16 v[78:81], v[130:133], v[204:207], v[78:81]
	v_mfma_f32_16x16x32_bf16 v[74:77], v[138:141], v[204:207], v[74:77]
	v_mfma_f32_16x16x32_bf16 v[70:73], v[130:133], v[212:215], v[70:73]
	v_mfma_f32_16x16x32_bf16 v[66:69], v[138:141], v[212:215], v[66:69]
	v_mfma_f32_16x16x32_bf16 v[94:97], v[134:137], v[192:195], v[94:97]
	v_mfma_f32_16x16x32_bf16 v[90:93], v[142:145], v[192:195], v[90:93]
	v_mfma_f32_16x16x32_bf16 v[86:89], v[134:137], v[200:203], v[86:89]
	v_mfma_f32_16x16x32_bf16 v[82:85], v[142:145], v[200:203], v[82:85]
	v_mfma_f32_16x16x32_bf16 v[78:81], v[134:137], v[208:211], v[78:81]
	v_mfma_f32_16x16x32_bf16 v[74:77], v[142:145], v[208:211], v[74:77]
	v_mfma_f32_16x16x32_bf16 v[70:73], v[134:137], v[216:219], v[70:73]
	v_mfma_f32_16x16x32_bf16 v[66:69], v[142:145], v[216:219], v[66:69]
	v_mfma_f32_16x16x32_bf16 v[30:33], v[146:149], v[188:191], v[30:33]
	v_mfma_f32_16x16x32_bf16 v[26:29], v[168:171], v[188:191], v[26:29]
	v_mfma_f32_16x16x32_bf16 v[22:25], v[146:149], v[196:199], v[22:25]
	v_mfma_f32_16x16x32_bf16 v[18:21], v[168:171], v[196:199], v[18:21]
	v_mfma_f32_16x16x32_bf16 v[14:17], v[146:149], v[204:207], v[14:17]
	v_mfma_f32_16x16x32_bf16 v[8:11], v[168:171], v[204:207], v[8:11]
	v_mfma_f32_16x16x32_bf16 v[4:7], v[146:149], v[212:215], v[4:7]
	v_mfma_f32_16x16x32_bf16 v[0:3], v[168:171], v[212:215], v[0:3]
	v_mfma_f32_16x16x32_bf16 v[30:33], v[150:153], v[192:195], v[30:33]
	v_mfma_f32_16x16x32_bf16 v[26:29], v[184:187], v[192:195], v[26:29]
	v_mfma_f32_16x16x32_bf16 v[22:25], v[150:153], v[200:203], v[22:25]
	v_mfma_f32_16x16x32_bf16 v[18:21], v[184:187], v[200:203], v[18:21]
	v_mfma_f32_16x16x32_bf16 v[14:17], v[150:153], v[208:211], v[14:17]
	v_mfma_f32_16x16x32_bf16 v[8:11], v[184:187], v[208:211], v[8:11]
	v_mfma_f32_16x16x32_bf16 v[4:7], v[150:153], v[216:219], v[4:7]
	v_mfma_f32_16x16x32_bf16 v[0:3], v[184:187], v[216:219], v[0:3]
	s_setprio 0
	s_barrier
	s_add_i32 s50, s50, 2
	s_add_u32 s48, s48, 0x100
	s_addc_u32 s49, s49, 0
	s_cmp_gt_u32 s50, 3
	s_mov_b64 s[22:23], s[6:7]
	s_cbranch_scc0 .LBB0_343
	s_and_b64 vcc, exec, s[10:11]
	s_cbranch_vccz .LBB0_346
	s_barrier

; #define PG8_STAGE(bufoff, gbase, voff) do { _Pragma("unroll") for (int _i = 0; _i < 2; ++_i) \
;         __builtin_amdgcn_global_load_lds((const unsigned*)((const char*)(gbase) + (voff)[_i]), (LAS unsigned*)(lds + (bufoff) + ldsw + _i * 8192), 16, 0, 0); } while (0)
; #define PG8_LDA(dst, b, h) do { _Pragma("unroll") for (int m = 0; m < 4; ++m) _Pragma("unroll") for (int k = 0; k < 2; ++k) dst[m][k] = *(const LAS bf16x8*)(lds + PG8_SA(b, h) + aoff + m * 2048 + k * 1024); } while (0)
; #define PG8_LDB(dst, b, h) do { _Pragma("unroll") for (int n = 0; n < 2; ++n) _Pragma("unroll") for (int k = 0; k < 2; ++k) dst[n][k] = *(const LAS bf16x8*)(lds + PG8_SB(b, h) + boff + n * 2048 + k * 1024); } while (0)
; #define PG8_MMA(ai, bj, At, Bt) do { __builtin_amdgcn_s_setprio(1); _Pragma("unroll") for (int m = 0; m < 4; ++m) _Pragma("unroll") for (int n = 0; n < 2; ++n) _Pragma("unroll") for (int k = 0; k < 2; ++k) \
;         acc[ai][bj][m][n] = __builtin_amdgcn_mfma_f32_16x16x32_bf16(Bt[n][k], At[m][k], acc[ai][bj][m][n], 0, 0, 0); __builtin_amdgcn_s_setprio(0); } while (0)
; #define PG8_WAIT_V(n) asm volatile("s_waitcnt vmcnt(" #n ")" ::: "memory")
; #define PG8_WAIT_L(n) asm volatile("s_waitcnt lgkmcnt(" #n ")" ::: "memory")
; #define PG8_BAR __builtin_amdgcn_s_barrier()
; #define PG8_SCHED __builtin_amdgcn_sched_barrier(0)
; template <class Epi>
; __device__ __forceinline__ void gemm_phase(LAS unsigned char* lds, const Gemm g, const StaticOrder& S, const Epi& E, int wave_s) {
;     ...
;             PG8_LDB(B0, 0, 0); PG8_LDB(B1, 0, 1); PG8_SCHED; PG8_LDA(At, 0, 0); PG8_STAGE(PG8_SA(1, 1), a1 + hstepA, voffA);
;             PG8_WAIT_V(8); PG8_WAIT_L(0); PG8_BAR; PG8_MMA(0, 0, At, B0); PG8_MMA(0, 1, At, B1); PG8_BAR; PG8_SCHED;
;             PG8_LDA(At, 0, 1); PG8_STAGE(PG8_SB(0, 0), b2, voffB); PG8_STAGE(PG8_SB(0, 1), b2 + hstepB, voffB); PG8_STAGE(PG8_SA(0, 0), a2, voffA);
;             PG8_WAIT_V(8); PG8_WAIT_L(0); PG8_BAR; PG8_MMA(1, 0, At, B0); PG8_MMA(1, 1, At, B1); PG8_BAR; PG8_SCHED;
;             PG8_LDB(B0, 1, 0); PG8_LDB(B1, 1, 1); PG8_SCHED; PG8_LDA(At, 1, 0); PG8_STAGE(PG8_SA(0, 1), a2 + hstepA, voffA);
.Lpp_lead_1:
	s_waitcnt lgkmcnt(4)
	s_setprio 1
	s_barrier
	s_waitcnt lgkmcnt(4)
	v_mfma_f32_16x16x32_bf16 v[66:69], v[0:3], v[34:37], 0
	v_mfma_f32_16x16x32_bf16 v[70:73], v[8:11], v[34:37], 0
	v_mfma_f32_16x16x32_bf16 v[74:77], v[0:3], v[42:45], 0
	v_mfma_f32_16x16x32_bf16 v[78:81], v[8:11], v[42:45], 0
	v_mfma_f32_16x16x32_bf16 v[82:85], v[0:3], v[50:53], 0
	v_mfma_f32_16x16x32_bf16 v[86:89], v[8:11], v[50:53], 0
	v_mfma_f32_16x16x32_bf16 v[90:93], v[0:3], v[58:61], 0
	v_mfma_f32_16x16x32_bf16 v[94:97], v[8:11], v[58:61], 0
	v_mfma_f32_16x16x32_bf16 v[66:69], v[4:7], v[38:41], v[66:69]
	v_mfma_f32_16x16x32_bf16 v[70:73], v[14:17], v[38:41], v[70:73]
	v_mfma_f32_16x16x32_bf16 v[74:77], v[4:7], v[46:49], v[74:77]
	v_mfma_f32_16x16x32_bf16 v[78:81], v[14:17], v[46:49], v[78:81]
	v_mfma_f32_16x16x32_bf16 v[82:85], v[4:7], v[54:57], v[82:85]
	v_mfma_f32_16x16x32_bf16 v[86:89], v[14:17], v[54:57], v[86:89]
	v_mfma_f32_16x16x32_bf16 v[90:93], v[4:7], v[62:65], v[90:93]
	v_mfma_f32_16x16x32_bf16 v[94:97], v[14:17], v[62:65], v[94:97]
	s_waitcnt lgkmcnt(0)
	v_mfma_f32_16x16x32_bf16 v[98:101], v[18:21], v[34:37], 0
	v_mfma_f32_16x16x32_bf16 v[34:37], v[26:29], v[34:37], 0
	v_mfma_f32_16x16x32_bf16 v[98:101], v[22:25], v[38:41], v[98:101]
	v_mfma_f32_16x16x32_bf16 v[34:37], v[30:33], v[38:41], v[34:37]
	v_mfma_f32_16x16x32_bf16 v[38:41], v[18:21], v[42:45], 0
	v_mfma_f32_16x16x32_bf16 v[42:45], v[26:29], v[42:45], 0
	v_mfma_f32_16x16x32_bf16 v[38:41], v[22:25], v[46:49], v[38:41]
	v_mfma_f32_16x16x32_bf16 v[42:45], v[30:33], v[46:49], v[42:45]
	v_mfma_f32_16x16x32_bf16 v[46:49], v[18:21], v[50:53], 0
	v_mfma_f32_16x16x32_bf16 v[50:53], v[26:29], v[50:53], 0
	v_mfma_f32_16x16x32_bf16 v[46:49], v[22:25], v[54:57], v[46:49]
	v_mfma_f32_16x16x32_bf16 v[50:53], v[30:33], v[54:57], v[50:53]
	v_mfma_f32_16x16x32_bf16 v[54:57], v[18:21], v[58:61], 0
	v_mfma_f32_16x16x32_bf16 v[58:61], v[26:29], v[58:61], 0
	v_mfma_f32_16x16x32_bf16 v[54:57], v[22:25], v[62:65], v[54:57]
	v_mfma_f32_16x16x32_bf16 v[58:61], v[30:33], v[62:65], v[58:61]
	s_setprio 0
	s_barrier
	s_add_i32 s45, s45, s30
	v_lshl_add_u64 v[172:173], s[22:23], 0, v[150:151]
	s_add_i32 s36, s45, 0x2000
	v_lshl_add_u64 v[130:131], v[172:173], 0, s[58:59]
	s_mov_b32 m0, s45
	v_lshl_add_u64 v[174:175], s[22:23], 0, v[146:147]
	s_add_u32 s48, s22, 0x10100
	ds_read_b128 v[62:65], v162 offset:16384
	ds_read_b128 v[102:105], v162 offset:17408
	ds_read_b128 v[106:109], v162 offset:18432
	ds_read_b128 v[110:113], v162 offset:19456
	ds_read_b128 v[114:117], v162 offset:20480
	ds_read_b128 v[118:121], v162 offset:21504
	ds_read_b128 v[122:125], v162 offset:22528
	ds_read_b128 v[126:129], v162 offset:23552
	global_load_lds_dwordx4 v[130:131], off
	v_lshl_add_u64 v[130:131], v[174:175], 0, s[58:59]
	s_mov_b32 m0, s36
	s_addc_u32 s49, s23, 0
	s_add_i32 s37, s44, s30
	global_load_lds_dwordx4 v[130:131], off
	v_lshl_add_u64 v[130:131], s[48:49], 0, v[150:151]
	s_mov_b32 m0, s37
	s_add_i32 s44, s37, 0x2000
	global_load_lds_dwordx4 v[130:131], off
	v_lshl_add_u64 v[130:131], s[48:49], 0, v[146:147]
	s_mov_b32 m0, s44
	v_lshl_add_u64 v[176:177], s[26:27], 0, v[152:153]
	global_load_lds_dwordx4 v[130:131], off
	v_lshl_add_u64 v[130:131], v[176:177], 0, s[58:59]
	s_mov_b32 m0, s31
	v_lshl_add_u64 v[214:215], s[26:27], 0, v[148:149]
	global_load_lds_dwordx4 v[130:131], off
	v_lshl_add_u64 v[130:131], v[214:215], 0, s[58:59]
	s_mov_b32 m0, s40
	s_nop 0
	global_load_lds_dwordx4 v[130:131], off
	s_waitcnt vmcnt(8)
	s_waitcnt lgkmcnt(0)
	s_setprio 1
	s_barrier
	s_waitcnt lgkmcnt(0)
	v_mfma_f32_16x16x32_bf16 v[130:133], v[0:3], v[62:65], 0
	v_mfma_f32_16x16x32_bf16 v[138:141], v[0:3], v[106:109], 0
	v_mfma_f32_16x16x32_bf16 v[156:159], v[0:3], v[114:117], 0
	v_mfma_f32_16x16x32_bf16 v[0:3], v[0:3], v[122:125], 0
	v_mfma_f32_16x16x32_bf16 v[130:133], v[4:7], v[102:105], v[130:133]
	v_mfma_f32_16x16x32_bf16 v[138:141], v[4:7], v[110:113], v[138:141]
	v_mfma_f32_16x16x32_bf16 v[156:159], v[4:7], v[118:121], v[156:159]
	v_mfma_f32_16x16x32_bf16 v[0:3], v[4:7], v[126:129], v[0:3]
	v_mfma_f32_16x16x32_bf16 v[4:7], v[8:11], v[122:125], 0
	v_mfma_f32_16x16x32_bf16 v[134:137], v[8:11], v[62:65], 0
	v_mfma_f32_16x16x32_bf16 v[142:145], v[8:11], v[106:109], 0
	v_mfma_f32_16x16x32_bf16 v[164:167], v[8:11], v[114:117], 0
	v_mfma_f32_16x16x32_bf16 v[4:7], v[14:17], v[126:129], v[4:7]
	v_mfma_f32_16x16x32_bf16 v[134:137], v[14:17], v[102:105], v[134:137]
	v_mfma_f32_16x16x32_bf16 v[142:145], v[14:17], v[110:113], v[142:145]
	v_mfma_f32_16x16x32_bf16 v[164:167], v[14:17], v[118:121], v[164:167]
	v_mfma_f32_16x16x32_bf16 v[8:11], v[18:21], v[62:65], 0
	v_mfma_f32_16x16x32_bf16 v[14:17], v[26:29], v[62:65], 0
	v_mfma_f32_16x16x32_bf16 v[8:11], v[22:25], v[102:105], v[8:11]
	v_mfma_f32_16x16x32_bf16 v[14:17], v[30:33], v[102:105], v[14:17]
	v_mfma_f32_16x16x32_bf16 v[62:65], v[18:21], v[106:109], 0
	v_mfma_f32_16x16x32_bf16 v[102:105], v[26:29], v[106:109], 0
	v_mfma_f32_16x16x32_bf16 v[106:109], v[18:21], v[114:117], 0
	v_mfma_f32_16x16x32_bf16 v[18:21], v[18:21], v[122:125], 0
	v_mfma_f32_16x16x32_bf16 v[62:65], v[22:25], v[110:113], v[62:65]
	v_mfma_f32_16x16x32_bf16 v[102:105], v[30:33], v[110:113], v[102:105]
	v_mfma_f32_16x16x32_bf16 v[106:109], v[22:25], v[118:121], v[106:109]
	v_mfma_f32_16x16x32_bf16 v[110:113], v[26:29], v[114:117], 0
	v_mfma_f32_16x16x32_bf16 v[18:21], v[22:25], v[126:129], v[18:21]
	v_mfma_f32_16x16x32_bf16 v[22:25], v[26:29], v[122:125], 0
	v_mfma_f32_16x16x32_bf16 v[110:113], v[30:33], v[118:121], v[110:113]
	v_mfma_f32_16x16x32_bf16 v[22:25], v[30:33], v[126:129], v[22:25]
	s_setprio 0
	s_barrier
	s_add_i32 s46, 0, 0x18000
	s_add_i32 s52, 0, 0x1c000
	v_add_u32_e32 v222, s46, v161
	v_add_u32_e32 v223, s52, v161
	ds_read_b128 v[26:29], v222
	ds_read_b128 v[30:33], v222 offset:1024
	ds_read_b128 v[114:117], v222 offset:2048
	ds_read_b128 v[118:121], v222 offset:3072
	ds_read_b128 v[182:185], v162 offset:32768
	ds_read_b128 v[186:189], v162 offset:33792
	ds_read_b128 v[190:193], v162 offset:34816
	ds_read_b128 v[194:197], v162 offset:35840
	ds_read_b128 v[198:201], v162 offset:36864
	ds_read_b128 v[202:205], v162 offset:37888
	ds_read_b128 v[206:209], v162 offset:38912
	ds_read_b128 v[210:213], v162 offset:39936
	ds_read_b128 v[122:125], v223
	ds_read_b128 v[126:129], v223 offset:1024
	ds_read_b128 v[168:171], v223 offset:2048
	ds_read_b128 v[178:181], v223 offset:3072
	s_add_u32 s48, s26, 0xc0100
	s_addc_u32 s49, s27, 0
	s_mov_b32 m0, s41
	v_lshl_add_u64 v[216:217], s[48:49], 0, v[152:153]
	global_load_lds_dwordx4 v[216:217], off
	v_lshl_add_u64 v[216:217], s[48:49], 0, v[148:149]
	s_mov_b32 m0, s42
	s_nop 0
	global_load_lds_dwordx4 v[216:217], off
	s_waitcnt vmcnt(8)
	s_cmp_lg_u64 s[6:7], 0
	s_cbranch_scc1 .Lpp_lead_2
	s_waitcnt lgkmcnt(0)
; #define PG8_STAGE(bufoff, gbase, voff) do { _Pragma("unroll") for (int _i = 0; _i < 2; ++_i) \
;         __builtin_amdgcn_global_load_lds((const unsigned*)((const char*)(gbase) + (voff)[_i]), (LAS unsigned*)(lds + (bufoff) + ldsw + _i * 8192), 16, 0, 0); } while (0)
; #define PG8_LDA(dst, b, h) do { _Pragma("unroll") for (int m = 0; m < 4; ++m) _Pragma("unroll") for (int k = 0; k < 2; ++k) dst[m][k] = *(const LAS bf16x8*)(lds + PG8_SA(b, h) + aoff + m * 2048 + k * 1024); } while (0)
; #define PG8_LDB(dst, b, h) do { _Pragma("unroll") for (int n = 0; n < 2; ++n) _Pragma("unroll") for (int k = 0; k < 2; ++k) dst[n][k] = *(const LAS bf16x8*)(lds + PG8_SB(b, h) + boff + n * 2048 + k * 1024); } while (0)
; #define PG8_MMA(ai, bj, At, Bt) do { __builtin_amdgcn_s_setprio(1); _Pragma("unroll") for (int m = 0; m < 4; ++m) _Pragma("unroll") for (int n = 0; n < 2; ++n) _Pragma("unroll") for (int k = 0; k < 2; ++k) \
;         acc[ai][bj][m][n] = __builtin_amdgcn_mfma_f32_16x16x32_bf16(Bt[n][k], At[m][k], acc[ai][bj][m][n], 0, 0, 0); __builtin_amdgcn_s_setprio(0); } while (0)
; #define PG8_WAIT_V(n) asm volatile("s_waitcnt vmcnt(" #n ")" ::: "memory")
; #define PG8_BAR __builtin_amdgcn_s_barrier()
; template <class Epi>
; __device__ __forceinline__ void gemm_phase(LAS unsigned char* lds, const Gemm g, const StaticOrder& S, const Epi& E, int wave_s) {
;     ...
;             PG8_LDB(B0, 0, 0); PG8_LDB(B1, 0, 1); PG8_SCHED; PG8_LDA(At, 0, 0); PG8_STAGE(PG8_SA(1, 1), a1 + hstepA, voffA);
;             PG8_WAIT_V(8); PG8_WAIT_L(0); PG8_BAR; PG8_MMA(0, 0, At, B0); PG8_MMA(0, 1, At, B1); PG8_BAR; PG8_SCHED;
;             PG8_LDA(At, 0, 1); PG8_STAGE(PG8_SB(0, 0), b2, voffB); PG8_STAGE(PG8_SB(0, 1), b2 + hstepB, voffB); PG8_STAGE(PG8_SA(0, 0), a2, voffA);
;             PG8_WAIT_V(8); PG8_WAIT_L(0); PG8_BAR; PG8_MMA(1, 0, At, B0); PG8_MMA(1, 1, At, B1); PG8_BAR; PG8_SCHED;
;             PG8_LDB(B0, 1, 0); PG8_LDB(B1, 1, 1); PG8_SCHED; PG8_LDA(At, 1, 0); PG8_STAGE(PG8_SA(0, 1), a2 + hstepA, voffA);
;             PG8_WAIT_V(8); PG8_WAIT_L(0); PG8_BAR; PG8_MMA(0, 0, At, B0); PG8_MMA(0, 1, At, B1); PG8_BAR; PG8_SCHED;
;             PG8_LDA(At, 1, 1); PG8_STAGE(PG8_SB(1, 0), b3, voffB); PG8_STAGE(PG8_SB(1, 1), b3 + hstepB, voffB); PG8_STAGE(PG8_SA(1, 0), a3, voffA);
;             PG8_WAIT_V(8); PG8_WAIT_L(0); PG8_BAR; PG8_MMA(1, 0, At, B0); PG8_MMA(1, 1, At, B1); PG8_BAR; PG8_SCHED;
.Lpp_lead_2:
	s_waitcnt lgkmcnt(4)
	s_setprio 1
	s_barrier
	s_waitcnt lgkmcnt(4)
	v_mfma_f32_16x16x32_bf16 v[66:69], v[26:29], v[182:185], v[66:69]
	v_mfma_f32_16x16x32_bf16 v[70:73], v[114:117], v[182:185], v[70:73]
	v_mfma_f32_16x16x32_bf16 v[74:77], v[26:29], v[190:193], v[74:77]
	v_mfma_f32_16x16x32_bf16 v[78:81], v[114:117], v[190:193], v[78:81]
	v_mfma_f32_16x16x32_bf16 v[82:85], v[26:29], v[198:201], v[82:85]
	v_mfma_f32_16x16x32_bf16 v[86:89], v[114:117], v[198:201], v[86:89]
	v_mfma_f32_16x16x32_bf16 v[90:93], v[26:29], v[206:209], v[90:93]
	v_mfma_f32_16x16x32_bf16 v[94:97], v[114:117], v[206:209], v[94:97]
	v_mfma_f32_16x16x32_bf16 v[66:69], v[30:33], v[186:189], v[66:69]
	v_mfma_f32_16x16x32_bf16 v[70:73], v[118:121], v[186:189], v[70:73]
	v_mfma_f32_16x16x32_bf16 v[74:77], v[30:33], v[194:197], v[74:77]
	v_mfma_f32_16x16x32_bf16 v[78:81], v[118:121], v[194:197], v[78:81]
	v_mfma_f32_16x16x32_bf16 v[82:85], v[30:33], v[202:205], v[82:85]
	v_mfma_f32_16x16x32_bf16 v[86:89], v[118:121], v[202:205], v[86:89]
	v_mfma_f32_16x16x32_bf16 v[90:93], v[30:33], v[210:213], v[90:93]
	v_mfma_f32_16x16x32_bf16 v[94:97], v[118:121], v[210:213], v[94:97]
	s_waitcnt lgkmcnt(0)
	v_mfma_f32_16x16x32_bf16 v[98:101], v[122:125], v[182:185], v[98:101]
	v_mfma_f32_16x16x32_bf16 v[34:37], v[168:171], v[182:185], v[34:37]
	v_mfma_f32_16x16x32_bf16 v[38:41], v[122:125], v[190:193], v[38:41]
	v_mfma_f32_16x16x32_bf16 v[42:45], v[168:171], v[190:193], v[42:45]
	v_mfma_f32_16x16x32_bf16 v[46:49], v[122:125], v[198:201], v[46:49]
	v_mfma_f32_16x16x32_bf16 v[50:53], v[168:171], v[198:201], v[50:53]
	v_mfma_f32_16x16x32_bf16 v[54:57], v[122:125], v[206:209], v[54:57]
	v_mfma_f32_16x16x32_bf16 v[58:61], v[168:171], v[206:209], v[58:61]
	v_mfma_f32_16x16x32_bf16 v[98:101], v[126:129], v[186:189], v[98:101]
	v_mfma_f32_16x16x32_bf16 v[34:37], v[178:181], v[186:189], v[34:37]
	v_mfma_f32_16x16x32_bf16 v[38:41], v[126:129], v[194:197], v[38:41]
	v_mfma_f32_16x16x32_bf16 v[42:45], v[178:181], v[194:197], v[42:45]
	v_mfma_f32_16x16x32_bf16 v[46:49], v[126:129], v[202:205], v[46:49]
	v_mfma_f32_16x16x32_bf16 v[50:53], v[178:181], v[202:205], v[50:53]
	v_mfma_f32_16x16x32_bf16 v[54:57], v[126:129], v[210:213], v[54:57]
	v_mfma_f32_16x16x32_bf16 v[58:61], v[178:181], v[210:213], v[58:61]
	s_setprio 0
	s_barrier
	s_add_i32 s48, s46, s30
	s_add_i32 s46, s48, 0x2000
	v_lshl_add_u64 v[172:173], v[172:173], 0, s[64:65]
	s_mov_b32 m0, s48
	s_add_u32 s50, s22, 0x10180
	ds_read_b128 v[182:185], v162 offset:49152
	ds_read_b128 v[186:189], v162 offset:50176
	ds_read_b128 v[190:193], v162 offset:51200
	ds_read_b128 v[194:197], v162 offset:52224
	ds_read_b128 v[198:201], v162 offset:53248
	ds_read_b128 v[202:205], v162 offset:54272
	ds_read_b128 v[206:209], v162 offset:55296
	ds_read_b128 v[210:213], v162 offset:56320
	global_load_lds_dwordx4 v[172:173], off
	v_lshl_add_u64 v[172:173], v[174:175], 0, s[64:65]
	s_mov_b32 m0, s46
	s_addc_u32 s51, s23, 0
	s_add_i32 s22, s52, s30
	global_load_lds_dwordx4 v[172:173], off
	v_lshl_add_u64 v[172:173], s[50:51], 0, v[150:151]
	s_mov_b32 m0, s22
	s_add_i32 s23, s22, 0x2000
	global_load_lds_dwordx4 v[172:173], off
	v_lshl_add_u64 v[172:173], s[50:51], 0, v[146:147]
	s_mov_b32 m0, s23
	s_nop 0
	global_load_lds_dwordx4 v[172:173], off
	v_lshl_add_u64 v[172:173], v[176:177], 0, s[64:65]
	s_mov_b32 m0, s43
	s_nop 0
	global_load_lds_dwordx4 v[172:173], off
	v_lshl_add_u64 v[172:173], v[214:215], 0, s[64:65]
	s_mov_b32 m0, s69
	s_nop 0
	global_load_lds_dwordx4 v[172:173], off
	s_waitcnt vmcnt(8)
	s_waitcnt lgkmcnt(0)
	s_setprio 1
	s_barrier
	s_waitcnt lgkmcnt(0)
	v_mfma_f32_16x16x32_bf16 v[0:3], v[26:29], v[206:209], v[0:3]
	v_mfma_f32_16x16x32_bf16 v[4:7], v[114:117], v[206:209], v[4:7]
	v_mfma_f32_16x16x32_bf16 v[130:133], v[26:29], v[182:185], v[130:133]
	v_mfma_f32_16x16x32_bf16 v[134:137], v[114:117], v[182:185], v[134:137]
	v_mfma_f32_16x16x32_bf16 v[138:141], v[26:29], v[190:193], v[138:141]
	v_mfma_f32_16x16x32_bf16 v[142:145], v[114:117], v[190:193], v[142:145]
	v_mfma_f32_16x16x32_bf16 v[156:159], v[26:29], v[198:201], v[156:159]
	v_mfma_f32_16x16x32_bf16 v[164:167], v[114:117], v[198:201], v[164:167]
	v_mfma_f32_16x16x32_bf16 v[0:3], v[30:33], v[210:213], v[0:3]
	v_mfma_f32_16x16x32_bf16 v[4:7], v[118:121], v[210:213], v[4:7]
	v_mfma_f32_16x16x32_bf16 v[130:133], v[30:33], v[186:189], v[130:133]
	v_mfma_f32_16x16x32_bf16 v[134:137], v[118:121], v[186:189], v[134:137]
	v_mfma_f32_16x16x32_bf16 v[138:141], v[30:33], v[194:197], v[138:141]
	v_mfma_f32_16x16x32_bf16 v[142:145], v[118:121], v[194:197], v[142:145]
	v_mfma_f32_16x16x32_bf16 v[156:159], v[30:33], v[202:205], v[156:159]
	v_mfma_f32_16x16x32_bf16 v[164:167], v[118:121], v[202:205], v[164:167]
	v_mfma_f32_16x16x32_bf16 v[8:11], v[122:125], v[182:185], v[8:11]
	v_mfma_f32_16x16x32_bf16 v[14:17], v[168:171], v[182:185], v[14:17]
	v_mfma_f32_16x16x32_bf16 v[26:29], v[122:125], v[190:193], v[62:65]
	v_mfma_f32_16x16x32_bf16 v[30:33], v[168:171], v[190:193], v[102:105]
	v_mfma_f32_16x16x32_bf16 v[62:65], v[122:125], v[198:201], v[106:109]
	v_mfma_f32_16x16x32_bf16 v[102:105], v[168:171], v[198:201], v[110:113]
	v_mfma_f32_16x16x32_bf16 v[18:21], v[122:125], v[206:209], v[18:21]
	v_mfma_f32_16x16x32_bf16 v[22:25], v[168:171], v[206:209], v[22:25]
	v_mfma_f32_16x16x32_bf16 v[8:11], v[126:129], v[186:189], v[8:11]
	v_mfma_f32_16x16x32_bf16 v[14:17], v[178:181], v[186:189], v[14:17]
	v_mfma_f32_16x16x32_bf16 v[26:29], v[126:129], v[194:197], v[26:29]
	v_mfma_f32_16x16x32_bf16 v[30:33], v[178:181], v[194:197], v[30:33]
	v_mfma_f32_16x16x32_bf16 v[62:65], v[126:129], v[202:205], v[62:65]
	v_mfma_f32_16x16x32_bf16 v[102:105], v[178:181], v[202:205], v[102:105]
	v_mfma_f32_16x16x32_bf16 v[18:21], v[126:129], v[210:213], v[18:21]
	v_mfma_f32_16x16x32_bf16 v[22:25], v[178:181], v[210:213], v[22:25]
	s_setprio 0
	s_barrier
	ds_read_b128 v[106:109], v163
	ds_read_b128 v[110:113], v163 offset:1024
	ds_read_b128 v[114:117], v163 offset:2048
	ds_read_b128 v[118:121], v163 offset:3072
	ds_read_b128 v[182:185], v162
	ds_read_b128 v[186:189], v162 offset:1024
	ds_read_b128 v[190:193], v162 offset:2048
	ds_read_b128 v[194:197], v162 offset:3072
	ds_read_b128 v[198:201], v162 offset:4096
	ds_read_b128 v[202:205], v162 offset:5120
	ds_read_b128 v[206:209], v162 offset:6144
	ds_read_b128 v[210:213], v162 offset:7168
	ds_read_b128 v[122:125], v218
	ds_read_b128 v[126:129], v218 offset:1024
	ds_read_b128 v[168:171], v218 offset:2048
	ds_read_b128 v[178:181], v218 offset:3072
	s_add_u32 s26, s26, 0xc0180
	s_addc_u32 s27, s27, 0
	s_mov_b32 m0, s47
	v_lshl_add_u64 v[172:173], s[26:27], 0, v[152:153]
	global_load_lds_dwordx4 v[172:173], off
	v_lshl_add_u64 v[172:173], s[26:27], 0, v[148:149]
	s_mov_b32 m0, s11
	s_nop 0
	global_load_lds_dwordx4 v[172:173], off
	s_waitcnt vmcnt(8)
	s_cmp_lg_u64 s[6:7], 0
	s_cbranch_scc1 .Lpp_lead_3
	s_waitcnt lgkmcnt(0)
; #define PG8_STAGE(bufoff, gbase, voff) do { _Pragma("unroll") for (int _i = 0; _i < 2; ++_i) \
;         __builtin_amdgcn_global_load_lds((const unsigned*)((const char*)(gbase) + (voff)[_i]), (LAS unsigned*)(lds + (bufoff) + ldsw + _i * 8192), 16, 0, 0); } while (0)
; #define PG8_LDA(dst, b, h) do { _Pragma("unroll") for (int m = 0; m < 4; ++m) _Pragma("unroll") for (int k = 0; k < 2; ++k) dst[m][k] = *(const LAS bf16x8*)(lds + PG8_SA(b, h) + aoff + m * 2048 + k * 1024); } while (0)
; #define PG8_LDB(dst, b, h) do { _Pragma("unroll") for (int n = 0; n < 2; ++n) _Pragma("unroll") for (int k = 0; k < 2; ++k) dst[n][k] = *(const LAS bf16x8*)(lds + PG8_SB(b, h) + boff + n * 2048 + k * 1024); } while (0)
; #define PG8_MMA(ai, bj, At, Bt) do { __builtin_amdgcn_s_setprio(1); _Pragma("unroll") for (int m = 0; m < 4; ++m) _Pragma("unroll") for (int n = 0; n < 2; ++n) _Pragma("unroll") for (int k = 0; k < 2; ++k) \
;         acc[ai][bj][m][n] = __builtin_amdgcn_mfma_f32_16x16x32_bf16(Bt[n][k], At[m][k], acc[ai][bj][m][n], 0, 0, 0); __builtin_amdgcn_s_setprio(0); } while (0)
; #define PG8_WAIT_V(n) asm volatile("s_waitcnt vmcnt(" #n ")" ::: "memory")
; #define PG8_BAR __builtin_amdgcn_s_barrier()
; template <class Epi>
; __device__ __forceinline__ void gemm_phase(LAS unsigned char* lds, const Gemm g, const StaticOrder& S, const Epi& E, int wave_s) {
;     ...
;             PG8_LDB(B0, 0, 0); PG8_LDB(B1, 0, 1); PG8_SCHED; PG8_LDA(At, 0, 0); PG8_STAGE(PG8_SA(1, 1), a1 + hstepA, voffA);
;             PG8_WAIT_V(8); PG8_WAIT_L(0); PG8_BAR; PG8_MMA(0, 0, At, B0); PG8_MMA(0, 1, At, B1); PG8_BAR; PG8_SCHED;
;             PG8_LDA(At, 0, 1); PG8_STAGE(PG8_SB(0, 0), b2, voffB); PG8_STAGE(PG8_SB(0, 1), b2 + hstepB, voffB); PG8_STAGE(PG8_SA(0, 0), a2, voffA);
;             PG8_WAIT_V(8); PG8_WAIT_L(0); PG8_BAR; PG8_MMA(1, 0, At, B0); PG8_MMA(1, 1, At, B1); PG8_BAR; PG8_SCHED;
;             PG8_LDB(B0, 1, 0); PG8_LDB(B1, 1, 1); PG8_SCHED; PG8_LDA(At, 1, 0); PG8_STAGE(PG8_SA(0, 1), a2 + hstepA, voffA);
;             PG8_WAIT_V(8); PG8_WAIT_L(0); PG8_BAR; PG8_MMA(0, 0, At, B0); PG8_MMA(0, 1, At, B1); PG8_BAR; PG8_SCHED;
;             PG8_LDA(At, 1, 1); PG8_STAGE(PG8_SB(1, 0), b3, voffB); PG8_STAGE(PG8_SB(1, 1), b3 + hstepB, voffB); PG8_STAGE(PG8_SA(1, 0), a3, voffA);
;             PG8_WAIT_V(8); PG8_WAIT_L(0); PG8_BAR; PG8_MMA(1, 0, At, B0); PG8_MMA(1, 1, At, B1); PG8_BAR; PG8_SCHED;
.Lpp_lead_3:
	s_waitcnt lgkmcnt(4)
	s_setprio 1
	s_barrier
	s_waitcnt lgkmcnt(4)
	v_mfma_f32_16x16x32_bf16 v[90:93], v[106:109], v[206:209], v[90:93]
	v_mfma_f32_16x16x32_bf16 v[66:69], v[106:109], v[182:185], v[66:69]
	v_mfma_f32_16x16x32_bf16 v[70:73], v[114:117], v[182:185], v[70:73]
	v_mfma_f32_16x16x32_bf16 v[74:77], v[106:109], v[190:193], v[74:77]
	v_mfma_f32_16x16x32_bf16 v[78:81], v[114:117], v[190:193], v[78:81]
	v_mfma_f32_16x16x32_bf16 v[82:85], v[106:109], v[198:201], v[82:85]
	v_mfma_f32_16x16x32_bf16 v[86:89], v[114:117], v[198:201], v[86:89]
	v_mfma_f32_16x16x32_bf16 v[214:217], v[110:113], v[210:213], v[90:93]
	v_mfma_f32_16x16x32_bf16 v[90:93], v[114:117], v[206:209], v[94:97]
	v_mfma_f32_16x16x32_bf16 v[66:69], v[110:113], v[186:189], v[66:69]
	v_mfma_f32_16x16x32_bf16 v[70:73], v[118:121], v[186:189], v[70:73]
	v_mfma_f32_16x16x32_bf16 v[74:77], v[110:113], v[194:197], v[74:77]
	v_mfma_f32_16x16x32_bf16 v[78:81], v[118:121], v[194:197], v[78:81]
	v_mfma_f32_16x16x32_bf16 v[82:85], v[110:113], v[202:205], v[82:85]
	v_mfma_f32_16x16x32_bf16 v[86:89], v[118:121], v[202:205], v[86:89]
	v_mfma_f32_16x16x32_bf16 v[94:97], v[118:121], v[210:213], v[90:93]
	s_waitcnt lgkmcnt(0)
	v_mfma_f32_16x16x32_bf16 v[34:37], v[168:171], v[182:185], v[34:37]
	v_mfma_f32_16x16x32_bf16 v[38:41], v[122:125], v[190:193], v[38:41]
	v_mfma_f32_16x16x32_bf16 v[42:45], v[168:171], v[190:193], v[42:45]
	v_mfma_f32_16x16x32_bf16 v[46:49], v[122:125], v[198:201], v[46:49]
	v_mfma_f32_16x16x32_bf16 v[50:53], v[168:171], v[198:201], v[50:53]
	v_mfma_f32_16x16x32_bf16 v[54:57], v[122:125], v[206:209], v[54:57]
	v_mfma_f32_16x16x32_bf16 v[58:61], v[168:171], v[206:209], v[58:61]
	v_mfma_f32_16x16x32_bf16 v[90:93], v[122:125], v[182:185], v[98:101]
	v_mfma_f32_16x16x32_bf16 v[34:37], v[178:181], v[186:189], v[34:37]
	v_mfma_f32_16x16x32_bf16 v[38:41], v[126:129], v[194:197], v[38:41]
	v_mfma_f32_16x16x32_bf16 v[42:45], v[178:181], v[194:197], v[42:45]
	v_mfma_f32_16x16x32_bf16 v[46:49], v[126:129], v[202:205], v[46:49]
	v_mfma_f32_16x16x32_bf16 v[50:53], v[178:181], v[202:205], v[50:53]
	v_mfma_f32_16x16x32_bf16 v[54:57], v[126:129], v[210:213], v[54:57]
	v_mfma_f32_16x16x32_bf16 v[58:61], v[178:181], v[210:213], v[58:61]
	v_mfma_f32_16x16x32_bf16 v[218:221], v[126:129], v[186:189], v[90:93]
	s_setprio 0
	s_barrier
	s_mov_b32 m0, s45
	v_lshl_add_u64 v[176:177], s[2:3], 0, v[150:151]
	s_add_u32 s26, s2, 0x10000
	ds_read_b128 v[90:93], v162 offset:16384
	ds_read_b128 v[98:101], v162 offset:17408
	ds_read_b128 v[182:185], v162 offset:18432
	ds_read_b128 v[186:189], v162 offset:19456
	ds_read_b128 v[190:193], v162 offset:20480
	ds_read_b128 v[194:197], v162 offset:21504
	ds_read_b128 v[198:201], v162 offset:22528
	ds_read_b128 v[202:205], v162 offset:23552
	global_load_lds_dwordx4 v[176:177], off
	v_lshl_add_u64 v[234:235], s[2:3], 0, v[146:147]
	s_mov_b32 m0, s36
	s_addc_u32 s27, s3, 0
	global_load_lds_dwordx4 v[234:235], off
	v_lshl_add_u64 v[172:173], s[26:27], 0, v[150:151]
	s_mov_b32 m0, s37
	v_lshl_add_u64 v[240:241], s[12:13], 0, v[152:153]
	global_load_lds_dwordx4 v[172:173], off
	v_lshl_add_u64 v[172:173], s[26:27], 0, v[146:147]
	s_mov_b32 m0, s44
	v_lshl_add_u64 v[250:251], s[12:13], 0, v[148:149]
	global_load_lds_dwordx4 v[172:173], off
	s_mov_b32 m0, s31
	s_nop 0
	global_load_lds_dwordx4 v[240:241], off
	s_mov_b32 m0, s40
	s_nop 0
	global_load_lds_dwordx4 v[250:251], off
	s_waitcnt vmcnt(8)
	s_waitcnt lgkmcnt(0)
	s_setprio 1
	s_barrier
	s_waitcnt lgkmcnt(0)
	v_mfma_f32_16x16x32_bf16 v[0:3], v[106:109], v[198:201], v[0:3]
	v_mfma_f32_16x16x32_bf16 v[4:7], v[114:117], v[198:201], v[4:7]
	v_mfma_f32_16x16x32_bf16 v[130:133], v[106:109], v[90:93], v[130:133]
	v_mfma_f32_16x16x32_bf16 v[134:137], v[114:117], v[90:93], v[134:137]
	v_mfma_f32_16x16x32_bf16 v[138:141], v[106:109], v[182:185], v[138:141]
	v_mfma_f32_16x16x32_bf16 v[142:145], v[114:117], v[182:185], v[142:145]
	v_mfma_f32_16x16x32_bf16 v[156:159], v[106:109], v[190:193], v[156:159]
	v_mfma_f32_16x16x32_bf16 v[164:167], v[114:117], v[190:193], v[164:167]
	v_mfma_f32_16x16x32_bf16 v[0:3], v[110:113], v[202:205], v[0:3]
	v_mfma_f32_16x16x32_bf16 v[4:7], v[118:121], v[202:205], v[4:7]
	v_mfma_f32_16x16x32_bf16 v[130:133], v[110:113], v[98:101], v[130:133]
	v_mfma_f32_16x16x32_bf16 v[134:137], v[118:121], v[98:101], v[134:137]
	v_mfma_f32_16x16x32_bf16 v[138:141], v[110:113], v[186:189], v[138:141]
	v_mfma_f32_16x16x32_bf16 v[142:145], v[118:121], v[186:189], v[142:145]
	v_mfma_f32_16x16x32_bf16 v[156:159], v[110:113], v[194:197], v[156:159]
	v_mfma_f32_16x16x32_bf16 v[164:167], v[118:121], v[194:197], v[164:167]
	v_mfma_f32_16x16x32_bf16 v[8:11], v[122:125], v[90:93], v[8:11]
	v_mfma_f32_16x16x32_bf16 v[206:209], v[126:129], v[98:101], v[8:11]
	v_mfma_f32_16x16x32_bf16 v[8:11], v[168:171], v[90:93], v[14:17]
	v_mfma_f32_16x16x32_bf16 v[14:17], v[178:181], v[98:101], v[8:11]
	v_mfma_f32_16x16x32_bf16 v[8:11], v[122:125], v[182:185], v[26:29]
	v_mfma_f32_16x16x32_bf16 v[210:213], v[126:129], v[186:189], v[8:11]
	v_mfma_f32_16x16x32_bf16 v[8:11], v[168:171], v[182:185], v[30:33]
	v_mfma_f32_16x16x32_bf16 v[30:33], v[178:181], v[186:189], v[8:11]
	v_mfma_f32_16x16x32_bf16 v[8:11], v[122:125], v[190:193], v[62:65]
	v_mfma_f32_16x16x32_bf16 v[182:185], v[126:129], v[194:197], v[8:11]
	v_mfma_f32_16x16x32_bf16 v[8:11], v[168:171], v[190:193], v[102:105]
	v_mfma_f32_16x16x32_bf16 v[186:189], v[178:181], v[194:197], v[8:11]
	v_mfma_f32_16x16x32_bf16 v[8:11], v[122:125], v[198:201], v[18:21]
	v_mfma_f32_16x16x32_bf16 v[190:193], v[126:129], v[202:205], v[8:11]
	v_mfma_f32_16x16x32_bf16 v[8:11], v[168:171], v[198:201], v[22:25]
	v_mfma_f32_16x16x32_bf16 v[168:171], v[178:181], v[202:205], v[8:11]
	s_setprio 0
	s_barrier
	s_nop 4
	ds_read_b128 v[8:11], v222
	ds_read_b128 v[22:25], v222 offset:1024
	ds_read_b128 v[62:65], v222 offset:2048
	ds_read_b128 v[178:181], v222 offset:3072
	ds_read_b128 v[18:21], v162 offset:32768
	ds_read_b128 v[26:29], v162 offset:33792
	ds_read_b128 v[102:105], v162 offset:34816
	ds_read_b128 v[226:229], v162 offset:35840
	ds_read_b128 v[230:233], v162 offset:36864
	ds_read_b128 v[242:245], v162 offset:37888
	ds_read_b128 v[246:249], v162 offset:38912
	ds_read_b128 v[172:175], v162 offset:39936
	ds_read_b128 v[194:197], v223
	ds_read_b128 v[198:201], v223 offset:1024
	ds_read_b128 v[202:205], v223 offset:2048
	ds_read_b128 v[222:225], v223 offset:3072
	s_add_u32 s26, s12, 0xc0000
	s_addc_u32 s27, s13, 0
	s_mov_b32 m0, s41
	v_lshl_add_u64 v[90:91], s[26:27], 0, v[152:153]
	global_load_lds_dwordx4 v[90:91], off
	v_lshl_add_u64 v[90:91], s[26:27], 0, v[148:149]
	s_mov_b32 m0, s42
	s_nop 0
	global_load_lds_dwordx4 v[90:91], off
	s_waitcnt vmcnt(8)
	s_cmp_lg_u64 s[6:7], 0
	s_cbranch_scc1 .Lpp_lead_4
	s_waitcnt lgkmcnt(0)
; #define PG8_STAGE(bufoff, gbase, voff) do { _Pragma("unroll") for (int _i = 0; _i < 2; ++_i) \
;         __builtin_amdgcn_global_load_lds((const unsigned*)((const char*)(gbase) + (voff)[_i]), (LAS unsigned*)(lds + (bufoff) + ldsw + _i * 8192), 16, 0, 0); } while (0)
; #define PG8_LDA(dst, b, h) do { _Pragma("unroll") for (int m = 0; m < 4; ++m) _Pragma("unroll") for (int k = 0; k < 2; ++k) dst[m][k] = *(const LAS bf16x8*)(lds + PG8_SA(b, h) + aoff + m * 2048 + k * 1024); } while (0)
; #define PG8_LDB(dst, b, h) do { _Pragma("unroll") for (int n = 0; n < 2; ++n) _Pragma("unroll") for (int k = 0; k < 2; ++k) dst[n][k] = *(const LAS bf16x8*)(lds + PG8_SB(b, h) + boff + n * 2048 + k * 1024); } while (0)
; #define PG8_MMA(ai, bj, At, Bt) do { __builtin_amdgcn_s_setprio(1); _Pragma("unroll") for (int m = 0; m < 4; ++m) _Pragma("unroll") for (int n = 0; n < 2; ++n) _Pragma("unroll") for (int k = 0; k < 2; ++k) \
;         acc[ai][bj][m][n] = __builtin_amdgcn_mfma_f32_16x16x32_bf16(Bt[n][k], At[m][k], acc[ai][bj][m][n], 0, 0, 0); __builtin_amdgcn_s_setprio(0); } while (0)
; #define PG8_WAIT_V(n) asm volatile("s_waitcnt vmcnt(" #n ")" ::: "memory")
; template <class Epi>
; __device__ __forceinline__ void gemm_phase(LAS unsigned char* lds, const Gemm g, const StaticOrder& S, const Epi& E, int wave_s) {
;     ...
;             PG8_LDB(B0, 0, 0); PG8_LDB(B1, 0, 1); PG8_SCHED; PG8_LDA(At, 0, 0); PG8_STAGE(PG8_SA(1, 1), a1 + hstepA, voffA);
;             PG8_WAIT_V(8); PG8_WAIT_L(0); PG8_BAR; PG8_MMA(0, 0, At, B0); PG8_MMA(0, 1, At, B1); PG8_BAR; PG8_SCHED;
;             PG8_LDA(At, 0, 1); PG8_STAGE(PG8_SB(0, 0), b2, voffB); PG8_STAGE(PG8_SB(0, 1), b2 + hstepB, voffB); PG8_STAGE(PG8_SA(0, 0), a2, voffA);
;             PG8_WAIT_V(8); PG8_WAIT_L(0); PG8_BAR; PG8_MMA(1, 0, At, B0); PG8_MMA(1, 1, At, B1); PG8_BAR; PG8_SCHED;
;             PG8_LDB(B0, 1, 0); PG8_LDB(B1, 1, 1); PG8_SCHED; PG8_LDA(At, 1, 0); PG8_STAGE(PG8_SA(0, 1), a2 + hstepA, voffA);
;             PG8_WAIT_V(8); PG8_WAIT_L(0); PG8_BAR; PG8_MMA(0, 0, At, B0); PG8_MMA(0, 1, At, B1); PG8_BAR; PG8_SCHED;
;             PG8_LDA(At, 1, 1); PG8_STAGE(PG8_SB(1, 0), b3, voffB); PG8_STAGE(PG8_SB(1, 1), b3 + hstepB, voffB); PG8_STAGE(PG8_SA(1, 0), a3, voffA);
;             PG8_WAIT_V(8); PG8_WAIT_L(0); PG8_BAR; PG8_MMA(1, 0, At, B0); PG8_MMA(1, 1, At, B1); PG8_BAR; PG8_SCHED;
;         }
;         if (wr == 0) PG8_BAR;
.Lpp_lead_4:
	s_waitcnt lgkmcnt(4)
	s_setprio 1
	s_barrier
	s_waitcnt lgkmcnt(4)
	v_mfma_f32_16x16x32_bf16 v[66:69], v[8:11], v[18:21], v[66:69]
	v_mfma_f32_16x16x32_bf16 v[122:125], v[22:25], v[26:29], v[66:69]
	v_mfma_f32_16x16x32_bf16 v[66:69], v[62:65], v[18:21], v[70:73]
	v_mfma_f32_16x16x32_bf16 v[114:117], v[178:181], v[26:29], v[66:69]
	v_mfma_f32_16x16x32_bf16 v[66:69], v[8:11], v[102:105], v[74:77]
	v_mfma_f32_16x16x32_bf16 v[106:109], v[22:25], v[226:229], v[66:69]
	v_mfma_f32_16x16x32_bf16 v[66:69], v[62:65], v[102:105], v[78:81]
	v_mfma_f32_16x16x32_bf16 v[98:101], v[178:181], v[226:229], v[66:69]
	v_mfma_f32_16x16x32_bf16 v[66:69], v[8:11], v[230:233], v[82:85]
	v_mfma_f32_16x16x32_bf16 v[90:93], v[22:25], v[242:245], v[66:69]
	v_mfma_f32_16x16x32_bf16 v[66:69], v[62:65], v[230:233], v[86:89]
	v_mfma_f32_16x16x32_bf16 v[82:85], v[178:181], v[242:245], v[66:69]
	v_mfma_f32_16x16x32_bf16 v[66:69], v[8:11], v[246:249], v[214:217]
	v_mfma_f32_16x16x32_bf16 v[74:77], v[22:25], v[172:175], v[66:69]
	v_mfma_f32_16x16x32_bf16 v[66:69], v[62:65], v[246:249], v[94:97]
	v_mfma_f32_16x16x32_bf16 v[66:69], v[178:181], v[172:175], v[66:69]
	s_waitcnt lgkmcnt(0)
	v_mfma_f32_16x16x32_bf16 v[70:73], v[194:197], v[18:21], v[218:221]
	v_mfma_f32_16x16x32_bf16 v[18:21], v[202:205], v[18:21], v[34:37]
	v_mfma_f32_16x16x32_bf16 v[118:121], v[222:225], v[26:29], v[18:21]
	v_mfma_f32_16x16x32_bf16 v[18:21], v[194:197], v[102:105], v[38:41]
	v_mfma_f32_16x16x32_bf16 v[110:113], v[198:201], v[226:229], v[18:21]
	v_mfma_f32_16x16x32_bf16 v[18:21], v[202:205], v[102:105], v[42:45]
	v_mfma_f32_16x16x32_bf16 v[102:105], v[222:225], v[226:229], v[18:21]
	v_mfma_f32_16x16x32_bf16 v[18:21], v[194:197], v[230:233], v[46:49]
	v_mfma_f32_16x16x32_bf16 v[94:97], v[198:201], v[242:245], v[18:21]
	v_mfma_f32_16x16x32_bf16 v[18:21], v[202:205], v[230:233], v[50:53]
	v_mfma_f32_16x16x32_bf16 v[86:89], v[222:225], v[242:245], v[18:21]
	v_mfma_f32_16x16x32_bf16 v[18:21], v[194:197], v[246:249], v[54:57]
	v_mfma_f32_16x16x32_bf16 v[78:81], v[198:201], v[172:175], v[18:21]
	v_mfma_f32_16x16x32_bf16 v[18:21], v[202:205], v[246:249], v[58:61]
	v_mfma_f32_16x16x32_bf16 v[126:129], v[198:201], v[26:29], v[70:73]
	v_mfma_f32_16x16x32_bf16 v[70:73], v[222:225], v[172:175], v[18:21]
	s_setprio 0
	s_barrier
	s_mov_b32 m0, s48
	s_nop 2
	v_lshl_add_u64 v[18:19], v[176:177], 0, s[84:85]
	s_add_u32 s2, s2, 0x10080
	ds_read_b128 v[38:41], v162 offset:49152
	ds_read_b128 v[46:49], v162 offset:50176
	ds_read_b128 v[172:175], v162 offset:51200
	ds_read_b128 v[214:217], v162 offset:52224
	ds_read_b128 v[218:221], v162 offset:53248
	ds_read_b128 v[226:229], v162 offset:54272
	ds_read_b128 v[230:233], v162 offset:55296
	ds_read_b128 v[242:245], v162 offset:56320
	global_load_lds_dwordx4 v[18:19], off
	v_lshl_add_u64 v[18:19], v[234:235], 0, s[84:85]
	s_mov_b32 m0, s46
	s_addc_u32 s3, s3, 0
	global_load_lds_dwordx4 v[18:19], off
	v_lshl_add_u64 v[18:19], s[2:3], 0, v[150:151]
	s_mov_b32 m0, s22
	s_nop 0
	global_load_lds_dwordx4 v[18:19], off
	v_lshl_add_u64 v[18:19], s[2:3], 0, v[146:147]
	s_mov_b32 m0, s23
	s_nop 0
	global_load_lds_dwordx4 v[18:19], off
	v_lshl_add_u64 v[18:19], v[240:241], 0, s[84:85]
	s_mov_b32 m0, s43
	s_nop 0
	global_load_lds_dwordx4 v[18:19], off
	v_lshl_add_u64 v[18:19], v[250:251], 0, s[84:85]
	s_mov_b32 m0, s69
	s_nop 0
	global_load_lds_dwordx4 v[18:19], off
	s_waitcnt vmcnt(8)
	s_waitcnt lgkmcnt(0)
	s_setprio 1
	s_barrier
	s_waitcnt lgkmcnt(0)
	v_mfma_f32_16x16x32_bf16 v[18:21], v[8:11], v[38:41], v[130:133]
	v_mfma_f32_16x16x32_bf16 v[58:61], v[22:25], v[46:49], v[18:21]
	v_mfma_f32_16x16x32_bf16 v[18:21], v[62:65], v[38:41], v[134:137]
	v_mfma_f32_16x16x32_bf16 v[50:53], v[178:181], v[46:49], v[18:21]
	v_mfma_f32_16x16x32_bf16 v[18:21], v[8:11], v[172:175], v[138:141]
	v_mfma_f32_16x16x32_bf16 v[42:45], v[22:25], v[214:217], v[18:21]
	v_mfma_f32_16x16x32_bf16 v[18:21], v[62:65], v[172:175], v[142:145]
	v_mfma_f32_16x16x32_bf16 v[34:37], v[178:181], v[214:217], v[18:21]
	v_mfma_f32_16x16x32_bf16 v[18:21], v[8:11], v[218:221], v[156:159]
	v_mfma_f32_16x16x32_bf16 v[0:3], v[8:11], v[230:233], v[0:3]
	v_mfma_f32_16x16x32_bf16 v[26:29], v[22:25], v[226:229], v[18:21]
	v_mfma_f32_16x16x32_bf16 v[18:21], v[62:65], v[218:221], v[164:167]
	v_mfma_f32_16x16x32_bf16 v[8:11], v[22:25], v[242:245], v[0:3]
	v_mfma_f32_16x16x32_bf16 v[0:3], v[62:65], v[230:233], v[4:7]
	v_mfma_f32_16x16x32_bf16 v[18:21], v[178:181], v[226:229], v[18:21]
	v_mfma_f32_16x16x32_bf16 v[0:3], v[178:181], v[242:245], v[0:3]
	v_mfma_f32_16x16x32_bf16 v[4:7], v[194:197], v[38:41], v[206:209]
	v_mfma_f32_16x16x32_bf16 v[62:65], v[198:201], v[46:49], v[4:7]
	v_mfma_f32_16x16x32_bf16 v[4:7], v[202:205], v[38:41], v[14:17]
	v_mfma_f32_16x16x32_bf16 v[54:57], v[222:225], v[46:49], v[4:7]
	v_mfma_f32_16x16x32_bf16 v[4:7], v[194:197], v[172:175], v[210:213]
	v_mfma_f32_16x16x32_bf16 v[46:49], v[198:201], v[214:217], v[4:7]
	v_mfma_f32_16x16x32_bf16 v[4:7], v[202:205], v[172:175], v[30:33]
	v_mfma_f32_16x16x32_bf16 v[38:41], v[222:225], v[214:217], v[4:7]
	v_mfma_f32_16x16x32_bf16 v[4:7], v[194:197], v[218:221], v[182:185]
	v_mfma_f32_16x16x32_bf16 v[30:33], v[198:201], v[226:229], v[4:7]
	v_mfma_f32_16x16x32_bf16 v[4:7], v[202:205], v[218:221], v[186:189]
	v_mfma_f32_16x16x32_bf16 v[22:25], v[222:225], v[226:229], v[4:7]
	v_mfma_f32_16x16x32_bf16 v[4:7], v[194:197], v[230:233], v[190:193]
	v_mfma_f32_16x16x32_bf16 v[14:17], v[198:201], v[242:245], v[4:7]
	v_mfma_f32_16x16x32_bf16 v[4:7], v[202:205], v[230:233], v[168:171]
	v_mfma_f32_16x16x32_bf16 v[4:7], v[222:225], v[242:245], v[4:7]
	s_setprio 0
	s_barrier
	s_andn2_b64 vcc, exec, s[6:7]
	s_cbranch_vccnz .LBB0_466
	s_barrier

; #define PG8_STAGE(bufoff, gbase, voff) do { _Pragma("unroll") for (int _i = 0; _i < 2; ++_i) \
;         __builtin_amdgcn_global_load_lds((const unsigned*)((const char*)(gbase) + (voff)[_i]), (LAS unsigned*)(lds + (bufoff) + ldsw + _i * 8192), 16, 0, 0); } while (0)
; #define PG8_LDA(dst, b, h) do { _Pragma("unroll") for (int m = 0; m < 4; ++m) _Pragma("unroll") for (int k = 0; k < 2; ++k) dst[m][k] = *(const LAS bf16x8*)(lds + PG8_SA(b, h) + aoff + m * 2048 + k * 1024); } while (0)
; #define PG8_LDB(dst, b, h) do { _Pragma("unroll") for (int n = 0; n < 2; ++n) _Pragma("unroll") for (int k = 0; k < 2; ++k) dst[n][k] = *(const LAS bf16x8*)(lds + PG8_SB(b, h) + boff + n * 2048 + k * 1024); } while (0)
; #define PG8_MMA(ai, bj, At, Bt) do { __builtin_amdgcn_s_setprio(1); _Pragma("unroll") for (int m = 0; m < 4; ++m) _Pragma("unroll") for (int n = 0; n < 2; ++n) _Pragma("unroll") for (int k = 0; k < 2; ++k) \
;         acc[ai][bj][m][n] = __builtin_amdgcn_mfma_f32_16x16x32_bf16(Bt[n][k], At[m][k], acc[ai][bj][m][n], 0, 0, 0); __builtin_amdgcn_s_setprio(0); } while (0)
; #define PG8_WAIT_V(n) asm volatile("s_waitcnt vmcnt(" #n ")" ::: "memory")
; #define PG8_BAR __builtin_amdgcn_s_barrier()
; template <class Epi>
; __device__ __forceinline__ void gemm_phase(LAS unsigned char* lds, const Gemm g, const StaticOrder& S, const Epi& E, int wave_s) {
;     ...
;             PG8_LDB(B0, 0, 0); PG8_LDB(B1, 0, 1); PG8_SCHED; PG8_LDA(At, 0, 0); PG8_STAGE(PG8_SA(1, 1), a1 + hstepA, voffA);
;             PG8_WAIT_V(8); PG8_WAIT_L(0); PG8_BAR; PG8_MMA(0, 0, At, B0); PG8_MMA(0, 1, At, B1); PG8_BAR; PG8_SCHED;
;             PG8_LDA(At, 0, 1); PG8_STAGE(PG8_SB(0, 0), b2, voffB); PG8_STAGE(PG8_SB(0, 1), b2 + hstepB, voffB); PG8_STAGE(PG8_SA(0, 0), a2, voffA);
;             PG8_WAIT_V(8); PG8_WAIT_L(0); PG8_BAR; PG8_MMA(1, 0, At, B0); PG8_MMA(1, 1, At, B1); PG8_BAR; PG8_SCHED;
;             PG8_LDB(B0, 1, 0); PG8_LDB(B1, 1, 1); PG8_SCHED; PG8_LDA(At, 1, 0); PG8_STAGE(PG8_SA(0, 1), a2 + hstepA, voffA);
;             PG8_WAIT_V(8); PG8_WAIT_L(0); PG8_BAR; PG8_MMA(0, 0, At, B0); PG8_MMA(0, 1, At, B1); PG8_BAR; PG8_SCHED;
;             PG8_LDA(At, 1, 1); PG8_STAGE(PG8_SB(1, 0), b3, voffB); PG8_STAGE(PG8_SB(1, 1), b3 + hstepB, voffB); PG8_STAGE(PG8_SA(1, 0), a3, voffA);
;             PG8_WAIT_V(8); PG8_WAIT_L(0); PG8_BAR; PG8_MMA(1, 0, At, B0); PG8_MMA(1, 1, At, B1); PG8_BAR; PG8_SCHED;
.Lpp_lead_9:
	s_waitcnt lgkmcnt(4)
	s_setprio 1
	s_barrier
	s_waitcnt lgkmcnt(4)
	v_mfma_f32_16x16x32_bf16 v[106:109], v[130:133], v[186:189], v[106:109]
	v_mfma_f32_16x16x32_bf16 v[114:117], v[152:155], v[186:189], v[114:117]
	v_mfma_f32_16x16x32_bf16 v[98:101], v[130:133], v[194:197], v[98:101]
	v_mfma_f32_16x16x32_bf16 v[110:113], v[152:155], v[194:197], v[110:113]
	v_mfma_f32_16x16x32_bf16 v[94:97], v[130:133], v[202:205], v[94:97]
	v_mfma_f32_16x16x32_bf16 v[102:105], v[152:155], v[202:205], v[102:105]
	v_mfma_f32_16x16x32_bf16 v[90:93], v[130:133], v[212:215], v[90:93]
	v_mfma_f32_16x16x32_bf16 v[126:129], v[152:155], v[212:215], v[126:129]
	v_mfma_f32_16x16x32_bf16 v[106:109], v[134:137], v[190:193], v[106:109]
	v_mfma_f32_16x16x32_bf16 v[114:117], v[156:159], v[190:193], v[114:117]
	v_mfma_f32_16x16x32_bf16 v[98:101], v[134:137], v[198:201], v[98:101]
	v_mfma_f32_16x16x32_bf16 v[110:113], v[156:159], v[198:201], v[110:113]
	v_mfma_f32_16x16x32_bf16 v[94:97], v[134:137], v[208:211], v[94:97]
	v_mfma_f32_16x16x32_bf16 v[102:105], v[156:159], v[208:211], v[102:105]
	v_mfma_f32_16x16x32_bf16 v[90:93], v[134:137], v[222:225], v[90:93]
	v_mfma_f32_16x16x32_bf16 v[126:129], v[156:159], v[222:225], v[126:129]
	s_waitcnt lgkmcnt(0)
	v_mfma_f32_16x16x32_bf16 v[62:65], v[160:163], v[186:189], v[62:65]
	v_mfma_f32_16x16x32_bf16 v[34:37], v[178:181], v[186:189], v[34:37]
	v_mfma_f32_16x16x32_bf16 v[58:61], v[160:163], v[194:197], v[58:61]
	v_mfma_f32_16x16x32_bf16 v[30:33], v[178:181], v[194:197], v[30:33]
	v_mfma_f32_16x16x32_bf16 v[54:57], v[160:163], v[202:205], v[54:57]
	v_mfma_f32_16x16x32_bf16 v[26:29], v[178:181], v[202:205], v[26:29]
	v_mfma_f32_16x16x32_bf16 v[50:53], v[160:163], v[212:215], v[50:53]
	v_mfma_f32_16x16x32_bf16 v[22:25], v[178:181], v[212:215], v[22:25]
	v_mfma_f32_16x16x32_bf16 v[62:65], v[170:173], v[190:193], v[62:65]
	v_mfma_f32_16x16x32_bf16 v[34:37], v[182:185], v[190:193], v[34:37]
	v_mfma_f32_16x16x32_bf16 v[58:61], v[170:173], v[198:201], v[58:61]
	v_mfma_f32_16x16x32_bf16 v[30:33], v[182:185], v[198:201], v[30:33]
	v_mfma_f32_16x16x32_bf16 v[54:57], v[170:173], v[208:211], v[54:57]
	v_mfma_f32_16x16x32_bf16 v[26:29], v[182:185], v[208:211], v[26:29]
	v_mfma_f32_16x16x32_bf16 v[50:53], v[170:173], v[222:225], v[50:53]
	v_mfma_f32_16x16x32_bf16 v[22:25], v[182:185], v[222:225], v[22:25]
	s_setprio 0
	s_barrier
	s_add_i32 s58, s58, s36
	v_lshl_add_u64 v[164:165], s[40:41], 0, v[12:13]
	s_mov_b32 m0, s58
	ds_read_b128 v[186:189], v247 offset:16384
	ds_read_b128 v[190:193], v247 offset:17408
	ds_read_b128 v[194:197], v247 offset:18432
	ds_read_b128 v[198:201], v247 offset:19456
	ds_read_b128 v[202:205], v247 offset:20480
	ds_read_b128 v[208:211], v247 offset:21504
	ds_read_b128 v[212:215], v247 offset:22528
	ds_read_b128 v[222:225], v247 offset:23552
	global_load_lds_dwordx4 v[164:165], off
	s_add_i32 m0, s58, 0x2000
	s_add_u32 s58, s40, 0x40000
	v_lshl_add_u64 v[174:175], s[40:41], 0, v[138:139]
	s_addc_u32 s59, s41, 0
	s_add_i32 s70, s70, s36
	global_load_lds_dwordx4 v[174:175], off
	v_lshl_add_u64 v[176:177], s[58:59], 0, v[12:13]
	s_mov_b32 m0, s70
	v_lshl_add_u64 v[240:241], s[42:43], 0, v[140:141]
	global_load_lds_dwordx4 v[176:177], off
	v_lshl_add_u64 v[176:177], s[58:59], 0, v[138:139]
	s_add_i32 m0, s70, 0x2000
	s_nop 0
	global_load_lds_dwordx4 v[176:177], off
	v_lshl_add_u64 v[176:177], s[42:43], 0, v[142:143]
	s_mov_b32 m0, s37
	s_nop 0
	global_load_lds_dwordx4 v[176:177], off
	s_mov_b32 m0, s44
	s_nop 0
	global_load_lds_dwordx4 v[240:241], off
	s_waitcnt vmcnt(8)
	s_waitcnt lgkmcnt(0)
	s_setprio 1
	s_barrier
	s_waitcnt lgkmcnt(0)
	v_mfma_f32_16x16x32_bf16 v[86:89], v[130:133], v[186:189], v[86:89]
	v_mfma_f32_16x16x32_bf16 v[122:125], v[152:155], v[186:189], v[122:125]
	v_mfma_f32_16x16x32_bf16 v[82:85], v[130:133], v[194:197], v[82:85]
	v_mfma_f32_16x16x32_bf16 v[118:121], v[152:155], v[194:197], v[118:121]
	v_mfma_f32_16x16x32_bf16 v[78:81], v[130:133], v[202:205], v[78:81]
	v_mfma_f32_16x16x32_bf16 v[70:73], v[152:155], v[202:205], v[70:73]
	v_mfma_f32_16x16x32_bf16 v[74:77], v[130:133], v[212:215], v[74:77]
	v_mfma_f32_16x16x32_bf16 v[66:69], v[152:155], v[212:215], v[66:69]
	v_mfma_f32_16x16x32_bf16 v[86:89], v[134:137], v[190:193], v[86:89]
	v_mfma_f32_16x16x32_bf16 v[122:125], v[156:159], v[190:193], v[122:125]
	v_mfma_f32_16x16x32_bf16 v[82:85], v[134:137], v[198:201], v[82:85]
	v_mfma_f32_16x16x32_bf16 v[118:121], v[156:159], v[198:201], v[118:121]
	v_mfma_f32_16x16x32_bf16 v[78:81], v[134:137], v[208:211], v[78:81]
	v_mfma_f32_16x16x32_bf16 v[70:73], v[156:159], v[208:211], v[70:73]
	v_mfma_f32_16x16x32_bf16 v[74:77], v[134:137], v[222:225], v[74:77]
	v_mfma_f32_16x16x32_bf16 v[66:69], v[156:159], v[222:225], v[66:69]
	v_mfma_f32_16x16x32_bf16 v[46:49], v[160:163], v[186:189], v[46:49]
	v_mfma_f32_16x16x32_bf16 v[14:17], v[178:181], v[186:189], v[14:17]
	v_mfma_f32_16x16x32_bf16 v[42:45], v[160:163], v[194:197], v[42:45]
	v_mfma_f32_16x16x32_bf16 v[8:11], v[178:181], v[194:197], v[8:11]
	v_mfma_f32_16x16x32_bf16 v[38:41], v[160:163], v[202:205], v[38:41]
	v_mfma_f32_16x16x32_bf16 v[4:7], v[178:181], v[202:205], v[4:7]
	v_mfma_f32_16x16x32_bf16 v[18:21], v[160:163], v[212:215], v[18:21]
	v_mfma_f32_16x16x32_bf16 v[0:3], v[178:181], v[212:215], v[0:3]
	v_mfma_f32_16x16x32_bf16 v[46:49], v[170:173], v[190:193], v[46:49]
	v_mfma_f32_16x16x32_bf16 v[14:17], v[182:185], v[190:193], v[14:17]
	v_mfma_f32_16x16x32_bf16 v[42:45], v[170:173], v[198:201], v[42:45]
	v_mfma_f32_16x16x32_bf16 v[8:11], v[182:185], v[198:201], v[8:11]
	v_mfma_f32_16x16x32_bf16 v[38:41], v[170:173], v[208:211], v[38:41]
	v_mfma_f32_16x16x32_bf16 v[4:7], v[182:185], v[208:211], v[4:7]
	v_mfma_f32_16x16x32_bf16 v[18:21], v[170:173], v[222:225], v[18:21]
	v_mfma_f32_16x16x32_bf16 v[0:3], v[182:185], v[222:225], v[0:3]
	s_setprio 0
	s_barrier
	s_add_i32 s58, 0, 0x18000
	s_add_i32 s59, 0, 0x1c000
	v_add_u32_e32 v156, s58, v167
	v_add_u32_e32 v182, s59, v167
	ds_read_b128 v[130:133], v156
	ds_read_b128 v[134:137], v156 offset:1024
	ds_read_b128 v[152:155], v156 offset:2048
	ds_read_b128 v[156:159], v156 offset:3072
	ds_read_b128 v[186:189], v247 offset:32768
	ds_read_b128 v[190:193], v247 offset:33792
	ds_read_b128 v[194:197], v247 offset:34816
	ds_read_b128 v[198:201], v247 offset:35840
	ds_read_b128 v[202:205], v247 offset:36864
	ds_read_b128 v[208:211], v247 offset:37888
	ds_read_b128 v[212:215], v247 offset:38912
	ds_read_b128 v[222:225], v247 offset:39936
	ds_read_b128 v[160:163], v182
	ds_read_b128 v[170:173], v182 offset:1024
	ds_read_b128 v[178:181], v182 offset:2048
	ds_read_b128 v[182:185], v182 offset:3072
	s_add_u32 s42, s42, 0x40000
	s_addc_u32 s43, s43, 0
	s_mov_b32 m0, s45
	v_lshl_add_u64 v[250:251], s[42:43], 0, v[142:143]
	global_load_lds_dwordx4 v[250:251], off
	v_lshl_add_u64 v[250:251], s[42:43], 0, v[140:141]
	s_mov_b32 m0, s46
	s_nop 0
	global_load_lds_dwordx4 v[250:251], off
	s_waitcnt vmcnt(8)
	s_cmp_lg_u64 s[22:23], 0
	s_cbranch_scc1 .Lpp_lead_10
	s_waitcnt lgkmcnt(0)
; #define PG8_STAGE(bufoff, gbase, voff) do { _Pragma("unroll") for (int _i = 0; _i < 2; ++_i) \
;         __builtin_amdgcn_global_load_lds((const unsigned*)((const char*)(gbase) + (voff)[_i]), (LAS unsigned*)(lds + (bufoff) + ldsw + _i * 8192), 16, 0, 0); } while (0)
; #define PG8_LDA(dst, b, h) do { _Pragma("unroll") for (int m = 0; m < 4; ++m) _Pragma("unroll") for (int k = 0; k < 2; ++k) dst[m][k] = *(const LAS bf16x8*)(lds + PG8_SA(b, h) + aoff + m * 2048 + k * 1024); } while (0)
; #define PG8_LDB(dst, b, h) do { _Pragma("unroll") for (int n = 0; n < 2; ++n) _Pragma("unroll") for (int k = 0; k < 2; ++k) dst[n][k] = *(const LAS bf16x8*)(lds + PG8_SB(b, h) + boff + n * 2048 + k * 1024); } while (0)
; #define PG8_MMA(ai, bj, At, Bt) do { __builtin_amdgcn_s_setprio(1); _Pragma("unroll") for (int m = 0; m < 4; ++m) _Pragma("unroll") for (int n = 0; n < 2; ++n) _Pragma("unroll") for (int k = 0; k < 2; ++k) \
;         acc[ai][bj][m][n] = __builtin_amdgcn_mfma_f32_16x16x32_bf16(Bt[n][k], At[m][k], acc[ai][bj][m][n], 0, 0, 0); __builtin_amdgcn_s_setprio(0); } while (0)
; #define PG8_WAIT_V(n) asm volatile("s_waitcnt vmcnt(" #n ")" ::: "memory")
; template <class Epi>
; __device__ __forceinline__ void gemm_phase(LAS unsigned char* lds, const Gemm g, const StaticOrder& S, const Epi& E, int wave_s) {
;     ...
;             PG8_LDB(B0, 0, 0); PG8_LDB(B1, 0, 1); PG8_SCHED; PG8_LDA(At, 0, 0); PG8_STAGE(PG8_SA(1, 1), a1 + hstepA, voffA);
;             PG8_WAIT_V(8); PG8_WAIT_L(0); PG8_BAR; PG8_MMA(0, 0, At, B0); PG8_MMA(0, 1, At, B1); PG8_BAR; PG8_SCHED;
;             PG8_LDA(At, 0, 1); PG8_STAGE(PG8_SB(0, 0), b2, voffB); PG8_STAGE(PG8_SB(0, 1), b2 + hstepB, voffB); PG8_STAGE(PG8_SA(0, 0), a2, voffA);
;             PG8_WAIT_V(8); PG8_WAIT_L(0); PG8_BAR; PG8_MMA(1, 0, At, B0); PG8_MMA(1, 1, At, B1); PG8_BAR; PG8_SCHED;
;             PG8_LDB(B0, 1, 0); PG8_LDB(B1, 1, 1); PG8_SCHED; PG8_LDA(At, 1, 0); PG8_STAGE(PG8_SA(0, 1), a2 + hstepA, voffA);
;             PG8_WAIT_V(8); PG8_WAIT_L(0); PG8_BAR; PG8_MMA(0, 0, At, B0); PG8_MMA(0, 1, At, B1); PG8_BAR; PG8_SCHED;
;             PG8_LDA(At, 1, 1); PG8_STAGE(PG8_SB(1, 0), b3, voffB); PG8_STAGE(PG8_SB(1, 1), b3 + hstepB, voffB); PG8_STAGE(PG8_SA(1, 0), a3, voffA);
;             PG8_WAIT_V(8); PG8_WAIT_L(0); PG8_BAR; PG8_MMA(1, 0, At, B0); PG8_MMA(1, 1, At, B1); PG8_BAR; PG8_SCHED;
;         }
.Lpp_lead_10:
	s_waitcnt lgkmcnt(4)
	s_setprio 1
	s_barrier
	s_waitcnt lgkmcnt(4)
	v_mfma_f32_16x16x32_bf16 v[106:109], v[130:133], v[186:189], v[106:109]
	v_mfma_f32_16x16x32_bf16 v[114:117], v[152:155], v[186:189], v[114:117]
	v_mfma_f32_16x16x32_bf16 v[98:101], v[130:133], v[194:197], v[98:101]
	v_mfma_f32_16x16x32_bf16 v[110:113], v[152:155], v[194:197], v[110:113]
	v_mfma_f32_16x16x32_bf16 v[94:97], v[130:133], v[202:205], v[94:97]
	v_mfma_f32_16x16x32_bf16 v[102:105], v[152:155], v[202:205], v[102:105]
	v_mfma_f32_16x16x32_bf16 v[90:93], v[130:133], v[212:215], v[90:93]
	v_mfma_f32_16x16x32_bf16 v[126:129], v[152:155], v[212:215], v[126:129]
	v_mfma_f32_16x16x32_bf16 v[106:109], v[134:137], v[190:193], v[106:109]
	v_mfma_f32_16x16x32_bf16 v[114:117], v[156:159], v[190:193], v[114:117]
	v_mfma_f32_16x16x32_bf16 v[98:101], v[134:137], v[198:201], v[98:101]
	v_mfma_f32_16x16x32_bf16 v[110:113], v[156:159], v[198:201], v[110:113]
	v_mfma_f32_16x16x32_bf16 v[94:97], v[134:137], v[208:211], v[94:97]
	v_mfma_f32_16x16x32_bf16 v[102:105], v[156:159], v[208:211], v[102:105]
	v_mfma_f32_16x16x32_bf16 v[90:93], v[134:137], v[222:225], v[90:93]
	v_mfma_f32_16x16x32_bf16 v[126:129], v[156:159], v[222:225], v[126:129]
	s_waitcnt lgkmcnt(0)
	v_mfma_f32_16x16x32_bf16 v[62:65], v[160:163], v[186:189], v[62:65]
	v_mfma_f32_16x16x32_bf16 v[34:37], v[178:181], v[186:189], v[34:37]
	v_mfma_f32_16x16x32_bf16 v[58:61], v[160:163], v[194:197], v[58:61]
	v_mfma_f32_16x16x32_bf16 v[30:33], v[178:181], v[194:197], v[30:33]
	v_mfma_f32_16x16x32_bf16 v[54:57], v[160:163], v[202:205], v[54:57]
	v_mfma_f32_16x16x32_bf16 v[26:29], v[178:181], v[202:205], v[26:29]
	v_mfma_f32_16x16x32_bf16 v[50:53], v[160:163], v[212:215], v[50:53]
	v_mfma_f32_16x16x32_bf16 v[22:25], v[178:181], v[212:215], v[22:25]
	v_mfma_f32_16x16x32_bf16 v[62:65], v[170:173], v[190:193], v[62:65]
	v_mfma_f32_16x16x32_bf16 v[34:37], v[182:185], v[190:193], v[34:37]
	v_mfma_f32_16x16x32_bf16 v[58:61], v[170:173], v[198:201], v[58:61]
	v_mfma_f32_16x16x32_bf16 v[30:33], v[182:185], v[198:201], v[30:33]
	v_mfma_f32_16x16x32_bf16 v[54:57], v[170:173], v[208:211], v[54:57]
	v_mfma_f32_16x16x32_bf16 v[26:29], v[182:185], v[208:211], v[26:29]
	v_mfma_f32_16x16x32_bf16 v[50:53], v[170:173], v[222:225], v[50:53]
	v_mfma_f32_16x16x32_bf16 v[22:25], v[182:185], v[222:225], v[22:25]
	s_setprio 0
	s_barrier
	s_add_i32 s42, s58, s36
	v_lshl_add_u64 v[164:165], v[164:165], 0, s[84:85]
	s_mov_b32 m0, s42
	ds_read_b128 v[186:189], v247 offset:49152
	ds_read_b128 v[190:193], v247 offset:50176
	ds_read_b128 v[194:197], v247 offset:51200
	ds_read_b128 v[198:201], v247 offset:52224
	ds_read_b128 v[202:205], v247 offset:53248
	ds_read_b128 v[208:211], v247 offset:54272
	ds_read_b128 v[212:215], v247 offset:55296
	ds_read_b128 v[222:225], v247 offset:56320
	global_load_lds_dwordx4 v[164:165], off
	s_add_i32 m0, s42, 0x2000
	s_add_u32 s40, s40, 0x40080
	v_lshl_add_u64 v[164:165], v[174:175], 0, s[84:85]
	s_addc_u32 s41, s41, 0
	s_add_i32 s42, s59, s36
	global_load_lds_dwordx4 v[164:165], off
	v_lshl_add_u64 v[164:165], s[40:41], 0, v[12:13]
	s_mov_b32 m0, s42
	s_nop 0
	global_load_lds_dwordx4 v[164:165], off
	v_lshl_add_u64 v[164:165], s[40:41], 0, v[138:139]
	s_add_i32 m0, s42, 0x2000
	s_nop 0
	global_load_lds_dwordx4 v[164:165], off
	v_lshl_add_u64 v[164:165], v[176:177], 0, s[84:85]
	s_mov_b32 m0, s50
	s_nop 0
	global_load_lds_dwordx4 v[164:165], off
	v_lshl_add_u64 v[164:165], v[240:241], 0, s[84:85]
	s_mov_b32 m0, s51
	s_nop 0
	global_load_lds_dwordx4 v[164:165], off
	s_waitcnt vmcnt(8)
	s_waitcnt lgkmcnt(0)
	s_setprio 1
	s_barrier
	s_waitcnt lgkmcnt(0)
	v_mfma_f32_16x16x32_bf16 v[86:89], v[130:133], v[186:189], v[86:89]
	v_mfma_f32_16x16x32_bf16 v[122:125], v[152:155], v[186:189], v[122:125]
	v_mfma_f32_16x16x32_bf16 v[82:85], v[130:133], v[194:197], v[82:85]
	v_mfma_f32_16x16x32_bf16 v[118:121], v[152:155], v[194:197], v[118:121]
	v_mfma_f32_16x16x32_bf16 v[78:81], v[130:133], v[202:205], v[78:81]
	v_mfma_f32_16x16x32_bf16 v[70:73], v[152:155], v[202:205], v[70:73]
	v_mfma_f32_16x16x32_bf16 v[74:77], v[130:133], v[212:215], v[74:77]
	v_mfma_f32_16x16x32_bf16 v[66:69], v[152:155], v[212:215], v[66:69]
	v_mfma_f32_16x16x32_bf16 v[86:89], v[134:137], v[190:193], v[86:89]
	v_mfma_f32_16x16x32_bf16 v[122:125], v[156:159], v[190:193], v[122:125]
	v_mfma_f32_16x16x32_bf16 v[82:85], v[134:137], v[198:201], v[82:85]
	v_mfma_f32_16x16x32_bf16 v[118:121], v[156:159], v[198:201], v[118:121]
	v_mfma_f32_16x16x32_bf16 v[78:81], v[134:137], v[208:211], v[78:81]
	v_mfma_f32_16x16x32_bf16 v[70:73], v[156:159], v[208:211], v[70:73]
	v_mfma_f32_16x16x32_bf16 v[74:77], v[134:137], v[222:225], v[74:77]
	v_mfma_f32_16x16x32_bf16 v[66:69], v[156:159], v[222:225], v[66:69]
	v_mfma_f32_16x16x32_bf16 v[46:49], v[160:163], v[186:189], v[46:49]
	v_mfma_f32_16x16x32_bf16 v[14:17], v[178:181], v[186:189], v[14:17]
	v_mfma_f32_16x16x32_bf16 v[42:45], v[160:163], v[194:197], v[42:45]
	v_mfma_f32_16x16x32_bf16 v[8:11], v[178:181], v[194:197], v[8:11]
	v_mfma_f32_16x16x32_bf16 v[38:41], v[160:163], v[202:205], v[38:41]
	v_mfma_f32_16x16x32_bf16 v[4:7], v[178:181], v[202:205], v[4:7]
	v_mfma_f32_16x16x32_bf16 v[18:21], v[160:163], v[212:215], v[18:21]
	v_mfma_f32_16x16x32_bf16 v[0:3], v[178:181], v[212:215], v[0:3]
	v_mfma_f32_16x16x32_bf16 v[46:49], v[170:173], v[190:193], v[46:49]
	v_mfma_f32_16x16x32_bf16 v[14:17], v[182:185], v[190:193], v[14:17]
	v_mfma_f32_16x16x32_bf16 v[42:45], v[170:173], v[198:201], v[42:45]
	v_mfma_f32_16x16x32_bf16 v[8:11], v[182:185], v[198:201], v[8:11]
	v_mfma_f32_16x16x32_bf16 v[38:41], v[170:173], v[208:211], v[38:41]
	v_mfma_f32_16x16x32_bf16 v[4:7], v[182:185], v[208:211], v[4:7]
	v_mfma_f32_16x16x32_bf16 v[18:21], v[170:173], v[222:225], v[18:21]
	v_mfma_f32_16x16x32_bf16 v[0:3], v[182:185], v[222:225], v[0:3]
	s_setprio 0
	s_barrier
	s_add_i32 s83, s83, 2
	s_add_u32 s8, s8, 0x100
	s_addc_u32 s9, s9, 0
	s_add_u32 s68, s68, 0x100
	s_addc_u32 s69, s69, 0
	s_cmp_gt_u32 s83, 13
	s_cbranch_scc0 .LBB0_916
	s_and_b64 vcc, exec, s[22:23]
	s_cbranch_vccz .LBB0_919
	s_barrier

; #define PG8_STAGE(bufoff, gbase, voff) do { _Pragma("unroll") for (int _i = 0; _i < 2; ++_i) \
;         __builtin_amdgcn_global_load_lds((const unsigned*)((const char*)(gbase) + (voff)[_i]), (LAS unsigned*)(lds + (bufoff) + ldsw + _i * 8192), 16, 0, 0); } while (0)
; #define PG8_LDA(dst, b, h) do { _Pragma("unroll") for (int m = 0; m < 4; ++m) _Pragma("unroll") for (int k = 0; k < 2; ++k) dst[m][k] = *(const LAS bf16x8*)(lds + PG8_SA(b, h) + aoff + m * 2048 + k * 1024); } while (0)
; #define PG8_LDB(dst, b, h) do { _Pragma("unroll") for (int n = 0; n < 2; ++n) _Pragma("unroll") for (int k = 0; k < 2; ++k) dst[n][k] = *(const LAS bf16x8*)(lds + PG8_SB(b, h) + boff + n * 2048 + k * 1024); } while (0)
; #define PG8_MMA(ai, bj, At, Bt) do { __builtin_amdgcn_s_setprio(1); _Pragma("unroll") for (int m = 0; m < 4; ++m) _Pragma("unroll") for (int n = 0; n < 2; ++n) _Pragma("unroll") for (int k = 0; k < 2; ++k) \
;         acc[ai][bj][m][n] = __builtin_amdgcn_mfma_f32_16x16x32_bf16(Bt[n][k], At[m][k], acc[ai][bj][m][n], 0, 0, 0); __builtin_amdgcn_s_setprio(0); } while (0)
; #define PG8_WAIT_V(n) asm volatile("s_waitcnt vmcnt(" #n ")" ::: "memory")
; #define PG8_BAR __builtin_amdgcn_s_barrier()
; template <class Epi>
; __device__ __forceinline__ void gemm_phase(LAS unsigned char* lds, const Gemm g, const StaticOrder& S, const Epi& E, int wave_s) {
;     ...
;             PG8_LDB(B0, 0, 0); PG8_LDB(B1, 0, 1); PG8_SCHED; PG8_LDA(At, 0, 0); PG8_STAGE(PG8_SA(1, 1), a1 + hstepA, voffA);
;             PG8_WAIT_V(8); PG8_WAIT_L(0); PG8_BAR; PG8_MMA(0, 0, At, B0); PG8_MMA(0, 1, At, B1); PG8_BAR; PG8_SCHED;
;             PG8_LDA(At, 0, 1); PG8_STAGE(PG8_SB(0, 0), b2, voffB); PG8_STAGE(PG8_SB(0, 1), b2 + hstepB, voffB); PG8_STAGE(PG8_SA(0, 0), a2, voffA);
;             PG8_WAIT_V(8); PG8_WAIT_L(0); PG8_BAR; PG8_MMA(1, 0, At, B0); PG8_MMA(1, 1, At, B1); PG8_BAR; PG8_SCHED;
;             PG8_LDB(B0, 1, 0); PG8_LDB(B1, 1, 1); PG8_SCHED; PG8_LDA(At, 1, 0); PG8_STAGE(PG8_SA(0, 1), a2 + hstepA, voffA);
;             PG8_WAIT_V(8); PG8_WAIT_L(0); PG8_BAR; PG8_MMA(0, 0, At, B0); PG8_MMA(0, 1, At, B1); PG8_BAR; PG8_SCHED;
;             PG8_LDA(At, 1, 1); PG8_STAGE(PG8_SB(1, 0), b3, voffB); PG8_STAGE(PG8_SB(1, 1), b3 + hstepB, voffB); PG8_STAGE(PG8_SA(1, 0), a3, voffA);
;             PG8_WAIT_V(8); PG8_WAIT_L(0); PG8_BAR; PG8_MMA(1, 0, At, B0); PG8_MMA(1, 1, At, B1); PG8_BAR; PG8_SCHED;
.Lpp_lead_11:
	s_waitcnt lgkmcnt(4)
	s_setprio 1
	s_barrier
	s_waitcnt lgkmcnt(4)
	v_mfma_f32_16x16x32_bf16 v[126:129], v[146:149], v[182:185], v[126:129]
	v_mfma_f32_16x16x32_bf16 v[122:125], v[154:157], v[182:185], v[122:125]
	v_mfma_f32_16x16x32_bf16 v[118:121], v[146:149], v[190:193], v[118:121]
	v_mfma_f32_16x16x32_bf16 v[114:117], v[154:157], v[190:193], v[114:117]
	v_mfma_f32_16x16x32_bf16 v[102:105], v[146:149], v[198:201], v[102:105]
	v_mfma_f32_16x16x32_bf16 v[98:101], v[154:157], v[198:201], v[98:101]
	v_mfma_f32_16x16x32_bf16 v[86:89], v[146:149], v[206:209], v[86:89]
	v_mfma_f32_16x16x32_bf16 v[82:85], v[154:157], v[206:209], v[82:85]
	v_mfma_f32_16x16x32_bf16 v[126:129], v[150:153], v[186:189], v[126:129]
	v_mfma_f32_16x16x32_bf16 v[122:125], v[158:161], v[186:189], v[122:125]
	v_mfma_f32_16x16x32_bf16 v[118:121], v[150:153], v[194:197], v[118:121]
	v_mfma_f32_16x16x32_bf16 v[114:117], v[158:161], v[194:197], v[114:117]
	v_mfma_f32_16x16x32_bf16 v[102:105], v[150:153], v[202:205], v[102:105]
	v_mfma_f32_16x16x32_bf16 v[98:101], v[158:161], v[202:205], v[98:101]
	v_mfma_f32_16x16x32_bf16 v[86:89], v[150:153], v[210:213], v[86:89]
	v_mfma_f32_16x16x32_bf16 v[82:85], v[158:161], v[210:213], v[82:85]
	s_waitcnt lgkmcnt(0)
	v_mfma_f32_16x16x32_bf16 v[110:113], v[162:165], v[182:185], v[110:113]
	v_mfma_f32_16x16x32_bf16 v[106:109], v[170:173], v[182:185], v[106:109]
	v_mfma_f32_16x16x32_bf16 v[94:97], v[162:165], v[190:193], v[94:97]
	v_mfma_f32_16x16x32_bf16 v[90:93], v[170:173], v[190:193], v[90:93]
	v_mfma_f32_16x16x32_bf16 v[78:81], v[162:165], v[198:201], v[78:81]
	v_mfma_f32_16x16x32_bf16 v[74:77], v[170:173], v[198:201], v[74:77]
	v_mfma_f32_16x16x32_bf16 v[70:73], v[162:165], v[206:209], v[70:73]
	v_mfma_f32_16x16x32_bf16 v[66:69], v[170:173], v[206:209], v[66:69]
	v_mfma_f32_16x16x32_bf16 v[110:113], v[166:169], v[186:189], v[110:113]
	v_mfma_f32_16x16x32_bf16 v[106:109], v[178:181], v[186:189], v[106:109]
	v_mfma_f32_16x16x32_bf16 v[94:97], v[166:169], v[194:197], v[94:97]
	v_mfma_f32_16x16x32_bf16 v[90:93], v[178:181], v[194:197], v[90:93]
	v_mfma_f32_16x16x32_bf16 v[78:81], v[166:169], v[202:205], v[78:81]
	v_mfma_f32_16x16x32_bf16 v[74:77], v[178:181], v[202:205], v[74:77]
	v_mfma_f32_16x16x32_bf16 v[70:73], v[166:169], v[210:213], v[70:73]
	v_mfma_f32_16x16x32_bf16 v[66:69], v[178:181], v[210:213], v[66:69]
	s_setprio 0
	s_barrier
	s_add_i32 s53, s53, s36
	v_lshl_add_u64 v[174:175], s[26:27], 0, v[134:135]
	s_mov_b32 m0, s53
	ds_read_b128 v[182:185], v144 offset:16384
	ds_read_b128 v[186:189], v144 offset:17408
	ds_read_b128 v[190:193], v144 offset:18432
	ds_read_b128 v[194:197], v144 offset:19456
	ds_read_b128 v[198:201], v144 offset:20480
	ds_read_b128 v[202:205], v144 offset:21504
	ds_read_b128 v[206:209], v144 offset:22528
	ds_read_b128 v[210:213], v144 offset:23552
	global_load_lds_dwordx4 v[174:175], off
	s_add_i32 m0, s53, 0x2000
	s_add_u32 s58, s26, 0x40000
	v_lshl_add_u64 v[176:177], s[26:27], 0, v[130:131]
	s_addc_u32 s59, s27, 0
	s_add_i32 s53, s54, s36
	global_load_lds_dwordx4 v[176:177], off
	v_lshl_add_u64 v[214:215], s[58:59], 0, v[134:135]
	s_mov_b32 m0, s53
	v_lshl_add_u64 v[216:217], s[30:31], 0, v[132:133]
	global_load_lds_dwordx4 v[214:215], off
	v_lshl_add_u64 v[214:215], s[58:59], 0, v[130:131]
	s_add_i32 m0, s53, 0x2000
	s_nop 0
	global_load_lds_dwordx4 v[214:215], off
	v_lshl_add_u64 v[214:215], s[30:31], 0, v[136:137]
	s_mov_b32 m0, s37
	s_nop 0
	global_load_lds_dwordx4 v[214:215], off
	s_mov_b32 m0, s40
	s_nop 0
	global_load_lds_dwordx4 v[216:217], off
	s_waitcnt vmcnt(8)
	s_waitcnt lgkmcnt(0)
	s_setprio 1
	s_barrier
	s_waitcnt lgkmcnt(0)
	v_mfma_f32_16x16x32_bf16 v[62:65], v[146:149], v[182:185], v[62:65]
	v_mfma_f32_16x16x32_bf16 v[58:61], v[154:157], v[182:185], v[58:61]
	v_mfma_f32_16x16x32_bf16 v[54:57], v[146:149], v[190:193], v[54:57]
	v_mfma_f32_16x16x32_bf16 v[50:53], v[154:157], v[190:193], v[50:53]
	v_mfma_f32_16x16x32_bf16 v[38:41], v[146:149], v[198:201], v[38:41]
	v_mfma_f32_16x16x32_bf16 v[34:37], v[154:157], v[198:201], v[34:37]
	v_mfma_f32_16x16x32_bf16 v[22:25], v[146:149], v[206:209], v[22:25]
	v_mfma_f32_16x16x32_bf16 v[18:21], v[154:157], v[206:209], v[18:21]
	v_mfma_f32_16x16x32_bf16 v[62:65], v[150:153], v[186:189], v[62:65]
	v_mfma_f32_16x16x32_bf16 v[58:61], v[158:161], v[186:189], v[58:61]
	v_mfma_f32_16x16x32_bf16 v[54:57], v[150:153], v[194:197], v[54:57]
	v_mfma_f32_16x16x32_bf16 v[50:53], v[158:161], v[194:197], v[50:53]
	v_mfma_f32_16x16x32_bf16 v[38:41], v[150:153], v[202:205], v[38:41]
	v_mfma_f32_16x16x32_bf16 v[34:37], v[158:161], v[202:205], v[34:37]
	v_mfma_f32_16x16x32_bf16 v[22:25], v[150:153], v[210:213], v[22:25]
	v_mfma_f32_16x16x32_bf16 v[18:21], v[158:161], v[210:213], v[18:21]
	v_mfma_f32_16x16x32_bf16 v[46:49], v[162:165], v[182:185], v[46:49]
	v_mfma_f32_16x16x32_bf16 v[42:45], v[170:173], v[182:185], v[42:45]
	v_mfma_f32_16x16x32_bf16 v[30:33], v[162:165], v[190:193], v[30:33]
	v_mfma_f32_16x16x32_bf16 v[26:29], v[170:173], v[190:193], v[26:29]
	v_mfma_f32_16x16x32_bf16 v[14:17], v[162:165], v[198:201], v[14:17]
	v_mfma_f32_16x16x32_bf16 v[8:11], v[170:173], v[198:201], v[8:11]
	v_mfma_f32_16x16x32_bf16 v[4:7], v[162:165], v[206:209], v[4:7]
	v_mfma_f32_16x16x32_bf16 v[0:3], v[170:173], v[206:209], v[0:3]
	v_mfma_f32_16x16x32_bf16 v[46:49], v[166:169], v[186:189], v[46:49]
	v_mfma_f32_16x16x32_bf16 v[42:45], v[178:181], v[186:189], v[42:45]
	v_mfma_f32_16x16x32_bf16 v[30:33], v[166:169], v[194:197], v[30:33]
	v_mfma_f32_16x16x32_bf16 v[26:29], v[178:181], v[194:197], v[26:29]
	v_mfma_f32_16x16x32_bf16 v[14:17], v[166:169], v[202:205], v[14:17]
	v_mfma_f32_16x16x32_bf16 v[8:11], v[178:181], v[202:205], v[8:11]
	v_mfma_f32_16x16x32_bf16 v[4:7], v[166:169], v[210:213], v[4:7]
	v_mfma_f32_16x16x32_bf16 v[0:3], v[178:181], v[210:213], v[0:3]
	s_setprio 0
	s_barrier
	s_add_i32 s53, 0, 0x18000
	v_add_u32_e32 v145, s53, v143
	s_add_i32 s54, 0, 0x1c000
	ds_read_b128 v[146:149], v145
	ds_read_b128 v[150:153], v145 offset:1024
	ds_read_b128 v[154:157], v145 offset:2048
	ds_read_b128 v[158:161], v145 offset:3072
	v_add_u32_e32 v145, s54, v143
	ds_read_b128 v[182:185], v144 offset:32768
	ds_read_b128 v[186:189], v144 offset:33792
	ds_read_b128 v[190:193], v144 offset:34816
	ds_read_b128 v[194:197], v144 offset:35840
	ds_read_b128 v[198:201], v144 offset:36864
	ds_read_b128 v[202:205], v144 offset:37888
	ds_read_b128 v[206:209], v144 offset:38912
	ds_read_b128 v[210:213], v144 offset:39936
	ds_read_b128 v[162:165], v145
	ds_read_b128 v[166:169], v145 offset:1024
	ds_read_b128 v[170:173], v145 offset:2048
	ds_read_b128 v[178:181], v145 offset:3072
	s_add_u32 s30, s30, 0x40000
	s_addc_u32 s31, s31, 0
	s_mov_b32 m0, s41
	v_lshl_add_u64 v[218:219], s[30:31], 0, v[136:137]
	global_load_lds_dwordx4 v[218:219], off
	v_lshl_add_u64 v[218:219], s[30:31], 0, v[132:133]
	s_mov_b32 m0, s42
	s_nop 0
	global_load_lds_dwordx4 v[218:219], off
	s_waitcnt vmcnt(8)
	s_cmp_lg_u64 s[6:7], 0
	s_cbranch_scc1 .Lpp_lead_12
	s_waitcnt lgkmcnt(0)
; #define PG8_STAGE(bufoff, gbase, voff) do { _Pragma("unroll") for (int _i = 0; _i < 2; ++_i) \
;         __builtin_amdgcn_global_load_lds((const unsigned*)((const char*)(gbase) + (voff)[_i]), (LAS unsigned*)(lds + (bufoff) + ldsw + _i * 8192), 16, 0, 0); } while (0)
; #define PG8_LDA(dst, b, h) do { _Pragma("unroll") for (int m = 0; m < 4; ++m) _Pragma("unroll") for (int k = 0; k < 2; ++k) dst[m][k] = *(const LAS bf16x8*)(lds + PG8_SA(b, h) + aoff + m * 2048 + k * 1024); } while (0)
; #define PG8_LDB(dst, b, h) do { _Pragma("unroll") for (int n = 0; n < 2; ++n) _Pragma("unroll") for (int k = 0; k < 2; ++k) dst[n][k] = *(const LAS bf16x8*)(lds + PG8_SB(b, h) + boff + n * 2048 + k * 1024); } while (0)
; #define PG8_MMA(ai, bj, At, Bt) do { __builtin_amdgcn_s_setprio(1); _Pragma("unroll") for (int m = 0; m < 4; ++m) _Pragma("unroll") for (int n = 0; n < 2; ++n) _Pragma("unroll") for (int k = 0; k < 2; ++k) \
;         acc[ai][bj][m][n] = __builtin_amdgcn_mfma_f32_16x16x32_bf16(Bt[n][k], At[m][k], acc[ai][bj][m][n], 0, 0, 0); __builtin_amdgcn_s_setprio(0); } while (0)
; #define PG8_WAIT_V(n) asm volatile("s_waitcnt vmcnt(" #n ")" ::: "memory")
; template <class Epi>
; __device__ __forceinline__ void gemm_phase(LAS unsigned char* lds, const Gemm g, const StaticOrder& S, const Epi& E, int wave_s) {
;     ...
;             PG8_LDB(B0, 0, 0); PG8_LDB(B1, 0, 1); PG8_SCHED; PG8_LDA(At, 0, 0); PG8_STAGE(PG8_SA(1, 1), a1 + hstepA, voffA);
;             PG8_WAIT_V(8); PG8_WAIT_L(0); PG8_BAR; PG8_MMA(0, 0, At, B0); PG8_MMA(0, 1, At, B1); PG8_BAR; PG8_SCHED;
;             PG8_LDA(At, 0, 1); PG8_STAGE(PG8_SB(0, 0), b2, voffB); PG8_STAGE(PG8_SB(0, 1), b2 + hstepB, voffB); PG8_STAGE(PG8_SA(0, 0), a2, voffA);
;             PG8_WAIT_V(8); PG8_WAIT_L(0); PG8_BAR; PG8_MMA(1, 0, At, B0); PG8_MMA(1, 1, At, B1); PG8_BAR; PG8_SCHED;
;             PG8_LDB(B0, 1, 0); PG8_LDB(B1, 1, 1); PG8_SCHED; PG8_LDA(At, 1, 0); PG8_STAGE(PG8_SA(0, 1), a2 + hstepA, voffA);
;             PG8_WAIT_V(8); PG8_WAIT_L(0); PG8_BAR; PG8_MMA(0, 0, At, B0); PG8_MMA(0, 1, At, B1); PG8_BAR; PG8_SCHED;
;             PG8_LDA(At, 1, 1); PG8_STAGE(PG8_SB(1, 0), b3, voffB); PG8_STAGE(PG8_SB(1, 1), b3 + hstepB, voffB); PG8_STAGE(PG8_SA(1, 0), a3, voffA);
;             PG8_WAIT_V(8); PG8_WAIT_L(0); PG8_BAR; PG8_MMA(1, 0, At, B0); PG8_MMA(1, 1, At, B1); PG8_BAR; PG8_SCHED;
;         }
.Lpp_lead_12:
	s_waitcnt lgkmcnt(4)
	s_setprio 1
	s_barrier
	s_waitcnt lgkmcnt(4)
	v_mfma_f32_16x16x32_bf16 v[126:129], v[146:149], v[182:185], v[126:129]
	v_mfma_f32_16x16x32_bf16 v[122:125], v[154:157], v[182:185], v[122:125]
	v_mfma_f32_16x16x32_bf16 v[118:121], v[146:149], v[190:193], v[118:121]
	v_mfma_f32_16x16x32_bf16 v[114:117], v[154:157], v[190:193], v[114:117]
	v_mfma_f32_16x16x32_bf16 v[102:105], v[146:149], v[198:201], v[102:105]
	v_mfma_f32_16x16x32_bf16 v[98:101], v[154:157], v[198:201], v[98:101]
	v_mfma_f32_16x16x32_bf16 v[86:89], v[146:149], v[206:209], v[86:89]
	v_mfma_f32_16x16x32_bf16 v[82:85], v[154:157], v[206:209], v[82:85]
	v_mfma_f32_16x16x32_bf16 v[126:129], v[150:153], v[186:189], v[126:129]
	v_mfma_f32_16x16x32_bf16 v[122:125], v[158:161], v[186:189], v[122:125]
	v_mfma_f32_16x16x32_bf16 v[118:121], v[150:153], v[194:197], v[118:121]
	v_mfma_f32_16x16x32_bf16 v[114:117], v[158:161], v[194:197], v[114:117]
	v_mfma_f32_16x16x32_bf16 v[102:105], v[150:153], v[202:205], v[102:105]
	v_mfma_f32_16x16x32_bf16 v[98:101], v[158:161], v[202:205], v[98:101]
	v_mfma_f32_16x16x32_bf16 v[86:89], v[150:153], v[210:213], v[86:89]
	v_mfma_f32_16x16x32_bf16 v[82:85], v[158:161], v[210:213], v[82:85]
	s_waitcnt lgkmcnt(0)
	v_mfma_f32_16x16x32_bf16 v[110:113], v[162:165], v[182:185], v[110:113]
	v_mfma_f32_16x16x32_bf16 v[106:109], v[170:173], v[182:185], v[106:109]
	v_mfma_f32_16x16x32_bf16 v[94:97], v[162:165], v[190:193], v[94:97]
	v_mfma_f32_16x16x32_bf16 v[90:93], v[170:173], v[190:193], v[90:93]
	v_mfma_f32_16x16x32_bf16 v[78:81], v[162:165], v[198:201], v[78:81]
	v_mfma_f32_16x16x32_bf16 v[74:77], v[170:173], v[198:201], v[74:77]
	v_mfma_f32_16x16x32_bf16 v[70:73], v[162:165], v[206:209], v[70:73]
	v_mfma_f32_16x16x32_bf16 v[66:69], v[170:173], v[206:209], v[66:69]
	v_mfma_f32_16x16x32_bf16 v[110:113], v[166:169], v[186:189], v[110:113]
	v_mfma_f32_16x16x32_bf16 v[106:109], v[178:181], v[186:189], v[106:109]
	v_mfma_f32_16x16x32_bf16 v[94:97], v[166:169], v[194:197], v[94:97]
	v_mfma_f32_16x16x32_bf16 v[90:93], v[178:181], v[194:197], v[90:93]
	v_mfma_f32_16x16x32_bf16 v[78:81], v[166:169], v[202:205], v[78:81]
	v_mfma_f32_16x16x32_bf16 v[74:77], v[178:181], v[202:205], v[74:77]
	v_mfma_f32_16x16x32_bf16 v[70:73], v[166:169], v[210:213], v[70:73]
	v_mfma_f32_16x16x32_bf16 v[66:69], v[178:181], v[210:213], v[66:69]
	s_setprio 0
	s_barrier
	s_add_i32 s30, s53, s36
	v_lshl_add_u64 v[174:175], v[174:175], 0, s[84:85]
	s_mov_b32 m0, s30
	ds_read_b128 v[182:185], v144 offset:49152
	ds_read_b128 v[186:189], v144 offset:50176
	ds_read_b128 v[190:193], v144 offset:51200
	ds_read_b128 v[194:197], v144 offset:52224
	ds_read_b128 v[198:201], v144 offset:53248
	ds_read_b128 v[202:205], v144 offset:54272
	ds_read_b128 v[206:209], v144 offset:55296
	ds_read_b128 v[210:213], v144 offset:56320
	global_load_lds_dwordx4 v[174:175], off
	s_add_i32 m0, s30, 0x2000
	s_add_u32 s26, s26, 0x40080
	v_lshl_add_u64 v[174:175], v[176:177], 0, s[84:85]
	s_addc_u32 s27, s27, 0
	s_add_i32 s30, s54, s36
	global_load_lds_dwordx4 v[174:175], off
	v_lshl_add_u64 v[174:175], s[26:27], 0, v[134:135]
	s_mov_b32 m0, s30
	s_nop 0
	global_load_lds_dwordx4 v[174:175], off
	v_lshl_add_u64 v[174:175], s[26:27], 0, v[130:131]
	s_add_i32 m0, s30, 0x2000
	s_nop 0
	global_load_lds_dwordx4 v[174:175], off
	v_lshl_add_u64 v[174:175], v[214:215], 0, s[84:85]
	s_mov_b32 m0, s43
	s_nop 0
	global_load_lds_dwordx4 v[174:175], off
	v_lshl_add_u64 v[174:175], v[216:217], 0, s[84:85]
	s_mov_b32 m0, s44
	s_nop 0
	global_load_lds_dwordx4 v[174:175], off
	s_waitcnt vmcnt(8)
	s_waitcnt lgkmcnt(0)
	s_setprio 1
	s_barrier
	s_waitcnt lgkmcnt(0)
	v_mfma_f32_16x16x32_bf16 v[62:65], v[146:149], v[182:185], v[62:65]
	v_mfma_f32_16x16x32_bf16 v[58:61], v[154:157], v[182:185], v[58:61]
	v_mfma_f32_16x16x32_bf16 v[54:57], v[146:149], v[190:193], v[54:57]
	v_mfma_f32_16x16x32_bf16 v[50:53], v[154:157], v[190:193], v[50:53]
	v_mfma_f32_16x16x32_bf16 v[38:41], v[146:149], v[198:201], v[38:41]
	v_mfma_f32_16x16x32_bf16 v[34:37], v[154:157], v[198:201], v[34:37]
	v_mfma_f32_16x16x32_bf16 v[22:25], v[146:149], v[206:209], v[22:25]
	v_mfma_f32_16x16x32_bf16 v[18:21], v[154:157], v[206:209], v[18:21]
	v_mfma_f32_16x16x32_bf16 v[62:65], v[150:153], v[186:189], v[62:65]
	v_mfma_f32_16x16x32_bf16 v[58:61], v[158:161], v[186:189], v[58:61]
	v_mfma_f32_16x16x32_bf16 v[54:57], v[150:153], v[194:197], v[54:57]
	v_mfma_f32_16x16x32_bf16 v[50:53], v[158:161], v[194:197], v[50:53]
	v_mfma_f32_16x16x32_bf16 v[38:41], v[150:153], v[202:205], v[38:41]
	v_mfma_f32_16x16x32_bf16 v[34:37], v[158:161], v[202:205], v[34:37]
	v_mfma_f32_16x16x32_bf16 v[22:25], v[150:153], v[210:213], v[22:25]
	v_mfma_f32_16x16x32_bf16 v[18:21], v[158:161], v[210:213], v[18:21]
	v_mfma_f32_16x16x32_bf16 v[46:49], v[162:165], v[182:185], v[46:49]
	v_mfma_f32_16x16x32_bf16 v[42:45], v[170:173], v[182:185], v[42:45]
	v_mfma_f32_16x16x32_bf16 v[30:33], v[162:165], v[190:193], v[30:33]
	v_mfma_f32_16x16x32_bf16 v[26:29], v[170:173], v[190:193], v[26:29]
	v_mfma_f32_16x16x32_bf16 v[14:17], v[162:165], v[198:201], v[14:17]
	v_mfma_f32_16x16x32_bf16 v[8:11], v[170:173], v[198:201], v[8:11]
	v_mfma_f32_16x16x32_bf16 v[4:7], v[162:165], v[206:209], v[4:7]
	v_mfma_f32_16x16x32_bf16 v[0:3], v[170:173], v[206:209], v[0:3]
	v_mfma_f32_16x16x32_bf16 v[46:49], v[166:169], v[186:189], v[46:49]
	v_mfma_f32_16x16x32_bf16 v[42:45], v[178:181], v[186:189], v[42:45]
	v_mfma_f32_16x16x32_bf16 v[30:33], v[166:169], v[194:197], v[30:33]
	v_mfma_f32_16x16x32_bf16 v[26:29], v[178:181], v[194:197], v[26:29]
	v_mfma_f32_16x16x32_bf16 v[14:17], v[166:169], v[202:205], v[14:17]
	v_mfma_f32_16x16x32_bf16 v[8:11], v[178:181], v[202:205], v[8:11]
	v_mfma_f32_16x16x32_bf16 v[4:7], v[166:169], v[210:213], v[4:7]
	v_mfma_f32_16x16x32_bf16 v[0:3], v[178:181], v[210:213], v[0:3]
	s_setprio 0
	s_barrier
	s_add_i32 s52, s52, 2
	s_add_u32 s22, s22, 0x100
	s_addc_u32 s23, s23, 0
	s_add_u32 s50, s50, 0x100
	s_addc_u32 s51, s51, 0
	s_cmp_gt_u32 s52, 13
	s_cbranch_scc0 .LBB0_1044
	s_and_b64 vcc, exec, s[6:7]
	s_cbranch_vccz .LBB0_1047
	s_barrier

; #define PG8_STAGE(bufoff, gbase, voff) do { _Pragma("unroll") for (int _i = 0; _i < 2; ++_i) \
;         __builtin_amdgcn_global_load_lds((const unsigned*)((const char*)(gbase) + (voff)[_i]), (LAS unsigned*)(lds + (bufoff) + ldsw + _i * 8192), 16, 0, 0); } while (0)
; #define PG8_LDA(dst, b, h) do { _Pragma("unroll") for (int m = 0; m < 4; ++m) _Pragma("unroll") for (int k = 0; k < 2; ++k) dst[m][k] = *(const LAS bf16x8*)(lds + PG8_SA(b, h) + aoff + m * 2048 + k * 1024); } while (0)
; #define PG8_LDB(dst, b, h) do { _Pragma("unroll") for (int n = 0; n < 2; ++n) _Pragma("unroll") for (int k = 0; k < 2; ++k) dst[n][k] = *(const LAS bf16x8*)(lds + PG8_SB(b, h) + boff + n * 2048 + k * 1024); } while (0)
; #define PG8_MMA(ai, bj, At, Bt) do { __builtin_amdgcn_s_setprio(1); _Pragma("unroll") for (int m = 0; m < 4; ++m) _Pragma("unroll") for (int n = 0; n < 2; ++n) _Pragma("unroll") for (int k = 0; k < 2; ++k) \
;         acc[ai][bj][m][n] = __builtin_amdgcn_mfma_f32_16x16x32_bf16(Bt[n][k], At[m][k], acc[ai][bj][m][n], 0, 0, 0); __builtin_amdgcn_s_setprio(0); } while (0)
; #define PG8_WAIT_V(n) asm volatile("s_waitcnt vmcnt(" #n ")" ::: "memory")
; #define PG8_BAR __builtin_amdgcn_s_barrier()
; template <class Epi>
; __device__ __forceinline__ void gemm_phase(LAS unsigned char* lds, const Gemm g, const StaticOrder& S, const Epi& E, int wave_s) {
;     ...
;             PG8_LDB(B0, 0, 0); PG8_LDB(B1, 0, 1); PG8_SCHED; PG8_LDA(At, 0, 0); PG8_STAGE(PG8_SA(1, 1), a1 + hstepA, voffA);
;             PG8_WAIT_V(8); PG8_WAIT_L(0); PG8_BAR; PG8_MMA(0, 0, At, B0); PG8_MMA(0, 1, At, B1); PG8_BAR; PG8_SCHED;
;             PG8_LDA(At, 0, 1); PG8_STAGE(PG8_SB(0, 0), b2, voffB); PG8_STAGE(PG8_SB(0, 1), b2 + hstepB, voffB); PG8_STAGE(PG8_SA(0, 0), a2, voffA);
;             PG8_WAIT_V(8); PG8_WAIT_L(0); PG8_BAR; PG8_MMA(1, 0, At, B0); PG8_MMA(1, 1, At, B1); PG8_BAR; PG8_SCHED;
;             PG8_LDB(B0, 1, 0); PG8_LDB(B1, 1, 1); PG8_SCHED; PG8_LDA(At, 1, 0); PG8_STAGE(PG8_SA(0, 1), a2 + hstepA, voffA);
;             PG8_WAIT_V(8); PG8_WAIT_L(0); PG8_BAR; PG8_MMA(0, 0, At, B0); PG8_MMA(0, 1, At, B1); PG8_BAR; PG8_SCHED;
;             PG8_LDA(At, 1, 1); PG8_STAGE(PG8_SB(1, 0), b3, voffB); PG8_STAGE(PG8_SB(1, 1), b3 + hstepB, voffB); PG8_STAGE(PG8_SA(1, 0), a3, voffA);
;             PG8_WAIT_V(8); PG8_WAIT_L(0); PG8_BAR; PG8_MMA(1, 0, At, B0); PG8_MMA(1, 1, At, B1); PG8_BAR; PG8_SCHED;
.Lpp_lead_13:
	s_waitcnt lgkmcnt(4)
	s_setprio 1
	s_barrier
	s_waitcnt lgkmcnt(4)
	v_mfma_f32_16x16x32_bf16 v[158:161], v[122:125], v[162:165], v[158:161]
	v_mfma_f32_16x16x32_bf16 v[154:157], v[130:133], v[162:165], v[154:157]
	v_mfma_f32_16x16x32_bf16 v[118:121], v[122:125], v[170:173], v[118:121]
	v_mfma_f32_16x16x32_bf16 v[114:117], v[130:133], v[170:173], v[114:117]
	v_mfma_f32_16x16x32_bf16 v[110:113], v[122:125], v[194:197], v[110:113]
	v_mfma_f32_16x16x32_bf16 v[106:109], v[130:133], v[194:197], v[106:109]
	v_mfma_f32_16x16x32_bf16 v[102:105], v[122:125], v[202:205], v[102:105]
	v_mfma_f32_16x16x32_bf16 v[98:101], v[130:133], v[202:205], v[98:101]
	v_mfma_f32_16x16x32_bf16 v[158:161], v[126:129], v[166:169], v[158:161]
	v_mfma_f32_16x16x32_bf16 v[154:157], v[134:137], v[166:169], v[154:157]
	v_mfma_f32_16x16x32_bf16 v[118:121], v[126:129], v[190:193], v[118:121]
	v_mfma_f32_16x16x32_bf16 v[114:117], v[134:137], v[190:193], v[114:117]
	v_mfma_f32_16x16x32_bf16 v[110:113], v[126:129], v[198:201], v[110:113]
	v_mfma_f32_16x16x32_bf16 v[106:109], v[134:137], v[198:201], v[106:109]
	v_mfma_f32_16x16x32_bf16 v[102:105], v[126:129], v[206:209], v[102:105]
	v_mfma_f32_16x16x32_bf16 v[98:101], v[134:137], v[206:209], v[98:101]
	s_waitcnt lgkmcnt(0)
	v_mfma_f32_16x16x32_bf16 v[94:97], v[138:141], v[162:165], v[94:97]
	v_mfma_f32_16x16x32_bf16 v[90:93], v[146:149], v[162:165], v[90:93]
	v_mfma_f32_16x16x32_bf16 v[86:89], v[138:141], v[170:173], v[86:89]
	v_mfma_f32_16x16x32_bf16 v[82:85], v[146:149], v[170:173], v[82:85]
	v_mfma_f32_16x16x32_bf16 v[78:81], v[138:141], v[194:197], v[78:81]
	v_mfma_f32_16x16x32_bf16 v[74:77], v[146:149], v[194:197], v[74:77]
	v_mfma_f32_16x16x32_bf16 v[38:41], v[138:141], v[202:205], v[38:41]
	v_mfma_f32_16x16x32_bf16 v[34:37], v[146:149], v[202:205], v[34:37]
	v_mfma_f32_16x16x32_bf16 v[94:97], v[142:145], v[166:169], v[94:97]
	v_mfma_f32_16x16x32_bf16 v[90:93], v[150:153], v[166:169], v[90:93]
	v_mfma_f32_16x16x32_bf16 v[86:89], v[142:145], v[190:193], v[86:89]
	v_mfma_f32_16x16x32_bf16 v[82:85], v[150:153], v[190:193], v[82:85]
	v_mfma_f32_16x16x32_bf16 v[78:81], v[142:145], v[198:201], v[78:81]
	v_mfma_f32_16x16x32_bf16 v[74:77], v[150:153], v[198:201], v[74:77]
	v_mfma_f32_16x16x32_bf16 v[38:41], v[142:145], v[206:209], v[38:41]
	v_mfma_f32_16x16x32_bf16 v[34:37], v[150:153], v[206:209], v[34:37]
	s_setprio 0
	s_barrier
	s_add_i32 s47, s47, s20
	v_lshl_add_u64 v[174:175], s[6:7], 0, v[182:183]
	s_mov_b32 m0, s47
	ds_read_b128 v[162:165], v245 offset:16384
	ds_read_b128 v[166:169], v245 offset:17408
	ds_read_b128 v[170:173], v245 offset:18432
	ds_read_b128 v[190:193], v245 offset:19456
	ds_read_b128 v[194:197], v245 offset:20480
	ds_read_b128 v[198:201], v245 offset:21504
	ds_read_b128 v[202:205], v245 offset:22528
	ds_read_b128 v[206:209], v245 offset:23552
	global_load_lds_dwordx4 v[174:175], off
	s_add_i32 m0, s47, 0x2000
	s_add_u32 s48, s6, 0x40000
	v_lshl_add_u64 v[176:177], s[6:7], 0, v[178:179]
	s_addc_u32 s49, s7, 0
	s_add_i32 s47, s50, s20
	global_load_lds_dwordx4 v[176:177], off
	v_lshl_add_u64 v[210:211], s[48:49], 0, v[182:183]
	s_mov_b32 m0, s47
	v_lshl_add_u64 v[212:213], s[8:9], 0, v[180:181]
	global_load_lds_dwordx4 v[210:211], off
	v_lshl_add_u64 v[210:211], s[48:49], 0, v[178:179]
	s_add_i32 m0, s47, 0x2000
	s_nop 0
	global_load_lds_dwordx4 v[210:211], off
	v_lshl_add_u64 v[210:211], s[8:9], 0, v[184:185]
	s_mov_b32 m0, s42
	s_nop 0
	global_load_lds_dwordx4 v[210:211], off
	s_mov_b32 m0, s43
	s_nop 0
	global_load_lds_dwordx4 v[212:213], off
	s_waitcnt vmcnt(8)
	s_waitcnt lgkmcnt(0)
	s_setprio 1
	s_barrier
	s_waitcnt lgkmcnt(0)
	v_mfma_f32_16x16x32_bf16 v[70:73], v[122:125], v[162:165], v[70:73]
	v_mfma_f32_16x16x32_bf16 v[66:69], v[130:133], v[162:165], v[66:69]
	v_mfma_f32_16x16x32_bf16 v[62:65], v[122:125], v[170:173], v[62:65]
	v_mfma_f32_16x16x32_bf16 v[58:61], v[130:133], v[170:173], v[58:61]
	v_mfma_f32_16x16x32_bf16 v[54:57], v[122:125], v[194:197], v[54:57]
	v_mfma_f32_16x16x32_bf16 v[50:53], v[130:133], v[194:197], v[50:53]
	v_mfma_f32_16x16x32_bf16 v[46:49], v[122:125], v[202:205], v[46:49]
	v_mfma_f32_16x16x32_bf16 v[42:45], v[130:133], v[202:205], v[42:45]
	v_mfma_f32_16x16x32_bf16 v[70:73], v[126:129], v[166:169], v[70:73]
	v_mfma_f32_16x16x32_bf16 v[66:69], v[134:137], v[166:169], v[66:69]
	v_mfma_f32_16x16x32_bf16 v[62:65], v[126:129], v[190:193], v[62:65]
	v_mfma_f32_16x16x32_bf16 v[58:61], v[134:137], v[190:193], v[58:61]
	v_mfma_f32_16x16x32_bf16 v[54:57], v[126:129], v[198:201], v[54:57]
	v_mfma_f32_16x16x32_bf16 v[50:53], v[134:137], v[198:201], v[50:53]
	v_mfma_f32_16x16x32_bf16 v[46:49], v[126:129], v[206:209], v[46:49]
	v_mfma_f32_16x16x32_bf16 v[42:45], v[134:137], v[206:209], v[42:45]
	v_mfma_f32_16x16x32_bf16 v[30:33], v[138:141], v[162:165], v[30:33]
	v_mfma_f32_16x16x32_bf16 v[26:29], v[146:149], v[162:165], v[26:29]
	v_mfma_f32_16x16x32_bf16 v[22:25], v[138:141], v[170:173], v[22:25]
	v_mfma_f32_16x16x32_bf16 v[18:21], v[146:149], v[170:173], v[18:21]
	v_mfma_f32_16x16x32_bf16 v[14:17], v[138:141], v[194:197], v[14:17]
	v_mfma_f32_16x16x32_bf16 v[8:11], v[146:149], v[194:197], v[8:11]
	v_mfma_f32_16x16x32_bf16 v[4:7], v[138:141], v[202:205], v[4:7]
	v_mfma_f32_16x16x32_bf16 v[0:3], v[146:149], v[202:205], v[0:3]
	v_mfma_f32_16x16x32_bf16 v[30:33], v[142:145], v[166:169], v[30:33]
	v_mfma_f32_16x16x32_bf16 v[26:29], v[150:153], v[166:169], v[26:29]
	v_mfma_f32_16x16x32_bf16 v[22:25], v[142:145], v[190:193], v[22:25]
	v_mfma_f32_16x16x32_bf16 v[18:21], v[150:153], v[190:193], v[18:21]
	v_mfma_f32_16x16x32_bf16 v[14:17], v[142:145], v[198:201], v[14:17]
	v_mfma_f32_16x16x32_bf16 v[8:11], v[150:153], v[198:201], v[8:11]
	v_mfma_f32_16x16x32_bf16 v[4:7], v[142:145], v[206:209], v[4:7]
	v_mfma_f32_16x16x32_bf16 v[0:3], v[150:153], v[206:209], v[0:3]
	s_setprio 0
	s_barrier
	s_add_i32 s47, 0, 0x18000
	v_add_u32_e32 v12, s47, v243
	s_add_i32 s48, 0, 0x1c000
	ds_read_b128 v[122:125], v12
	ds_read_b128 v[126:129], v12 offset:1024
	ds_read_b128 v[130:133], v12 offset:2048
	ds_read_b128 v[134:137], v12 offset:3072
	v_add_u32_e32 v12, s48, v243
	ds_read_b128 v[162:165], v245 offset:32768
	ds_read_b128 v[166:169], v245 offset:33792
	ds_read_b128 v[170:173], v245 offset:34816
	ds_read_b128 v[190:193], v245 offset:35840
	ds_read_b128 v[194:197], v245 offset:36864
	ds_read_b128 v[198:201], v245 offset:37888
	ds_read_b128 v[202:205], v245 offset:38912
	ds_read_b128 v[206:209], v245 offset:39936
	ds_read_b128 v[138:141], v12
	ds_read_b128 v[142:145], v12 offset:1024
	ds_read_b128 v[146:149], v12 offset:2048
	ds_read_b128 v[150:153], v12 offset:3072
	s_add_u32 s8, s8, 0x40000
	s_addc_u32 s9, s9, 0
	s_mov_b32 m0, s82
	v_lshl_add_u64 v[214:215], s[8:9], 0, v[184:185]
	global_load_lds_dwordx4 v[214:215], off
	v_lshl_add_u64 v[214:215], s[8:9], 0, v[180:181]
	s_mov_b32 m0, s83
	s_nop 0
	global_load_lds_dwordx4 v[214:215], off
	s_waitcnt vmcnt(8)
	s_cmp_lg_u64 s[0:1], 0
	s_cbranch_scc1 .Lpp_lead_14
	s_waitcnt lgkmcnt(0)
; #define PG8_STAGE(bufoff, gbase, voff) do { _Pragma("unroll") for (int _i = 0; _i < 2; ++_i) \
;         __builtin_amdgcn_global_load_lds((const unsigned*)((const char*)(gbase) + (voff)[_i]), (LAS unsigned*)(lds + (bufoff) + ldsw + _i * 8192), 16, 0, 0); } while (0)
; #define PG8_LDA(dst, b, h) do { _Pragma("unroll") for (int m = 0; m < 4; ++m) _Pragma("unroll") for (int k = 0; k < 2; ++k) dst[m][k] = *(const LAS bf16x8*)(lds + PG8_SA(b, h) + aoff + m * 2048 + k * 1024); } while (0)
; #define PG8_LDB(dst, b, h) do { _Pragma("unroll") for (int n = 0; n < 2; ++n) _Pragma("unroll") for (int k = 0; k < 2; ++k) dst[n][k] = *(const LAS bf16x8*)(lds + PG8_SB(b, h) + boff + n * 2048 + k * 1024); } while (0)
; #define PG8_MMA(ai, bj, At, Bt) do { __builtin_amdgcn_s_setprio(1); _Pragma("unroll") for (int m = 0; m < 4; ++m) _Pragma("unroll") for (int n = 0; n < 2; ++n) _Pragma("unroll") for (int k = 0; k < 2; ++k) \
;         acc[ai][bj][m][n] = __builtin_amdgcn_mfma_f32_16x16x32_bf16(Bt[n][k], At[m][k], acc[ai][bj][m][n], 0, 0, 0); __builtin_amdgcn_s_setprio(0); } while (0)
; #define PG8_WAIT_V(n) asm volatile("s_waitcnt vmcnt(" #n ")" ::: "memory")
; template <class Epi>
; __device__ __forceinline__ void gemm_phase(LAS unsigned char* lds, const Gemm g, const StaticOrder& S, const Epi& E, int wave_s) {
;     ...
;             PG8_LDB(B0, 0, 0); PG8_LDB(B1, 0, 1); PG8_SCHED; PG8_LDA(At, 0, 0); PG8_STAGE(PG8_SA(1, 1), a1 + hstepA, voffA);
;             PG8_WAIT_V(8); PG8_WAIT_L(0); PG8_BAR; PG8_MMA(0, 0, At, B0); PG8_MMA(0, 1, At, B1); PG8_BAR; PG8_SCHED;
;             PG8_LDA(At, 0, 1); PG8_STAGE(PG8_SB(0, 0), b2, voffB); PG8_STAGE(PG8_SB(0, 1), b2 + hstepB, voffB); PG8_STAGE(PG8_SA(0, 0), a2, voffA);
;             PG8_WAIT_V(8); PG8_WAIT_L(0); PG8_BAR; PG8_MMA(1, 0, At, B0); PG8_MMA(1, 1, At, B1); PG8_BAR; PG8_SCHED;
;             PG8_LDB(B0, 1, 0); PG8_LDB(B1, 1, 1); PG8_SCHED; PG8_LDA(At, 1, 0); PG8_STAGE(PG8_SA(0, 1), a2 + hstepA, voffA);
;             PG8_WAIT_V(8); PG8_WAIT_L(0); PG8_BAR; PG8_MMA(0, 0, At, B0); PG8_MMA(0, 1, At, B1); PG8_BAR; PG8_SCHED;
;             PG8_LDA(At, 1, 1); PG8_STAGE(PG8_SB(1, 0), b3, voffB); PG8_STAGE(PG8_SB(1, 1), b3 + hstepB, voffB); PG8_STAGE(PG8_SA(1, 0), a3, voffA);
;             PG8_WAIT_V(8); PG8_WAIT_L(0); PG8_BAR; PG8_MMA(1, 0, At, B0); PG8_MMA(1, 1, At, B1); PG8_BAR; PG8_SCHED;
;         }
.Lpp_lead_14:
	s_waitcnt lgkmcnt(4)
	s_setprio 1
	s_barrier
	s_waitcnt lgkmcnt(4)
	v_mfma_f32_16x16x32_bf16 v[158:161], v[122:125], v[162:165], v[158:161]
	v_mfma_f32_16x16x32_bf16 v[154:157], v[130:133], v[162:165], v[154:157]
	v_mfma_f32_16x16x32_bf16 v[118:121], v[122:125], v[170:173], v[118:121]
	v_mfma_f32_16x16x32_bf16 v[114:117], v[130:133], v[170:173], v[114:117]
	v_mfma_f32_16x16x32_bf16 v[110:113], v[122:125], v[194:197], v[110:113]
	v_mfma_f32_16x16x32_bf16 v[106:109], v[130:133], v[194:197], v[106:109]
	v_mfma_f32_16x16x32_bf16 v[102:105], v[122:125], v[202:205], v[102:105]
	v_mfma_f32_16x16x32_bf16 v[98:101], v[130:133], v[202:205], v[98:101]
	v_mfma_f32_16x16x32_bf16 v[158:161], v[126:129], v[166:169], v[158:161]
	v_mfma_f32_16x16x32_bf16 v[154:157], v[134:137], v[166:169], v[154:157]
	v_mfma_f32_16x16x32_bf16 v[118:121], v[126:129], v[190:193], v[118:121]
	v_mfma_f32_16x16x32_bf16 v[114:117], v[134:137], v[190:193], v[114:117]
	v_mfma_f32_16x16x32_bf16 v[110:113], v[126:129], v[198:201], v[110:113]
	v_mfma_f32_16x16x32_bf16 v[106:109], v[134:137], v[198:201], v[106:109]
	v_mfma_f32_16x16x32_bf16 v[102:105], v[126:129], v[206:209], v[102:105]
	v_mfma_f32_16x16x32_bf16 v[98:101], v[134:137], v[206:209], v[98:101]
	s_waitcnt lgkmcnt(0)
	v_mfma_f32_16x16x32_bf16 v[94:97], v[138:141], v[162:165], v[94:97]
	v_mfma_f32_16x16x32_bf16 v[90:93], v[146:149], v[162:165], v[90:93]
	v_mfma_f32_16x16x32_bf16 v[86:89], v[138:141], v[170:173], v[86:89]
	v_mfma_f32_16x16x32_bf16 v[82:85], v[146:149], v[170:173], v[82:85]
	v_mfma_f32_16x16x32_bf16 v[78:81], v[138:141], v[194:197], v[78:81]
	v_mfma_f32_16x16x32_bf16 v[74:77], v[146:149], v[194:197], v[74:77]
	v_mfma_f32_16x16x32_bf16 v[38:41], v[138:141], v[202:205], v[38:41]
	v_mfma_f32_16x16x32_bf16 v[34:37], v[146:149], v[202:205], v[34:37]
	v_mfma_f32_16x16x32_bf16 v[94:97], v[142:145], v[166:169], v[94:97]
	v_mfma_f32_16x16x32_bf16 v[90:93], v[150:153], v[166:169], v[90:93]
	v_mfma_f32_16x16x32_bf16 v[86:89], v[142:145], v[190:193], v[86:89]
	v_mfma_f32_16x16x32_bf16 v[82:85], v[150:153], v[190:193], v[82:85]
	v_mfma_f32_16x16x32_bf16 v[78:81], v[142:145], v[198:201], v[78:81]
	v_mfma_f32_16x16x32_bf16 v[74:77], v[150:153], v[198:201], v[74:77]
	v_mfma_f32_16x16x32_bf16 v[38:41], v[142:145], v[206:209], v[38:41]
	v_mfma_f32_16x16x32_bf16 v[34:37], v[150:153], v[206:209], v[34:37]
	s_setprio 0
	s_barrier
	s_add_i32 s8, s47, s20
	v_lshl_add_u64 v[174:175], v[174:175], 0, s[84:85]
	s_mov_b32 m0, s8
	ds_read_b128 v[162:165], v245 offset:49152
	ds_read_b128 v[166:169], v245 offset:50176
	ds_read_b128 v[170:173], v245 offset:51200
	ds_read_b128 v[190:193], v245 offset:52224
	ds_read_b128 v[194:197], v245 offset:53248
	ds_read_b128 v[198:201], v245 offset:54272
	ds_read_b128 v[202:205], v245 offset:55296
	ds_read_b128 v[206:209], v245 offset:56320
	global_load_lds_dwordx4 v[174:175], off
	s_add_i32 m0, s8, 0x2000
	s_add_u32 s6, s6, 0x40080
	v_lshl_add_u64 v[174:175], v[176:177], 0, s[84:85]
	s_addc_u32 s7, s7, 0
	s_add_i32 s8, s48, s20
	global_load_lds_dwordx4 v[174:175], off
	v_lshl_add_u64 v[174:175], s[6:7], 0, v[182:183]
	s_mov_b32 m0, s8
	s_nop 0
	global_load_lds_dwordx4 v[174:175], off
	v_lshl_add_u64 v[174:175], s[6:7], 0, v[178:179]
	s_add_i32 m0, s8, 0x2000
	s_nop 0
	global_load_lds_dwordx4 v[174:175], off
	v_lshl_add_u64 v[174:175], v[210:211], 0, s[84:85]
	s_mov_b32 m0, s96
	s_nop 0
	global_load_lds_dwordx4 v[174:175], off
	v_lshl_add_u64 v[174:175], v[212:213], 0, s[84:85]
	s_mov_b32 m0, s97
	s_nop 0
	global_load_lds_dwordx4 v[174:175], off
	s_waitcnt vmcnt(8)
	s_waitcnt lgkmcnt(0)
	s_setprio 1
	s_barrier
	s_waitcnt lgkmcnt(0)
	v_mfma_f32_16x16x32_bf16 v[70:73], v[122:125], v[162:165], v[70:73]
	v_mfma_f32_16x16x32_bf16 v[66:69], v[130:133], v[162:165], v[66:69]
	v_mfma_f32_16x16x32_bf16 v[62:65], v[122:125], v[170:173], v[62:65]
	v_mfma_f32_16x16x32_bf16 v[58:61], v[130:133], v[170:173], v[58:61]
	v_mfma_f32_16x16x32_bf16 v[54:57], v[122:125], v[194:197], v[54:57]
	v_mfma_f32_16x16x32_bf16 v[50:53], v[130:133], v[194:197], v[50:53]
	v_mfma_f32_16x16x32_bf16 v[46:49], v[122:125], v[202:205], v[46:49]
	v_mfma_f32_16x16x32_bf16 v[42:45], v[130:133], v[202:205], v[42:45]
	v_mfma_f32_16x16x32_bf16 v[70:73], v[126:129], v[166:169], v[70:73]
	v_mfma_f32_16x16x32_bf16 v[66:69], v[134:137], v[166:169], v[66:69]
	v_mfma_f32_16x16x32_bf16 v[62:65], v[126:129], v[190:193], v[62:65]
	v_mfma_f32_16x16x32_bf16 v[58:61], v[134:137], v[190:193], v[58:61]
	v_mfma_f32_16x16x32_bf16 v[54:57], v[126:129], v[198:201], v[54:57]
	v_mfma_f32_16x16x32_bf16 v[50:53], v[134:137], v[198:201], v[50:53]
	v_mfma_f32_16x16x32_bf16 v[46:49], v[126:129], v[206:209], v[46:49]
	v_mfma_f32_16x16x32_bf16 v[42:45], v[134:137], v[206:209], v[42:45]
	v_mfma_f32_16x16x32_bf16 v[30:33], v[138:141], v[162:165], v[30:33]
	v_mfma_f32_16x16x32_bf16 v[26:29], v[146:149], v[162:165], v[26:29]
	v_mfma_f32_16x16x32_bf16 v[22:25], v[138:141], v[170:173], v[22:25]
	v_mfma_f32_16x16x32_bf16 v[18:21], v[146:149], v[170:173], v[18:21]
	v_mfma_f32_16x16x32_bf16 v[14:17], v[138:141], v[194:197], v[14:17]
	v_mfma_f32_16x16x32_bf16 v[8:11], v[146:149], v[194:197], v[8:11]
	v_mfma_f32_16x16x32_bf16 v[4:7], v[138:141], v[202:205], v[4:7]
	v_mfma_f32_16x16x32_bf16 v[0:3], v[146:149], v[202:205], v[0:3]
	v_mfma_f32_16x16x32_bf16 v[30:33], v[142:145], v[166:169], v[30:33]
	v_mfma_f32_16x16x32_bf16 v[26:29], v[150:153], v[166:169], v[26:29]
	v_mfma_f32_16x16x32_bf16 v[22:25], v[142:145], v[190:193], v[22:25]
	v_mfma_f32_16x16x32_bf16 v[18:21], v[150:153], v[190:193], v[18:21]
	v_mfma_f32_16x16x32_bf16 v[14:17], v[142:145], v[198:201], v[14:17]
	v_mfma_f32_16x16x32_bf16 v[8:11], v[150:153], v[198:201], v[8:11]
	v_mfma_f32_16x16x32_bf16 v[4:7], v[142:145], v[206:209], v[4:7]
	v_mfma_f32_16x16x32_bf16 v[0:3], v[150:153], v[206:209], v[0:3]
	s_setprio 0
	s_barrier
	s_add_i32 s46, s46, 2
	s_add_u32 s4, s4, 0x100
	s_addc_u32 s5, s5, 0
	s_add_u32 s44, s44, 0x100
	s_addc_u32 s45, s45, 0
	s_cmp_gt_u32 s46, 13
	s_cbranch_scc0 .LBB0_1112
	s_and_b64 vcc, exec, s[0:1]
	s_cbranch_vccz .LBB0_1115
	s_barrier

; #define PG8_STAGE(bufoff, gbase, voff) do { _Pragma("unroll") for (int _i = 0; _i < 2; ++_i) \
;         __builtin_amdgcn_global_load_lds((const unsigned*)((const char*)(gbase) + (voff)[_i]), (LAS unsigned*)(lds + (bufoff) + ldsw + _i * 8192), 16, 0, 0); } while (0)
; #define PG8_LDA(dst, b, h) do { _Pragma("unroll") for (int m = 0; m < 4; ++m) _Pragma("unroll") for (int k = 0; k < 2; ++k) dst[m][k] = *(const LAS bf16x8*)(lds + PG8_SA(b, h) + aoff + m * 2048 + k * 1024); } while (0)
; #define PG8_LDB(dst, b, h) do { _Pragma("unroll") for (int n = 0; n < 2; ++n) _Pragma("unroll") for (int k = 0; k < 2; ++k) dst[n][k] = *(const LAS bf16x8*)(lds + PG8_SB(b, h) + boff + n * 2048 + k * 1024); } while (0)
; #define PG8_MMA(ai, bj, At, Bt) do { __builtin_amdgcn_s_setprio(1); _Pragma("unroll") for (int m = 0; m < 4; ++m) _Pragma("unroll") for (int n = 0; n < 2; ++n) _Pragma("unroll") for (int k = 0; k < 2; ++k) \
;         acc[ai][bj][m][n] = __builtin_amdgcn_mfma_f32_16x16x32_bf16(Bt[n][k], At[m][k], acc[ai][bj][m][n], 0, 0, 0); __builtin_amdgcn_s_setprio(0); } while (0)
; #define PG8_WAIT_V(n) asm volatile("s_waitcnt vmcnt(" #n ")" ::: "memory")
; #define PG8_BAR __builtin_amdgcn_s_barrier()
; template <class Epi>
; __device__ __forceinline__ void gemm_phase(LAS unsigned char* lds, const Gemm g, const StaticOrder& S, const Epi& E, int wave_s) {
;     ...
;             PG8_LDB(B0, 0, 0); PG8_LDB(B1, 0, 1); PG8_SCHED; PG8_LDA(At, 0, 0); PG8_STAGE(PG8_SA(1, 1), a1 + hstepA, voffA);
;             PG8_WAIT_V(8); PG8_WAIT_L(0); PG8_BAR; PG8_MMA(0, 0, At, B0); PG8_MMA(0, 1, At, B1); PG8_BAR; PG8_SCHED;
;             PG8_LDA(At, 0, 1); PG8_STAGE(PG8_SB(0, 0), b2, voffB); PG8_STAGE(PG8_SB(0, 1), b2 + hstepB, voffB); PG8_STAGE(PG8_SA(0, 0), a2, voffA);
;             PG8_WAIT_V(8); PG8_WAIT_L(0); PG8_BAR; PG8_MMA(1, 0, At, B0); PG8_MMA(1, 1, At, B1); PG8_BAR; PG8_SCHED;
;             PG8_LDB(B0, 1, 0); PG8_LDB(B1, 1, 1); PG8_SCHED; PG8_LDA(At, 1, 0); PG8_STAGE(PG8_SA(0, 1), a2 + hstepA, voffA);
;             PG8_WAIT_V(8); PG8_WAIT_L(0); PG8_BAR; PG8_MMA(0, 0, At, B0); PG8_MMA(0, 1, At, B1); PG8_BAR; PG8_SCHED;
;             PG8_LDA(At, 1, 1); PG8_STAGE(PG8_SB(1, 0), b3, voffB); PG8_STAGE(PG8_SB(1, 1), b3 + hstepB, voffB); PG8_STAGE(PG8_SA(1, 0), a3, voffA);
;             PG8_WAIT_V(8); PG8_WAIT_L(0); PG8_BAR; PG8_MMA(1, 0, At, B0); PG8_MMA(1, 1, At, B1); PG8_BAR; PG8_SCHED;
.Lpp_lead_15:
	s_waitcnt lgkmcnt(4)
	s_setprio 1
	s_barrier
	s_waitcnt lgkmcnt(4)
	v_mfma_f32_16x16x32_bf16 v[78:81], v[130:133], v[186:189], v[78:81]
	v_mfma_f32_16x16x32_bf16 v[106:109], v[138:141], v[186:189], v[106:109]
	v_mfma_f32_16x16x32_bf16 v[74:77], v[130:133], v[194:197], v[74:77]
	v_mfma_f32_16x16x32_bf16 v[98:101], v[138:141], v[194:197], v[98:101]
	v_mfma_f32_16x16x32_bf16 v[70:73], v[130:133], v[210:213], v[70:73]
	v_mfma_f32_16x16x32_bf16 v[86:89], v[138:141], v[210:213], v[86:89]
	v_mfma_f32_16x16x32_bf16 v[62:65], v[130:133], v[232:235], v[62:65]
	v_mfma_f32_16x16x32_bf16 v[122:125], v[138:141], v[232:235], v[122:125]
	v_mfma_f32_16x16x32_bf16 v[78:81], v[134:137], v[190:193], v[78:81]
	v_mfma_f32_16x16x32_bf16 v[106:109], v[142:145], v[190:193], v[106:109]
	v_mfma_f32_16x16x32_bf16 v[74:77], v[134:137], v[198:201], v[74:77]
	v_mfma_f32_16x16x32_bf16 v[98:101], v[142:145], v[198:201], v[98:101]
	v_mfma_f32_16x16x32_bf16 v[70:73], v[134:137], v[214:217], v[70:73]
	v_mfma_f32_16x16x32_bf16 v[86:89], v[142:145], v[214:217], v[86:89]
	v_mfma_f32_16x16x32_bf16 v[62:65], v[134:137], v[174:177], v[62:65]
	v_mfma_f32_16x16x32_bf16 v[122:125], v[142:145], v[174:177], v[122:125]
	s_waitcnt lgkmcnt(0)
	v_mfma_f32_16x16x32_bf16 v[102:105], v[146:149], v[186:189], v[102:105]
	v_mfma_f32_16x16x32_bf16 v[34:37], v[178:181], v[186:189], v[34:37]
	v_mfma_f32_16x16x32_bf16 v[94:97], v[146:149], v[194:197], v[94:97]
	v_mfma_f32_16x16x32_bf16 v[30:33], v[178:181], v[194:197], v[30:33]
	v_mfma_f32_16x16x32_bf16 v[90:93], v[146:149], v[210:213], v[90:93]
	v_mfma_f32_16x16x32_bf16 v[26:29], v[178:181], v[210:213], v[26:29]
	v_mfma_f32_16x16x32_bf16 v[82:85], v[146:149], v[232:235], v[82:85]
	v_mfma_f32_16x16x32_bf16 v[22:25], v[178:181], v[232:235], v[22:25]
	v_mfma_f32_16x16x32_bf16 v[102:105], v[170:173], v[190:193], v[102:105]
	v_mfma_f32_16x16x32_bf16 v[34:37], v[182:185], v[190:193], v[34:37]
	v_mfma_f32_16x16x32_bf16 v[94:97], v[170:173], v[198:201], v[94:97]
	v_mfma_f32_16x16x32_bf16 v[30:33], v[182:185], v[198:201], v[30:33]
	v_mfma_f32_16x16x32_bf16 v[90:93], v[170:173], v[214:217], v[90:93]
	v_mfma_f32_16x16x32_bf16 v[26:29], v[182:185], v[214:217], v[26:29]
	v_mfma_f32_16x16x32_bf16 v[82:85], v[170:173], v[174:177], v[82:85]
	v_mfma_f32_16x16x32_bf16 v[22:25], v[182:185], v[174:177], v[22:25]
	s_setprio 0
	s_barrier
	s_add_i32 s54, s54, s65
	v_lshl_add_u64 v[164:165], s[8:9], 0, v[12:13]
	s_mov_b32 m0, s54
	ds_read_b128 v[174:177], v167 offset:16384
	ds_read_b128 v[186:189], v167 offset:17408
	ds_read_b128 v[190:193], v167 offset:18432
	ds_read_b128 v[194:197], v167 offset:19456
	ds_read_b128 v[198:201], v167 offset:20480
	ds_read_b128 v[210:213], v167 offset:21504
	ds_read_b128 v[214:217], v167 offset:22528
	ds_read_b128 v[232:235], v167 offset:23552
	global_load_lds_dwordx4 v[164:165], off
	s_add_i32 m0, s54, 0x2000
	s_add_u32 s58, s8, 0xb0000
	v_lshl_add_u64 v[202:203], s[8:9], 0, v[150:151]
	s_addc_u32 s59, s9, 0
	s_add_i32 s54, s70, s65
	global_load_lds_dwordx4 v[202:203], off
	v_lshl_add_u64 v[206:207], s[58:59], 0, v[12:13]
	s_mov_b32 m0, s54
	v_lshl_add_u64 v[218:219], vcc, 0, v[152:153]
	global_load_lds_dwordx4 v[206:207], off
	v_lshl_add_u64 v[206:207], s[58:59], 0, v[150:151]
	s_add_i32 m0, s54, 0x2000
	s_nop 0
	global_load_lds_dwordx4 v[206:207], off
	v_lshl_add_u64 v[206:207], vcc, 0, v[154:155]
	s_mov_b32 m0, s52
	s_nop 0
	global_load_lds_dwordx4 v[206:207], off
	s_mov_b32 m0, s53
	s_nop 0
	global_load_lds_dwordx4 v[218:219], off
	s_waitcnt vmcnt(8)
	s_waitcnt lgkmcnt(0)
	s_setprio 1
	s_barrier
	s_waitcnt lgkmcnt(0)
	v_mfma_f32_16x16x32_bf16 v[58:61], v[130:133], v[174:177], v[58:61]
	v_mfma_f32_16x16x32_bf16 v[118:121], v[138:141], v[174:177], v[118:121]
	v_mfma_f32_16x16x32_bf16 v[54:57], v[130:133], v[190:193], v[54:57]
	v_mfma_f32_16x16x32_bf16 v[126:129], v[138:141], v[190:193], v[126:129]
	v_mfma_f32_16x16x32_bf16 v[50:53], v[130:133], v[198:201], v[50:53]
	v_mfma_f32_16x16x32_bf16 v[114:117], v[138:141], v[198:201], v[114:117]
	v_mfma_f32_16x16x32_bf16 v[46:49], v[130:133], v[214:217], v[46:49]
	v_mfma_f32_16x16x32_bf16 v[110:113], v[138:141], v[214:217], v[110:113]
	v_mfma_f32_16x16x32_bf16 v[58:61], v[134:137], v[186:189], v[58:61]
	v_mfma_f32_16x16x32_bf16 v[118:121], v[142:145], v[186:189], v[118:121]
	v_mfma_f32_16x16x32_bf16 v[54:57], v[134:137], v[194:197], v[54:57]
	v_mfma_f32_16x16x32_bf16 v[126:129], v[142:145], v[194:197], v[126:129]
	v_mfma_f32_16x16x32_bf16 v[50:53], v[134:137], v[210:213], v[50:53]
	v_mfma_f32_16x16x32_bf16 v[114:117], v[142:145], v[210:213], v[114:117]
	v_mfma_f32_16x16x32_bf16 v[46:49], v[134:137], v[232:235], v[46:49]
	v_mfma_f32_16x16x32_bf16 v[110:113], v[142:145], v[232:235], v[110:113]
	v_mfma_f32_16x16x32_bf16 v[66:69], v[146:149], v[174:177], v[66:69]
	v_mfma_f32_16x16x32_bf16 v[14:17], v[178:181], v[174:177], v[14:17]
	v_mfma_f32_16x16x32_bf16 v[42:45], v[146:149], v[190:193], v[42:45]
	v_mfma_f32_16x16x32_bf16 v[8:11], v[178:181], v[190:193], v[8:11]
	v_mfma_f32_16x16x32_bf16 v[38:41], v[146:149], v[198:201], v[38:41]
	v_mfma_f32_16x16x32_bf16 v[4:7], v[178:181], v[198:201], v[4:7]
	v_mfma_f32_16x16x32_bf16 v[18:21], v[146:149], v[214:217], v[18:21]
	v_mfma_f32_16x16x32_bf16 v[0:3], v[178:181], v[214:217], v[0:3]
	v_mfma_f32_16x16x32_bf16 v[66:69], v[170:173], v[186:189], v[66:69]
	v_mfma_f32_16x16x32_bf16 v[14:17], v[182:185], v[186:189], v[14:17]
	v_mfma_f32_16x16x32_bf16 v[42:45], v[170:173], v[194:197], v[42:45]
	v_mfma_f32_16x16x32_bf16 v[8:11], v[182:185], v[194:197], v[8:11]
	v_mfma_f32_16x16x32_bf16 v[38:41], v[170:173], v[210:213], v[38:41]
	v_mfma_f32_16x16x32_bf16 v[4:7], v[182:185], v[210:213], v[4:7]
	v_mfma_f32_16x16x32_bf16 v[18:21], v[170:173], v[232:235], v[18:21]
	v_mfma_f32_16x16x32_bf16 v[0:3], v[182:185], v[232:235], v[0:3]
	s_setprio 0
	s_barrier
	s_add_i32 s54, 0, 0x18000
	s_add_i32 s70, 0, 0x1c000
	v_add_u32_e32 v142, s54, v209
	v_add_u32_e32 v169, s70, v209
	ds_read_b128 v[130:133], v142
	ds_read_b128 v[134:137], v142 offset:1024
	ds_read_b128 v[138:141], v142 offset:2048
	ds_read_b128 v[142:145], v142 offset:3072
	ds_read_b128 v[182:185], v167 offset:32768
	ds_read_b128 v[186:189], v167 offset:33792
	ds_read_b128 v[190:193], v167 offset:34816
	ds_read_b128 v[194:197], v167 offset:35840
	ds_read_b128 v[198:201], v167 offset:36864
	ds_read_b128 v[210:213], v167 offset:37888
	ds_read_b128 v[214:217], v167 offset:38912
	ds_read_b128 v[232:235], v167 offset:39936
	ds_read_b128 v[146:149], v169
	ds_read_b128 v[170:173], v169 offset:1024
	ds_read_b128 v[174:177], v169 offset:2048
	ds_read_b128 v[178:181], v169 offset:3072
	s_add_u32 s58, vcc_lo, 0xb0000
	s_addc_u32 s59, vcc_hi, 0
	s_mov_b32 m0, s35
	v_lshl_add_u64 v[224:225], s[58:59], 0, v[154:155]
	global_load_lds_dwordx4 v[224:225], off
	v_lshl_add_u64 v[224:225], s[58:59], 0, v[152:153]
	s_mov_b32 m0, s18
	s_nop 0
	global_load_lds_dwordx4 v[224:225], off
	s_waitcnt vmcnt(8)
	s_cmp_lg_u64 s[26:27], 0
	s_cbranch_scc1 .Lpp_lead_16
	s_waitcnt lgkmcnt(0)
; #define PG8_STAGE(bufoff, gbase, voff) do { _Pragma("unroll") for (int _i = 0; _i < 2; ++_i) \
;         __builtin_amdgcn_global_load_lds((const unsigned*)((const char*)(gbase) + (voff)[_i]), (LAS unsigned*)(lds + (bufoff) + ldsw + _i * 8192), 16, 0, 0); } while (0)
; #define PG8_LDA(dst, b, h) do { _Pragma("unroll") for (int m = 0; m < 4; ++m) _Pragma("unroll") for (int k = 0; k < 2; ++k) dst[m][k] = *(const LAS bf16x8*)(lds + PG8_SA(b, h) + aoff + m * 2048 + k * 1024); } while (0)
; #define PG8_LDB(dst, b, h) do { _Pragma("unroll") for (int n = 0; n < 2; ++n) _Pragma("unroll") for (int k = 0; k < 2; ++k) dst[n][k] = *(const LAS bf16x8*)(lds + PG8_SB(b, h) + boff + n * 2048 + k * 1024); } while (0)
; #define PG8_MMA(ai, bj, At, Bt) do { __builtin_amdgcn_s_setprio(1); _Pragma("unroll") for (int m = 0; m < 4; ++m) _Pragma("unroll") for (int n = 0; n < 2; ++n) _Pragma("unroll") for (int k = 0; k < 2; ++k) \
;         acc[ai][bj][m][n] = __builtin_amdgcn_mfma_f32_16x16x32_bf16(Bt[n][k], At[m][k], acc[ai][bj][m][n], 0, 0, 0); __builtin_amdgcn_s_setprio(0); } while (0)
; #define PG8_WAIT_V(n) asm volatile("s_waitcnt vmcnt(" #n ")" ::: "memory")
; template <class Epi>
; __device__ __forceinline__ void gemm_phase(LAS unsigned char* lds, const Gemm g, const StaticOrder& S, const Epi& E, int wave_s) {
;     ...
;             PG8_LDB(B0, 0, 0); PG8_LDB(B1, 0, 1); PG8_SCHED; PG8_LDA(At, 0, 0); PG8_STAGE(PG8_SA(1, 1), a1 + hstepA, voffA);
;             PG8_WAIT_V(8); PG8_WAIT_L(0); PG8_BAR; PG8_MMA(0, 0, At, B0); PG8_MMA(0, 1, At, B1); PG8_BAR; PG8_SCHED;
;             PG8_LDA(At, 0, 1); PG8_STAGE(PG8_SB(0, 0), b2, voffB); PG8_STAGE(PG8_SB(0, 1), b2 + hstepB, voffB); PG8_STAGE(PG8_SA(0, 0), a2, voffA);
;             PG8_WAIT_V(8); PG8_WAIT_L(0); PG8_BAR; PG8_MMA(1, 0, At, B0); PG8_MMA(1, 1, At, B1); PG8_BAR; PG8_SCHED;
;             PG8_LDB(B0, 1, 0); PG8_LDB(B1, 1, 1); PG8_SCHED; PG8_LDA(At, 1, 0); PG8_STAGE(PG8_SA(0, 1), a2 + hstepA, voffA);
;             PG8_WAIT_V(8); PG8_WAIT_L(0); PG8_BAR; PG8_MMA(0, 0, At, B0); PG8_MMA(0, 1, At, B1); PG8_BAR; PG8_SCHED;
;             PG8_LDA(At, 1, 1); PG8_STAGE(PG8_SB(1, 0), b3, voffB); PG8_STAGE(PG8_SB(1, 1), b3 + hstepB, voffB); PG8_STAGE(PG8_SA(1, 0), a3, voffA);
;             PG8_WAIT_V(8); PG8_WAIT_L(0); PG8_BAR; PG8_MMA(1, 0, At, B0); PG8_MMA(1, 1, At, B1); PG8_BAR; PG8_SCHED;
;         }
.Lpp_lead_16:
	s_waitcnt lgkmcnt(4)
	s_setprio 1
	s_barrier
	s_waitcnt lgkmcnt(4)
	v_mfma_f32_16x16x32_bf16 v[78:81], v[130:133], v[182:185], v[78:81]
	v_mfma_f32_16x16x32_bf16 v[106:109], v[138:141], v[182:185], v[106:109]
	v_mfma_f32_16x16x32_bf16 v[74:77], v[130:133], v[190:193], v[74:77]
	v_mfma_f32_16x16x32_bf16 v[98:101], v[138:141], v[190:193], v[98:101]
	v_mfma_f32_16x16x32_bf16 v[70:73], v[130:133], v[198:201], v[70:73]
	v_mfma_f32_16x16x32_bf16 v[86:89], v[138:141], v[198:201], v[86:89]
	v_mfma_f32_16x16x32_bf16 v[62:65], v[130:133], v[214:217], v[62:65]
	v_mfma_f32_16x16x32_bf16 v[122:125], v[138:141], v[214:217], v[122:125]
	v_mfma_f32_16x16x32_bf16 v[78:81], v[134:137], v[186:189], v[78:81]
	v_mfma_f32_16x16x32_bf16 v[106:109], v[142:145], v[186:189], v[106:109]
	v_mfma_f32_16x16x32_bf16 v[74:77], v[134:137], v[194:197], v[74:77]
	v_mfma_f32_16x16x32_bf16 v[98:101], v[142:145], v[194:197], v[98:101]
	v_mfma_f32_16x16x32_bf16 v[70:73], v[134:137], v[210:213], v[70:73]
	v_mfma_f32_16x16x32_bf16 v[86:89], v[142:145], v[210:213], v[86:89]
	v_mfma_f32_16x16x32_bf16 v[62:65], v[134:137], v[232:235], v[62:65]
	v_mfma_f32_16x16x32_bf16 v[122:125], v[142:145], v[232:235], v[122:125]
	s_waitcnt lgkmcnt(0)
	v_mfma_f32_16x16x32_bf16 v[102:105], v[146:149], v[182:185], v[102:105]
	v_mfma_f32_16x16x32_bf16 v[34:37], v[174:177], v[182:185], v[34:37]
	v_mfma_f32_16x16x32_bf16 v[94:97], v[146:149], v[190:193], v[94:97]
	v_mfma_f32_16x16x32_bf16 v[30:33], v[174:177], v[190:193], v[30:33]
	v_mfma_f32_16x16x32_bf16 v[90:93], v[146:149], v[198:201], v[90:93]
	v_mfma_f32_16x16x32_bf16 v[26:29], v[174:177], v[198:201], v[26:29]
	v_mfma_f32_16x16x32_bf16 v[82:85], v[146:149], v[214:217], v[82:85]
	v_mfma_f32_16x16x32_bf16 v[22:25], v[174:177], v[214:217], v[22:25]
	v_mfma_f32_16x16x32_bf16 v[102:105], v[170:173], v[186:189], v[102:105]
	v_mfma_f32_16x16x32_bf16 v[34:37], v[178:181], v[186:189], v[34:37]
	v_mfma_f32_16x16x32_bf16 v[94:97], v[170:173], v[194:197], v[94:97]
	v_mfma_f32_16x16x32_bf16 v[30:33], v[178:181], v[194:197], v[30:33]
	v_mfma_f32_16x16x32_bf16 v[90:93], v[170:173], v[210:213], v[90:93]
	v_mfma_f32_16x16x32_bf16 v[26:29], v[178:181], v[210:213], v[26:29]
	v_mfma_f32_16x16x32_bf16 v[82:85], v[170:173], v[232:235], v[82:85]
	v_mfma_f32_16x16x32_bf16 v[22:25], v[178:181], v[232:235], v[22:25]
	s_setprio 0
	s_barrier
	s_add_i32 s54, s54, s65
	v_lshl_add_u64 v[164:165], v[164:165], 0, s[84:85]
	s_mov_b32 m0, s54
	ds_read_b128 v[182:185], v167 offset:49152
	ds_read_b128 v[186:189], v167 offset:50176
	ds_read_b128 v[190:193], v167 offset:51200
	ds_read_b128 v[194:197], v167 offset:52224
	ds_read_b128 v[198:201], v167 offset:53248
	ds_read_b128 v[210:213], v167 offset:54272
	ds_read_b128 v[214:217], v167 offset:55296
	ds_read_b128 v[232:235], v167 offset:56320
	global_load_lds_dwordx4 v[164:165], off
	s_add_i32 m0, s54, 0x2000
	s_add_u32 s8, s8, 0xb0080
	v_lshl_add_u64 v[164:165], v[202:203], 0, s[84:85]
	s_addc_u32 s9, s9, 0
	s_add_i32 s54, s70, s65
	global_load_lds_dwordx4 v[164:165], off
	v_lshl_add_u64 v[164:165], s[8:9], 0, v[12:13]
	s_mov_b32 m0, s54
	s_nop 0
	global_load_lds_dwordx4 v[164:165], off
	v_lshl_add_u64 v[164:165], s[8:9], 0, v[150:151]
	s_add_i32 m0, s54, 0x2000
	s_nop 0
	global_load_lds_dwordx4 v[164:165], off
	v_lshl_add_u64 v[164:165], v[206:207], 0, s[84:85]
	s_mov_b32 m0, s45
	s_nop 0
	global_load_lds_dwordx4 v[164:165], off
	v_lshl_add_u64 v[164:165], v[218:219], 0, s[84:85]
	s_mov_b32 m0, s46
	s_nop 0
	global_load_lds_dwordx4 v[164:165], off
	s_waitcnt vmcnt(8)
	s_waitcnt lgkmcnt(0)
	s_setprio 1
	s_barrier
	s_waitcnt lgkmcnt(0)
	v_mfma_f32_16x16x32_bf16 v[58:61], v[130:133], v[182:185], v[58:61]
	v_mfma_f32_16x16x32_bf16 v[118:121], v[138:141], v[182:185], v[118:121]
	v_mfma_f32_16x16x32_bf16 v[54:57], v[130:133], v[190:193], v[54:57]
	v_mfma_f32_16x16x32_bf16 v[126:129], v[138:141], v[190:193], v[126:129]
	v_mfma_f32_16x16x32_bf16 v[50:53], v[130:133], v[198:201], v[50:53]
	v_mfma_f32_16x16x32_bf16 v[114:117], v[138:141], v[198:201], v[114:117]
	v_mfma_f32_16x16x32_bf16 v[46:49], v[130:133], v[214:217], v[46:49]
	v_mfma_f32_16x16x32_bf16 v[110:113], v[138:141], v[214:217], v[110:113]
	v_mfma_f32_16x16x32_bf16 v[58:61], v[134:137], v[186:189], v[58:61]
	v_mfma_f32_16x16x32_bf16 v[118:121], v[142:145], v[186:189], v[118:121]
	v_mfma_f32_16x16x32_bf16 v[54:57], v[134:137], v[194:197], v[54:57]
	v_mfma_f32_16x16x32_bf16 v[126:129], v[142:145], v[194:197], v[126:129]
	v_mfma_f32_16x16x32_bf16 v[50:53], v[134:137], v[210:213], v[50:53]
	v_mfma_f32_16x16x32_bf16 v[114:117], v[142:145], v[210:213], v[114:117]
	v_mfma_f32_16x16x32_bf16 v[46:49], v[134:137], v[232:235], v[46:49]
	v_mfma_f32_16x16x32_bf16 v[110:113], v[142:145], v[232:235], v[110:113]
	v_mfma_f32_16x16x32_bf16 v[66:69], v[146:149], v[182:185], v[66:69]
	v_mfma_f32_16x16x32_bf16 v[14:17], v[174:177], v[182:185], v[14:17]
	v_mfma_f32_16x16x32_bf16 v[42:45], v[146:149], v[190:193], v[42:45]
	v_mfma_f32_16x16x32_bf16 v[8:11], v[174:177], v[190:193], v[8:11]
	v_mfma_f32_16x16x32_bf16 v[38:41], v[146:149], v[198:201], v[38:41]
	v_mfma_f32_16x16x32_bf16 v[4:7], v[174:177], v[198:201], v[4:7]
	v_mfma_f32_16x16x32_bf16 v[18:21], v[146:149], v[214:217], v[18:21]
	v_mfma_f32_16x16x32_bf16 v[0:3], v[174:177], v[214:217], v[0:3]
	v_mfma_f32_16x16x32_bf16 v[66:69], v[170:173], v[186:189], v[66:69]
	v_mfma_f32_16x16x32_bf16 v[14:17], v[178:181], v[186:189], v[14:17]
	v_mfma_f32_16x16x32_bf16 v[42:45], v[170:173], v[194:197], v[42:45]
	v_mfma_f32_16x16x32_bf16 v[8:11], v[178:181], v[194:197], v[8:11]
	v_mfma_f32_16x16x32_bf16 v[38:41], v[170:173], v[210:213], v[38:41]
	v_mfma_f32_16x16x32_bf16 v[4:7], v[178:181], v[210:213], v[4:7]
	v_mfma_f32_16x16x32_bf16 v[18:21], v[170:173], v[232:235], v[18:21]
	v_mfma_f32_16x16x32_bf16 v[0:3], v[178:181], v[232:235], v[0:3]
	s_setprio 0
	s_barrier
	s_add_i32 s51, s51, 2
	s_add_u32 s49, s49, 0x100
	s_addc_u32 s50, s50, 0
	s_cmp_gt_u32 s51, 41
	s_mov_b64 s[94:95], s[6:7]
	s_cbranch_scc0 .LBB0_1188
	s_and_b64 vcc, exec, s[26:27]
	s_cbranch_vccz .LBB0_1191
	s_barrier
